# GEMM K loops: hipcc's per-segment s_setprio flips deleted, no static raise
# baseline (speedup 1.0000x reference)
.LBB0_311:
	s_add_u32 s4, s62, 0xfffc0080
	s_addc_u32 s5, s63, -1
	s_add_i32 s84, 0, 0x10000
	s_cmp_eq_u32 s82, 12
	s_cselect_b32 s65, s33, s5
	s_cselect_b32 s64, s36, s4
	s_cselect_b32 s35, s53, s79
	s_cselect_b32 s34, s55, s75
	s_add_i32 s4, 0, 0x14000
	v_add_u32_e32 v164, s84, v143
	v_add_u32_e32 v180, s4, v143
	ds_read_b128 v[138:141], v164
	ds_read_b128 v[156:159], v164 offset:1024
	ds_read_b128 v[160:163], v164 offset:2048
	ds_read_b128 v[164:167], v164 offset:3072
	ds_read_b128 v[168:171], v180
	ds_read_b128 v[172:175], v180 offset:1024
	ds_read_b128 v[176:179], v180 offset:2048
	ds_read_b128 v[204:207], v180 offset:3072
	v_lshl_add_u64 v[180:181], s[62:63], 0, v[134:135]
	s_add_i32 m0, s68, 0xc000
	ds_read_b128 v[208:211], v155
	ds_read_b128 v[212:215], v155 offset:1024
	ds_read_b128 v[216:219], v155 offset:2048
	ds_read_b128 v[220:223], v155 offset:3072
	ds_read_b128 v[224:227], v155 offset:4096
	ds_read_b128 v[228:231], v155 offset:5120
	ds_read_b128 v[232:235], v155 offset:6144
	ds_read_b128 v[236:239], v155 offset:7168
	global_load_lds_dwordx4 v[180:181], off
	v_lshl_add_u64 v[180:181], s[62:63], 0, v[136:137]
	s_add_i32 m0, s68, 0xe000
	s_nop 0
	global_load_lds_dwordx4 v[180:181], off
	s_waitcnt vmcnt(8)
	s_waitcnt lgkmcnt(0)
	s_barrier
	s_waitcnt lgkmcnt(0)
	v_mfma_f32_16x16x32_bf16 v[124:127], v[138:141], v[208:211], v[124:127]
	v_mfma_f32_16x16x32_bf16 v[120:123], v[160:163], v[208:211], v[120:123]
	v_mfma_f32_16x16x32_bf16 v[108:111], v[138:141], v[216:219], v[108:111]
	v_mfma_f32_16x16x32_bf16 v[104:107], v[160:163], v[216:219], v[104:107]
	v_mfma_f32_16x16x32_bf16 v[92:95], v[138:141], v[224:227], v[92:95]
	v_mfma_f32_16x16x32_bf16 v[88:91], v[160:163], v[224:227], v[88:91]
	v_mfma_f32_16x16x32_bf16 v[76:79], v[138:141], v[232:235], v[76:79]
	v_mfma_f32_16x16x32_bf16 v[72:75], v[160:163], v[232:235], v[72:75]
	v_mfma_f32_16x16x32_bf16 v[124:127], v[156:159], v[212:215], v[124:127]
	v_mfma_f32_16x16x32_bf16 v[120:123], v[164:167], v[212:215], v[120:123]
	v_mfma_f32_16x16x32_bf16 v[108:111], v[156:159], v[220:223], v[108:111]
	v_mfma_f32_16x16x32_bf16 v[104:107], v[164:167], v[220:223], v[104:107]
	v_mfma_f32_16x16x32_bf16 v[92:95], v[156:159], v[228:231], v[92:95]
	v_mfma_f32_16x16x32_bf16 v[88:91], v[164:167], v[228:231], v[88:91]
	v_mfma_f32_16x16x32_bf16 v[76:79], v[156:159], v[236:239], v[76:79]
	v_mfma_f32_16x16x32_bf16 v[72:75], v[164:167], v[236:239], v[72:75]
	v_mfma_f32_16x16x32_bf16 v[116:119], v[168:171], v[208:211], v[116:119]
	v_mfma_f32_16x16x32_bf16 v[112:115], v[176:179], v[208:211], v[112:115]
	v_mfma_f32_16x16x32_bf16 v[100:103], v[168:171], v[216:219], v[100:103]
	v_mfma_f32_16x16x32_bf16 v[96:99], v[176:179], v[216:219], v[96:99]
	v_mfma_f32_16x16x32_bf16 v[84:87], v[168:171], v[224:227], v[84:87]
	v_mfma_f32_16x16x32_bf16 v[80:83], v[176:179], v[224:227], v[80:83]
	v_mfma_f32_16x16x32_bf16 v[68:71], v[168:171], v[232:235], v[68:71]
	v_mfma_f32_16x16x32_bf16 v[64:67], v[176:179], v[232:235], v[64:67]
	v_mfma_f32_16x16x32_bf16 v[116:119], v[172:175], v[212:215], v[116:119]
	v_mfma_f32_16x16x32_bf16 v[112:115], v[204:207], v[212:215], v[112:115]
	v_mfma_f32_16x16x32_bf16 v[100:103], v[172:175], v[220:223], v[100:103]
	v_mfma_f32_16x16x32_bf16 v[96:99], v[204:207], v[220:223], v[96:99]
	v_mfma_f32_16x16x32_bf16 v[84:87], v[172:175], v[228:231], v[84:87]
	v_mfma_f32_16x16x32_bf16 v[80:83], v[204:207], v[228:231], v[80:83]
	v_mfma_f32_16x16x32_bf16 v[68:71], v[172:175], v[236:239], v[68:71]
	v_mfma_f32_16x16x32_bf16 v[64:67], v[204:207], v[236:239], v[64:67]
	s_barrier
	s_add_i32 s5, s84, s28
	v_lshl_add_u64 v[180:181], s[34:35], 0, v[144:145]
	s_mov_b32 m0, s5
	ds_read_b128 v[208:211], v155 offset:16384
	ds_read_b128 v[212:215], v155 offset:17408
	ds_read_b128 v[216:219], v155 offset:18432
	ds_read_b128 v[220:223], v155 offset:19456
	ds_read_b128 v[224:227], v155 offset:20480
	ds_read_b128 v[228:231], v155 offset:21504
	ds_read_b128 v[232:235], v155 offset:22528
	ds_read_b128 v[236:239], v155 offset:23552
	global_load_lds_dwordx4 v[180:181], off
	s_add_i32 m0, s5, 0x2000
	s_add_u32 s88, s34, 0x40000
	v_lshl_add_u64 v[240:241], s[34:35], 0, v[128:129]
	s_addc_u32 s89, s35, 0
	s_add_i32 s4, s4, s28
	global_load_lds_dwordx4 v[240:241], off
	v_lshl_add_u64 v[242:243], s[88:89], 0, v[144:145]
	s_mov_b32 m0, s4
	v_lshl_add_u64 v[244:245], s[64:65], 0, v[130:131]
	global_load_lds_dwordx4 v[242:243], off
	v_lshl_add_u64 v[242:243], s[88:89], 0, v[128:129]
	s_add_i32 m0, s4, 0x2000
	s_nop 0
	global_load_lds_dwordx4 v[242:243], off
	v_lshl_add_u64 v[242:243], s[64:65], 0, v[132:133]
	s_mov_b32 m0, s68
	s_nop 0
	global_load_lds_dwordx4 v[242:243], off
	s_mov_b32 m0, s69
	s_nop 0
	global_load_lds_dwordx4 v[244:245], off
	s_waitcnt vmcnt(8)
	s_waitcnt lgkmcnt(0)
	s_barrier
	s_waitcnt lgkmcnt(0)
	v_mfma_f32_16x16x32_bf16 v[60:63], v[138:141], v[208:211], v[60:63]
	v_mfma_f32_16x16x32_bf16 v[56:59], v[160:163], v[208:211], v[56:59]
	v_mfma_f32_16x16x32_bf16 v[44:47], v[138:141], v[216:219], v[44:47]
	v_mfma_f32_16x16x32_bf16 v[40:43], v[160:163], v[216:219], v[40:43]
	v_mfma_f32_16x16x32_bf16 v[28:31], v[138:141], v[224:227], v[28:31]
	v_mfma_f32_16x16x32_bf16 v[24:27], v[160:163], v[224:227], v[24:27]
	v_mfma_f32_16x16x32_bf16 v[12:15], v[138:141], v[232:235], v[12:15]
	v_mfma_f32_16x16x32_bf16 v[8:11], v[160:163], v[232:235], v[8:11]
	v_mfma_f32_16x16x32_bf16 v[60:63], v[156:159], v[212:215], v[60:63]
	v_mfma_f32_16x16x32_bf16 v[56:59], v[164:167], v[212:215], v[56:59]
	v_mfma_f32_16x16x32_bf16 v[44:47], v[156:159], v[220:223], v[44:47]
	v_mfma_f32_16x16x32_bf16 v[40:43], v[164:167], v[220:223], v[40:43]
	v_mfma_f32_16x16x32_bf16 v[28:31], v[156:159], v[228:231], v[28:31]
	v_mfma_f32_16x16x32_bf16 v[24:27], v[164:167], v[228:231], v[24:27]
	v_mfma_f32_16x16x32_bf16 v[12:15], v[156:159], v[236:239], v[12:15]
	v_mfma_f32_16x16x32_bf16 v[8:11], v[164:167], v[236:239], v[8:11]
	v_mfma_f32_16x16x32_bf16 v[52:55], v[168:171], v[208:211], v[52:55]
	v_mfma_f32_16x16x32_bf16 v[48:51], v[176:179], v[208:211], v[48:51]
	v_mfma_f32_16x16x32_bf16 v[36:39], v[168:171], v[216:219], v[36:39]
	v_mfma_f32_16x16x32_bf16 v[32:35], v[176:179], v[216:219], v[32:35]
	v_mfma_f32_16x16x32_bf16 v[20:23], v[168:171], v[224:227], v[20:23]
	v_mfma_f32_16x16x32_bf16 v[16:19], v[176:179], v[224:227], v[16:19]
	v_mfma_f32_16x16x32_bf16 v[4:7], v[168:171], v[232:235], v[4:7]
	v_mfma_f32_16x16x32_bf16 v[0:3], v[176:179], v[232:235], v[0:3]
	v_mfma_f32_16x16x32_bf16 v[52:55], v[172:175], v[212:215], v[52:55]
	v_mfma_f32_16x16x32_bf16 v[48:51], v[204:207], v[212:215], v[48:51]
	v_mfma_f32_16x16x32_bf16 v[36:39], v[172:175], v[220:223], v[36:39]
	v_mfma_f32_16x16x32_bf16 v[32:35], v[204:207], v[220:223], v[32:35]
	v_mfma_f32_16x16x32_bf16 v[20:23], v[172:175], v[228:231], v[20:23]
	v_mfma_f32_16x16x32_bf16 v[16:19], v[204:207], v[228:231], v[16:19]
	v_mfma_f32_16x16x32_bf16 v[4:7], v[172:175], v[236:239], v[4:7]
	v_mfma_f32_16x16x32_bf16 v[0:3], v[204:207], v[236:239], v[0:3]
	s_barrier
	s_add_i32 s4, 0, 0x18000
	s_add_i32 s5, 0, 0x1c000
	v_add_u32_e32 v164, s4, v143
	v_add_u32_e32 v202, s5, v143
	ds_read_b128 v[138:141], v164
	ds_read_b128 v[156:159], v164 offset:1024
	ds_read_b128 v[160:163], v164 offset:2048
	ds_read_b128 v[164:167], v164 offset:3072
	ds_read_b128 v[168:171], v202
	ds_read_b128 v[172:175], v202 offset:1024
	ds_read_b128 v[176:179], v202 offset:2048
	ds_read_b128 v[204:207], v202 offset:3072
	s_add_u32 s64, s64, 0x40000
	s_addc_u32 s65, s65, 0
	s_mov_b32 m0, s70
	v_lshl_add_u64 v[246:247], s[64:65], 0, v[132:133]
	ds_read_b128 v[208:211], v155 offset:32768
	ds_read_b128 v[212:215], v155 offset:33792
	ds_read_b128 v[216:219], v155 offset:34816
	ds_read_b128 v[220:223], v155 offset:35840
	ds_read_b128 v[224:227], v155 offset:36864
	ds_read_b128 v[228:231], v155 offset:37888
	ds_read_b128 v[232:235], v155 offset:38912
	ds_read_b128 v[236:239], v155 offset:39936
	global_load_lds_dwordx4 v[246:247], off
	v_lshl_add_u64 v[246:247], s[64:65], 0, v[130:131]
	s_mov_b32 m0, s71
	s_nop 0
	global_load_lds_dwordx4 v[246:247], off
	s_waitcnt vmcnt(8)
	s_waitcnt lgkmcnt(0)
	s_barrier
	s_waitcnt lgkmcnt(0)
	v_mfma_f32_16x16x32_bf16 v[124:127], v[138:141], v[208:211], v[124:127]
	v_mfma_f32_16x16x32_bf16 v[120:123], v[160:163], v[208:211], v[120:123]
	v_mfma_f32_16x16x32_bf16 v[108:111], v[138:141], v[216:219], v[108:111]
	v_mfma_f32_16x16x32_bf16 v[104:107], v[160:163], v[216:219], v[104:107]
	v_mfma_f32_16x16x32_bf16 v[92:95], v[138:141], v[224:227], v[92:95]
	v_mfma_f32_16x16x32_bf16 v[88:91], v[160:163], v[224:227], v[88:91]
	v_mfma_f32_16x16x32_bf16 v[76:79], v[138:141], v[232:235], v[76:79]
	v_mfma_f32_16x16x32_bf16 v[72:75], v[160:163], v[232:235], v[72:75]
	v_mfma_f32_16x16x32_bf16 v[124:127], v[156:159], v[212:215], v[124:127]
	v_mfma_f32_16x16x32_bf16 v[120:123], v[164:167], v[212:215], v[120:123]
	v_mfma_f32_16x16x32_bf16 v[108:111], v[156:159], v[220:223], v[108:111]
	v_mfma_f32_16x16x32_bf16 v[104:107], v[164:167], v[220:223], v[104:107]
	v_mfma_f32_16x16x32_bf16 v[92:95], v[156:159], v[228:231], v[92:95]
	v_mfma_f32_16x16x32_bf16 v[88:91], v[164:167], v[228:231], v[88:91]
	v_mfma_f32_16x16x32_bf16 v[76:79], v[156:159], v[236:239], v[76:79]
	v_mfma_f32_16x16x32_bf16 v[72:75], v[164:167], v[236:239], v[72:75]
	v_mfma_f32_16x16x32_bf16 v[116:119], v[168:171], v[208:211], v[116:119]
	v_mfma_f32_16x16x32_bf16 v[112:115], v[176:179], v[208:211], v[112:115]
	v_mfma_f32_16x16x32_bf16 v[100:103], v[168:171], v[216:219], v[100:103]
	v_mfma_f32_16x16x32_bf16 v[96:99], v[176:179], v[216:219], v[96:99]
	v_mfma_f32_16x16x32_bf16 v[84:87], v[168:171], v[224:227], v[84:87]
	v_mfma_f32_16x16x32_bf16 v[80:83], v[176:179], v[224:227], v[80:83]
	v_mfma_f32_16x16x32_bf16 v[68:71], v[168:171], v[232:235], v[68:71]
	v_mfma_f32_16x16x32_bf16 v[64:67], v[176:179], v[232:235], v[64:67]
	v_mfma_f32_16x16x32_bf16 v[116:119], v[172:175], v[212:215], v[116:119]
	v_mfma_f32_16x16x32_bf16 v[112:115], v[204:207], v[212:215], v[112:115]
	v_mfma_f32_16x16x32_bf16 v[100:103], v[172:175], v[220:223], v[100:103]
	v_mfma_f32_16x16x32_bf16 v[96:99], v[204:207], v[220:223], v[96:99]
	v_mfma_f32_16x16x32_bf16 v[84:87], v[172:175], v[228:231], v[84:87]
	v_mfma_f32_16x16x32_bf16 v[80:83], v[204:207], v[228:231], v[80:83]
	v_mfma_f32_16x16x32_bf16 v[68:71], v[172:175], v[236:239], v[68:71]
	v_mfma_f32_16x16x32_bf16 v[64:67], v[204:207], v[236:239], v[64:67]
	s_barrier
	s_add_i32 s4, s4, s28
	v_lshl_add_u64 v[180:181], v[180:181], 0, s[26:27]
	s_mov_b32 m0, s4
	ds_read_b128 v[208:211], v155 offset:49152
	ds_read_b128 v[212:215], v155 offset:50176
	ds_read_b128 v[216:219], v155 offset:51200
	ds_read_b128 v[220:223], v155 offset:52224
	ds_read_b128 v[224:227], v155 offset:53248
	ds_read_b128 v[228:231], v155 offset:54272
	ds_read_b128 v[232:235], v155 offset:55296
	ds_read_b128 v[236:239], v155 offset:56320
	global_load_lds_dwordx4 v[180:181], off
	s_add_i32 m0, s4, 0x2000
	s_add_u32 s34, s34, 0x40080
	v_lshl_add_u64 v[180:181], v[240:241], 0, s[26:27]
	s_addc_u32 s35, s35, 0
	s_add_i32 s4, s5, s28
	global_load_lds_dwordx4 v[180:181], off
	v_lshl_add_u64 v[180:181], s[34:35], 0, v[144:145]
	s_mov_b32 m0, s4
	s_nop 0
	global_load_lds_dwordx4 v[180:181], off
	v_lshl_add_u64 v[180:181], s[34:35], 0, v[128:129]
	s_add_i32 m0, s4, 0x2000
	s_nop 0
	global_load_lds_dwordx4 v[180:181], off
	v_lshl_add_u64 v[180:181], v[242:243], 0, s[26:27]
	s_mov_b32 m0, s72
	s_nop 0
	global_load_lds_dwordx4 v[180:181], off
	v_lshl_add_u64 v[180:181], v[244:245], 0, s[26:27]
	s_mov_b32 m0, s73
	s_nop 0
	global_load_lds_dwordx4 v[180:181], off
	s_waitcnt vmcnt(8)
	s_waitcnt lgkmcnt(0)
	s_barrier
	s_waitcnt lgkmcnt(0)
	v_mfma_f32_16x16x32_bf16 v[60:63], v[138:141], v[208:211], v[60:63]
	v_mfma_f32_16x16x32_bf16 v[56:59], v[160:163], v[208:211], v[56:59]
	v_mfma_f32_16x16x32_bf16 v[44:47], v[138:141], v[216:219], v[44:47]
	v_mfma_f32_16x16x32_bf16 v[40:43], v[160:163], v[216:219], v[40:43]
	v_mfma_f32_16x16x32_bf16 v[28:31], v[138:141], v[224:227], v[28:31]
	v_mfma_f32_16x16x32_bf16 v[24:27], v[160:163], v[224:227], v[24:27]
	v_mfma_f32_16x16x32_bf16 v[12:15], v[138:141], v[232:235], v[12:15]
	v_mfma_f32_16x16x32_bf16 v[8:11], v[160:163], v[232:235], v[8:11]
	v_mfma_f32_16x16x32_bf16 v[60:63], v[156:159], v[212:215], v[60:63]
	v_mfma_f32_16x16x32_bf16 v[56:59], v[164:167], v[212:215], v[56:59]
	v_mfma_f32_16x16x32_bf16 v[44:47], v[156:159], v[220:223], v[44:47]
	v_mfma_f32_16x16x32_bf16 v[40:43], v[164:167], v[220:223], v[40:43]
	v_mfma_f32_16x16x32_bf16 v[28:31], v[156:159], v[228:231], v[28:31]
	v_mfma_f32_16x16x32_bf16 v[24:27], v[164:167], v[228:231], v[24:27]
	v_mfma_f32_16x16x32_bf16 v[12:15], v[156:159], v[236:239], v[12:15]
	v_mfma_f32_16x16x32_bf16 v[8:11], v[164:167], v[236:239], v[8:11]
	v_mfma_f32_16x16x32_bf16 v[52:55], v[168:171], v[208:211], v[52:55]
	v_mfma_f32_16x16x32_bf16 v[48:51], v[176:179], v[208:211], v[48:51]
	v_mfma_f32_16x16x32_bf16 v[36:39], v[168:171], v[216:219], v[36:39]
	v_mfma_f32_16x16x32_bf16 v[32:35], v[176:179], v[216:219], v[32:35]
	v_mfma_f32_16x16x32_bf16 v[20:23], v[168:171], v[224:227], v[20:23]
	v_mfma_f32_16x16x32_bf16 v[16:19], v[176:179], v[224:227], v[16:19]
	v_mfma_f32_16x16x32_bf16 v[4:7], v[168:171], v[232:235], v[4:7]
	v_mfma_f32_16x16x32_bf16 v[0:3], v[176:179], v[232:235], v[0:3]
	v_mfma_f32_16x16x32_bf16 v[52:55], v[172:175], v[212:215], v[52:55]
	v_mfma_f32_16x16x32_bf16 v[48:51], v[204:207], v[212:215], v[48:51]
	v_mfma_f32_16x16x32_bf16 v[36:39], v[172:175], v[220:223], v[36:39]
	v_mfma_f32_16x16x32_bf16 v[32:35], v[204:207], v[220:223], v[32:35]
	v_mfma_f32_16x16x32_bf16 v[20:23], v[172:175], v[228:231], v[20:23]
	v_mfma_f32_16x16x32_bf16 v[16:19], v[204:207], v[228:231], v[16:19]
	v_mfma_f32_16x16x32_bf16 v[4:7], v[172:175], v[236:239], v[4:7]
	v_mfma_f32_16x16x32_bf16 v[0:3], v[204:207], v[236:239], v[0:3]
	s_barrier
	s_add_i32 s82, s82, 2
	s_add_u32 s62, s62, 0x100
	s_addc_u32 s63, s63, 0
	s_add_u32 s75, s75, 0x100
	s_addc_u32 s79, s79, 0
	s_cmp_gt_u32 s82, 13
	s_cbranch_scc0 .LBB0_311
	v_lshl_add_u32 v140, s2, 8, v142
	v_ashrrev_i32_e32 v141, 31, v140
	v_lshl_add_u64 v[156:157], v[140:141], 4, s[48:49]
	global_load_dwordx4 v[208:211], v[156:157], off
	global_load_dwordx4 v[212:215], v[156:157], off offset:256
	global_load_dwordx4 v[216:219], v[156:157], off offset:512
	global_load_dwordx4 v[220:223], v[156:157], off offset:768
	global_load_dwordx4 v[224:227], v[156:157], off offset:2048
	global_load_dwordx4 v[228:231], v[156:157], off offset:2304
	global_load_dwordx4 v[232:235], v[156:157], off offset:2560
	global_load_dwordx4 v[236:239], v[156:157], off offset:2816
	s_and_b64 vcc, exec, s[50:51]
	s_cbranch_vccz .LBB0_314
	s_barrier

.LBB0_406:
	s_add_u32 s62, s60, 0x100
	s_addc_u32 s63, s61, 0
	s_add_i32 s4, 0, 0x10000
	s_cmp_eq_u32 s29, 40
	s_cselect_b32 s65, s45, s63
	s_cselect_b32 s64, s44, s62
	v_add_u32_e32 v142, s4, v160
	s_cselect_b32 s35, s59, s28
	s_cselect_b32 s34, s58, s3
	s_add_i32 s5, 0, 0x14000
	ds_read_b128 v[138:141], v142
	ds_read_b128 v[154:157], v142 offset:1024
	ds_read_b128 v[172:175], v142 offset:2048
	ds_read_b128 v[176:179], v142 offset:3072
	v_add_u32_e32 v142, s5, v160
	ds_read_b128 v[204:207], v142
	ds_read_b128 v[208:211], v142 offset:1024
	ds_read_b128 v[212:215], v142 offset:2048
	ds_read_b128 v[216:219], v142 offset:3072
	v_lshl_add_u64 v[142:143], s[60:61], 0, v[134:135]
	s_add_i32 m0, s36, 0xc000
	ds_read_b128 v[220:223], v170
	ds_read_b128 v[224:227], v170 offset:1024
	ds_read_b128 v[228:231], v170 offset:2048
	ds_read_b128 v[232:235], v170 offset:3072
	ds_read_b128 v[236:239], v170 offset:4096
	ds_read_b128 v[240:243], v170 offset:5120
	ds_read_b128 v[244:247], v170 offset:6144
	ds_read_b128 v[248:251], v170 offset:7168
	global_load_lds_dwordx4 v[142:143], off
	v_lshl_add_u64 v[142:143], s[60:61], 0, v[136:137]
	s_add_i32 m0, s36, 0xe000
	s_nop 0
	global_load_lds_dwordx4 v[142:143], off
	s_waitcnt vmcnt(8)
	s_waitcnt lgkmcnt(0)
	s_barrier
	s_waitcnt lgkmcnt(0)
	v_mfma_f32_16x16x32_bf16 v[124:127], v[138:141], v[220:223], v[124:127]
	v_mfma_f32_16x16x32_bf16 v[120:123], v[172:175], v[220:223], v[120:123]
	v_mfma_f32_16x16x32_bf16 v[108:111], v[138:141], v[228:231], v[108:111]
	v_mfma_f32_16x16x32_bf16 v[104:107], v[172:175], v[228:231], v[104:107]
	v_mfma_f32_16x16x32_bf16 v[92:95], v[138:141], v[236:239], v[92:95]
	v_mfma_f32_16x16x32_bf16 v[88:91], v[172:175], v[236:239], v[88:91]
	v_mfma_f32_16x16x32_bf16 v[76:79], v[138:141], v[244:247], v[76:79]
	v_mfma_f32_16x16x32_bf16 v[72:75], v[172:175], v[244:247], v[72:75]
	v_mfma_f32_16x16x32_bf16 v[124:127], v[154:157], v[224:227], v[124:127]
	v_mfma_f32_16x16x32_bf16 v[120:123], v[176:179], v[224:227], v[120:123]
	v_mfma_f32_16x16x32_bf16 v[108:111], v[154:157], v[232:235], v[108:111]
	v_mfma_f32_16x16x32_bf16 v[104:107], v[176:179], v[232:235], v[104:107]
	v_mfma_f32_16x16x32_bf16 v[92:95], v[154:157], v[240:243], v[92:95]
	v_mfma_f32_16x16x32_bf16 v[88:91], v[176:179], v[240:243], v[88:91]
	v_mfma_f32_16x16x32_bf16 v[76:79], v[154:157], v[248:251], v[76:79]
	v_mfma_f32_16x16x32_bf16 v[72:75], v[176:179], v[248:251], v[72:75]
	v_mfma_f32_16x16x32_bf16 v[116:119], v[204:207], v[220:223], v[116:119]
	v_mfma_f32_16x16x32_bf16 v[112:115], v[212:215], v[220:223], v[112:115]
	v_mfma_f32_16x16x32_bf16 v[100:103], v[204:207], v[228:231], v[100:103]
	v_mfma_f32_16x16x32_bf16 v[96:99], v[212:215], v[228:231], v[96:99]
	v_mfma_f32_16x16x32_bf16 v[84:87], v[204:207], v[236:239], v[84:87]
	v_mfma_f32_16x16x32_bf16 v[80:83], v[212:215], v[236:239], v[80:83]
	v_mfma_f32_16x16x32_bf16 v[68:71], v[204:207], v[244:247], v[68:71]
	v_mfma_f32_16x16x32_bf16 v[64:67], v[212:215], v[244:247], v[64:67]
	v_mfma_f32_16x16x32_bf16 v[116:119], v[208:211], v[224:227], v[116:119]
	v_mfma_f32_16x16x32_bf16 v[112:115], v[216:219], v[224:227], v[112:115]
	v_mfma_f32_16x16x32_bf16 v[100:103], v[208:211], v[232:235], v[100:103]
	v_mfma_f32_16x16x32_bf16 v[96:99], v[216:219], v[232:235], v[96:99]
	v_mfma_f32_16x16x32_bf16 v[84:87], v[208:211], v[240:243], v[84:87]
	v_mfma_f32_16x16x32_bf16 v[80:83], v[216:219], v[240:243], v[80:83]
	v_mfma_f32_16x16x32_bf16 v[68:71], v[208:211], v[248:251], v[68:71]
	v_mfma_f32_16x16x32_bf16 v[64:67], v[216:219], v[248:251], v[64:67]
	s_barrier
	s_add_i32 s4, s4, s33
	v_lshl_add_u64 v[142:143], s[34:35], 0, v[128:129]
	s_mov_b32 m0, s4
	ds_read_b128 v[220:223], v170 offset:16384
	ds_read_b128 v[224:227], v170 offset:17408
	ds_read_b128 v[228:231], v170 offset:18432
	ds_read_b128 v[232:235], v170 offset:19456
	ds_read_b128 v[236:239], v170 offset:20480
	ds_read_b128 v[240:243], v170 offset:21504
	ds_read_b128 v[244:247], v170 offset:22528
	ds_read_b128 v[248:251], v170 offset:23552
	global_load_lds_dwordx4 v[142:143], off
	s_add_i32 m0, s4, 0x2000
	s_add_u32 s60, s34, 0xb0000
	v_lshl_add_u64 v[158:159], s[34:35], 0, v[130:131]
	s_addc_u32 s61, s35, 0
	s_add_i32 s4, s5, s33
	global_load_lds_dwordx4 v[158:159], off
	v_lshl_add_u64 v[180:181], s[60:61], 0, v[128:129]
	s_mov_b32 m0, s4
	v_lshl_add_u64 v[202:203], s[64:65], 0, v[130:131]
	global_load_lds_dwordx4 v[180:181], off
	v_lshl_add_u64 v[180:181], s[60:61], 0, v[130:131]
	s_add_i32 m0, s4, 0x2000
	s_nop 0
	global_load_lds_dwordx4 v[180:181], off
	v_lshl_add_u64 v[180:181], s[64:65], 0, v[128:129]
	s_mov_b32 m0, s36
	s_nop 0
	global_load_lds_dwordx4 v[180:181], off
	s_mov_b32 m0, s70
	s_nop 0
	global_load_lds_dwordx4 v[202:203], off
	s_waitcnt vmcnt(8)
	s_waitcnt lgkmcnt(0)
	s_barrier
	s_waitcnt lgkmcnt(0)
	v_mfma_f32_16x16x32_bf16 v[60:63], v[138:141], v[220:223], v[60:63]
	v_mfma_f32_16x16x32_bf16 v[56:59], v[172:175], v[220:223], v[56:59]
	v_mfma_f32_16x16x32_bf16 v[44:47], v[138:141], v[228:231], v[44:47]
	v_mfma_f32_16x16x32_bf16 v[40:43], v[172:175], v[228:231], v[40:43]
	v_mfma_f32_16x16x32_bf16 v[28:31], v[138:141], v[236:239], v[28:31]
	v_mfma_f32_16x16x32_bf16 v[24:27], v[172:175], v[236:239], v[24:27]
	v_mfma_f32_16x16x32_bf16 v[12:15], v[138:141], v[244:247], v[12:15]
	v_mfma_f32_16x16x32_bf16 v[8:11], v[172:175], v[244:247], v[8:11]
	v_mfma_f32_16x16x32_bf16 v[60:63], v[154:157], v[224:227], v[60:63]
	v_mfma_f32_16x16x32_bf16 v[56:59], v[176:179], v[224:227], v[56:59]
	v_mfma_f32_16x16x32_bf16 v[44:47], v[154:157], v[232:235], v[44:47]
	v_mfma_f32_16x16x32_bf16 v[40:43], v[176:179], v[232:235], v[40:43]
	v_mfma_f32_16x16x32_bf16 v[28:31], v[154:157], v[240:243], v[28:31]
	v_mfma_f32_16x16x32_bf16 v[24:27], v[176:179], v[240:243], v[24:27]
	v_mfma_f32_16x16x32_bf16 v[12:15], v[154:157], v[248:251], v[12:15]
	v_mfma_f32_16x16x32_bf16 v[8:11], v[176:179], v[248:251], v[8:11]
	v_mfma_f32_16x16x32_bf16 v[52:55], v[204:207], v[220:223], v[52:55]
	v_mfma_f32_16x16x32_bf16 v[48:51], v[212:215], v[220:223], v[48:51]
	v_mfma_f32_16x16x32_bf16 v[36:39], v[204:207], v[228:231], v[36:39]
	v_mfma_f32_16x16x32_bf16 v[32:35], v[212:215], v[228:231], v[32:35]
	v_mfma_f32_16x16x32_bf16 v[20:23], v[204:207], v[236:239], v[20:23]
	v_mfma_f32_16x16x32_bf16 v[16:19], v[212:215], v[236:239], v[16:19]
	v_mfma_f32_16x16x32_bf16 v[4:7], v[204:207], v[244:247], v[4:7]
	v_mfma_f32_16x16x32_bf16 v[0:3], v[212:215], v[244:247], v[0:3]
	v_mfma_f32_16x16x32_bf16 v[52:55], v[208:211], v[224:227], v[52:55]
	v_mfma_f32_16x16x32_bf16 v[48:51], v[216:219], v[224:227], v[48:51]
	v_mfma_f32_16x16x32_bf16 v[36:39], v[208:211], v[232:235], v[36:39]
	v_mfma_f32_16x16x32_bf16 v[32:35], v[216:219], v[232:235], v[32:35]
	v_mfma_f32_16x16x32_bf16 v[20:23], v[208:211], v[240:243], v[20:23]
	v_mfma_f32_16x16x32_bf16 v[16:19], v[216:219], v[240:243], v[16:19]
	v_mfma_f32_16x16x32_bf16 v[4:7], v[208:211], v[248:251], v[4:7]
	v_mfma_f32_16x16x32_bf16 v[0:3], v[216:219], v[248:251], v[0:3]
	s_barrier
	s_add_i32 s4, 0, 0x18000
	v_add_u32_e32 v144, s4, v160
	s_add_i32 s5, 0, 0x1c000
	ds_read_b128 v[138:141], v144
	ds_read_b128 v[154:157], v144 offset:1024
	ds_read_b128 v[172:175], v144 offset:2048
	ds_read_b128 v[176:179], v144 offset:3072
	v_add_u32_e32 v144, s5, v160
	ds_read_b128 v[204:207], v144
	ds_read_b128 v[208:211], v144 offset:1024
	ds_read_b128 v[212:215], v144 offset:2048
	ds_read_b128 v[216:219], v144 offset:3072
	s_add_u32 s60, s64, 0xb0000
	s_addc_u32 s61, s65, 0
	s_mov_b32 m0, s71
	v_lshl_add_u64 v[252:253], s[60:61], 0, v[128:129]
	ds_read_b128 v[220:223], v170 offset:32768
	ds_read_b128 v[224:227], v170 offset:33792
	ds_read_b128 v[228:231], v170 offset:34816
	ds_read_b128 v[232:235], v170 offset:35840
	ds_read_b128 v[236:239], v170 offset:36864
	ds_read_b128 v[240:243], v170 offset:37888
	ds_read_b128 v[244:247], v170 offset:38912
	ds_read_b128 v[248:251], v170 offset:39936
	global_load_lds_dwordx4 v[252:253], off
	v_lshl_add_u64 v[252:253], s[60:61], 0, v[130:131]
	s_mov_b32 m0, s72
	s_nop 0
	global_load_lds_dwordx4 v[252:253], off
	s_waitcnt vmcnt(8)
	s_waitcnt lgkmcnt(0)
	s_barrier
	s_waitcnt lgkmcnt(0)
	v_mfma_f32_16x16x32_bf16 v[124:127], v[138:141], v[220:223], v[124:127]
	v_mfma_f32_16x16x32_bf16 v[120:123], v[172:175], v[220:223], v[120:123]
	v_mfma_f32_16x16x32_bf16 v[108:111], v[138:141], v[228:231], v[108:111]
	v_mfma_f32_16x16x32_bf16 v[104:107], v[172:175], v[228:231], v[104:107]
	v_mfma_f32_16x16x32_bf16 v[92:95], v[138:141], v[236:239], v[92:95]
	v_mfma_f32_16x16x32_bf16 v[88:91], v[172:175], v[236:239], v[88:91]
	v_mfma_f32_16x16x32_bf16 v[76:79], v[138:141], v[244:247], v[76:79]
	v_mfma_f32_16x16x32_bf16 v[72:75], v[172:175], v[244:247], v[72:75]
	v_mfma_f32_16x16x32_bf16 v[124:127], v[154:157], v[224:227], v[124:127]
	v_mfma_f32_16x16x32_bf16 v[120:123], v[176:179], v[224:227], v[120:123]
	v_mfma_f32_16x16x32_bf16 v[108:111], v[154:157], v[232:235], v[108:111]
	v_mfma_f32_16x16x32_bf16 v[104:107], v[176:179], v[232:235], v[104:107]
	v_mfma_f32_16x16x32_bf16 v[92:95], v[154:157], v[240:243], v[92:95]
	v_mfma_f32_16x16x32_bf16 v[88:91], v[176:179], v[240:243], v[88:91]
	v_mfma_f32_16x16x32_bf16 v[76:79], v[154:157], v[248:251], v[76:79]
	v_mfma_f32_16x16x32_bf16 v[72:75], v[176:179], v[248:251], v[72:75]
	v_mfma_f32_16x16x32_bf16 v[116:119], v[204:207], v[220:223], v[116:119]
	v_mfma_f32_16x16x32_bf16 v[112:115], v[212:215], v[220:223], v[112:115]
	v_mfma_f32_16x16x32_bf16 v[100:103], v[204:207], v[228:231], v[100:103]
	v_mfma_f32_16x16x32_bf16 v[96:99], v[212:215], v[228:231], v[96:99]
	v_mfma_f32_16x16x32_bf16 v[84:87], v[204:207], v[236:239], v[84:87]
	v_mfma_f32_16x16x32_bf16 v[80:83], v[212:215], v[236:239], v[80:83]
	v_mfma_f32_16x16x32_bf16 v[68:71], v[204:207], v[244:247], v[68:71]
	v_mfma_f32_16x16x32_bf16 v[64:67], v[212:215], v[244:247], v[64:67]
	v_mfma_f32_16x16x32_bf16 v[116:119], v[208:211], v[224:227], v[116:119]
	v_mfma_f32_16x16x32_bf16 v[112:115], v[216:219], v[224:227], v[112:115]
	v_mfma_f32_16x16x32_bf16 v[100:103], v[208:211], v[232:235], v[100:103]
	v_mfma_f32_16x16x32_bf16 v[96:99], v[216:219], v[232:235], v[96:99]
	v_mfma_f32_16x16x32_bf16 v[84:87], v[208:211], v[240:243], v[84:87]
	v_mfma_f32_16x16x32_bf16 v[80:83], v[216:219], v[240:243], v[80:83]
	v_mfma_f32_16x16x32_bf16 v[68:71], v[208:211], v[248:251], v[68:71]
	v_mfma_f32_16x16x32_bf16 v[64:67], v[216:219], v[248:251], v[64:67]
	s_barrier
	s_add_i32 s4, s4, s33
	v_lshl_add_u64 v[142:143], v[142:143], 0, s[26:27]
	s_mov_b32 m0, s4
	ds_read_b128 v[220:223], v170 offset:49152
	ds_read_b128 v[224:227], v170 offset:50176
	ds_read_b128 v[228:231], v170 offset:51200
	ds_read_b128 v[232:235], v170 offset:52224
	ds_read_b128 v[236:239], v170 offset:53248
	ds_read_b128 v[240:243], v170 offset:54272
	ds_read_b128 v[244:247], v170 offset:55296
	ds_read_b128 v[248:251], v170 offset:56320
	global_load_lds_dwordx4 v[142:143], off
	s_add_i32 m0, s4, 0x2000
	s_add_u32 s34, s34, 0xb0080
	v_lshl_add_u64 v[142:143], v[158:159], 0, s[26:27]
	s_addc_u32 s35, s35, 0
	s_add_i32 s4, s5, s33
	global_load_lds_dwordx4 v[142:143], off
	v_lshl_add_u64 v[142:143], s[34:35], 0, v[128:129]
	s_mov_b32 m0, s4
	s_nop 0
	global_load_lds_dwordx4 v[142:143], off
	v_lshl_add_u64 v[142:143], s[34:35], 0, v[130:131]
	s_add_i32 m0, s4, 0x2000
	s_nop 0
	global_load_lds_dwordx4 v[142:143], off
	v_lshl_add_u64 v[142:143], v[180:181], 0, s[26:27]
	s_mov_b32 m0, s73
	s_nop 0
	global_load_lds_dwordx4 v[142:143], off
	v_lshl_add_u64 v[142:143], v[202:203], 0, s[26:27]
	s_mov_b32 m0, s74
	s_nop 0
	global_load_lds_dwordx4 v[142:143], off
	s_waitcnt vmcnt(8)
	s_waitcnt lgkmcnt(0)
	s_barrier
	s_waitcnt lgkmcnt(0)
	v_mfma_f32_16x16x32_bf16 v[60:63], v[138:141], v[220:223], v[60:63]
	v_mfma_f32_16x16x32_bf16 v[56:59], v[172:175], v[220:223], v[56:59]
	v_mfma_f32_16x16x32_bf16 v[44:47], v[138:141], v[228:231], v[44:47]
	v_mfma_f32_16x16x32_bf16 v[40:43], v[172:175], v[228:231], v[40:43]
	v_mfma_f32_16x16x32_bf16 v[28:31], v[138:141], v[236:239], v[28:31]
	v_mfma_f32_16x16x32_bf16 v[24:27], v[172:175], v[236:239], v[24:27]
	v_mfma_f32_16x16x32_bf16 v[12:15], v[138:141], v[244:247], v[12:15]
	v_mfma_f32_16x16x32_bf16 v[8:11], v[172:175], v[244:247], v[8:11]
	v_mfma_f32_16x16x32_bf16 v[60:63], v[154:157], v[224:227], v[60:63]
	v_mfma_f32_16x16x32_bf16 v[56:59], v[176:179], v[224:227], v[56:59]
	v_mfma_f32_16x16x32_bf16 v[44:47], v[154:157], v[232:235], v[44:47]
	v_mfma_f32_16x16x32_bf16 v[40:43], v[176:179], v[232:235], v[40:43]
	v_mfma_f32_16x16x32_bf16 v[28:31], v[154:157], v[240:243], v[28:31]
	v_mfma_f32_16x16x32_bf16 v[24:27], v[176:179], v[240:243], v[24:27]
	v_mfma_f32_16x16x32_bf16 v[12:15], v[154:157], v[248:251], v[12:15]
	v_mfma_f32_16x16x32_bf16 v[8:11], v[176:179], v[248:251], v[8:11]
	v_mfma_f32_16x16x32_bf16 v[52:55], v[204:207], v[220:223], v[52:55]
	v_mfma_f32_16x16x32_bf16 v[48:51], v[212:215], v[220:223], v[48:51]
	v_mfma_f32_16x16x32_bf16 v[36:39], v[204:207], v[228:231], v[36:39]
	v_mfma_f32_16x16x32_bf16 v[32:35], v[212:215], v[228:231], v[32:35]
	v_mfma_f32_16x16x32_bf16 v[20:23], v[204:207], v[236:239], v[20:23]
	v_mfma_f32_16x16x32_bf16 v[16:19], v[212:215], v[236:239], v[16:19]
	v_mfma_f32_16x16x32_bf16 v[4:7], v[204:207], v[244:247], v[4:7]
	v_mfma_f32_16x16x32_bf16 v[0:3], v[212:215], v[244:247], v[0:3]
	v_mfma_f32_16x16x32_bf16 v[52:55], v[208:211], v[224:227], v[52:55]
	v_mfma_f32_16x16x32_bf16 v[48:51], v[216:219], v[224:227], v[48:51]
	v_mfma_f32_16x16x32_bf16 v[36:39], v[208:211], v[232:235], v[36:39]
	v_mfma_f32_16x16x32_bf16 v[32:35], v[216:219], v[232:235], v[32:35]
	v_mfma_f32_16x16x32_bf16 v[20:23], v[208:211], v[240:243], v[20:23]
	v_mfma_f32_16x16x32_bf16 v[16:19], v[216:219], v[240:243], v[16:19]
	v_mfma_f32_16x16x32_bf16 v[4:7], v[208:211], v[248:251], v[4:7]
	v_mfma_f32_16x16x32_bf16 v[0:3], v[216:219], v[248:251], v[0:3]
	s_barrier
	s_add_i32 s29, s29, 2
	s_add_u32 s3, s3, 0x100
	s_addc_u32 s28, s28, 0
	s_cmp_gt_u32 s29, 41
	s_mov_b64 s[60:61], s[62:63]
	s_cbranch_scc0 .LBB0_406
	s_and_b64 vcc, exec, s[54:55]
	s_cbranch_vccz .LBB0_409
	s_barrier

.LBB0_456:
	s_add_u32 s60, s58, 0x100
	s_addc_u32 s61, s59, 0
	s_add_i32 s4, 0, 0x10000
	s_cmp_eq_u32 s51, 40
	s_cselect_b32 s63, s45, s61
	s_cselect_b32 s62, s44, s60
	s_cselect_b32 s35, s47, s29
	s_cselect_b32 s34, s46, s28
	s_add_i32 s5, 0, 0x14000
	v_add_u32_e32 v140, s4, v166
	v_add_u32_e32 v144, s5, v166
	ds_read_b128 v[128:131], v140
	ds_read_b128 v[132:135], v140 offset:1024
	ds_read_b128 v[136:139], v140 offset:2048
	ds_read_b128 v[140:143], v140 offset:3072
	ds_read_b128 v[178:181], v144
	ds_read_b128 v[204:207], v144 offset:1024
	ds_read_b128 v[208:211], v144 offset:2048
	ds_read_b128 v[212:215], v144 offset:3072
	v_lshl_add_u64 v[164:165], s[58:59], 0, v[160:161]
	s_add_i32 m0, s36, 0xc000
	ds_read_b128 v[216:219], v176
	ds_read_b128 v[220:223], v176 offset:1024
	ds_read_b128 v[224:227], v176 offset:2048
	ds_read_b128 v[228:231], v176 offset:3072
	ds_read_b128 v[232:235], v176 offset:4096
	ds_read_b128 v[236:239], v176 offset:5120
	ds_read_b128 v[240:243], v176 offset:6144
	ds_read_b128 v[244:247], v176 offset:7168
	global_load_lds_dwordx4 v[164:165], off
	v_lshl_add_u64 v[164:165], s[58:59], 0, v[162:163]
	s_add_i32 m0, s36, 0xe000
	s_nop 0
	global_load_lds_dwordx4 v[164:165], off
	s_waitcnt vmcnt(8)
	s_waitcnt lgkmcnt(0)
	s_barrier
	s_waitcnt lgkmcnt(0)
	v_mfma_f32_16x16x32_bf16 v[124:127], v[128:131], v[216:219], v[124:127]
	v_mfma_f32_16x16x32_bf16 v[120:123], v[136:139], v[216:219], v[120:123]
	v_mfma_f32_16x16x32_bf16 v[108:111], v[128:131], v[224:227], v[108:111]
	v_mfma_f32_16x16x32_bf16 v[104:107], v[136:139], v[224:227], v[104:107]
	v_mfma_f32_16x16x32_bf16 v[92:95], v[128:131], v[232:235], v[92:95]
	v_mfma_f32_16x16x32_bf16 v[88:91], v[136:139], v[232:235], v[88:91]
	v_mfma_f32_16x16x32_bf16 v[76:79], v[128:131], v[240:243], v[76:79]
	v_mfma_f32_16x16x32_bf16 v[72:75], v[136:139], v[240:243], v[72:75]
	v_mfma_f32_16x16x32_bf16 v[124:127], v[132:135], v[220:223], v[124:127]
	v_mfma_f32_16x16x32_bf16 v[120:123], v[140:143], v[220:223], v[120:123]
	v_mfma_f32_16x16x32_bf16 v[108:111], v[132:135], v[228:231], v[108:111]
	v_mfma_f32_16x16x32_bf16 v[104:107], v[140:143], v[228:231], v[104:107]
	v_mfma_f32_16x16x32_bf16 v[92:95], v[132:135], v[236:239], v[92:95]
	v_mfma_f32_16x16x32_bf16 v[88:91], v[140:143], v[236:239], v[88:91]
	v_mfma_f32_16x16x32_bf16 v[76:79], v[132:135], v[244:247], v[76:79]
	v_mfma_f32_16x16x32_bf16 v[72:75], v[140:143], v[244:247], v[72:75]
	v_mfma_f32_16x16x32_bf16 v[116:119], v[178:181], v[216:219], v[116:119]
	v_mfma_f32_16x16x32_bf16 v[112:115], v[208:211], v[216:219], v[112:115]
	v_mfma_f32_16x16x32_bf16 v[100:103], v[178:181], v[224:227], v[100:103]
	v_mfma_f32_16x16x32_bf16 v[96:99], v[208:211], v[224:227], v[96:99]
	v_mfma_f32_16x16x32_bf16 v[84:87], v[178:181], v[232:235], v[84:87]
	v_mfma_f32_16x16x32_bf16 v[80:83], v[208:211], v[232:235], v[80:83]
	v_mfma_f32_16x16x32_bf16 v[68:71], v[178:181], v[240:243], v[68:71]
	v_mfma_f32_16x16x32_bf16 v[64:67], v[208:211], v[240:243], v[64:67]
	v_mfma_f32_16x16x32_bf16 v[116:119], v[204:207], v[220:223], v[116:119]
	v_mfma_f32_16x16x32_bf16 v[112:115], v[212:215], v[220:223], v[112:115]
	v_mfma_f32_16x16x32_bf16 v[100:103], v[204:207], v[228:231], v[100:103]
	v_mfma_f32_16x16x32_bf16 v[96:99], v[212:215], v[228:231], v[96:99]
	v_mfma_f32_16x16x32_bf16 v[84:87], v[204:207], v[236:239], v[84:87]
	v_mfma_f32_16x16x32_bf16 v[80:83], v[212:215], v[236:239], v[80:83]
	v_mfma_f32_16x16x32_bf16 v[68:71], v[204:207], v[244:247], v[68:71]
	v_mfma_f32_16x16x32_bf16 v[64:67], v[212:215], v[244:247], v[64:67]
	s_barrier
	s_add_i32 s4, s4, s33
	v_lshl_add_u64 v[164:165], s[34:35], 0, v[154:155]
	s_mov_b32 m0, s4
	ds_read_b128 v[216:219], v176 offset:16384
	ds_read_b128 v[220:223], v176 offset:17408
	ds_read_b128 v[224:227], v176 offset:18432
	ds_read_b128 v[228:231], v176 offset:19456
	ds_read_b128 v[232:235], v176 offset:20480
	ds_read_b128 v[236:239], v176 offset:21504
	ds_read_b128 v[240:243], v176 offset:22528
	ds_read_b128 v[244:247], v176 offset:23552
	global_load_lds_dwordx4 v[164:165], off
	s_add_i32 m0, s4, 0x2000
	s_add_u32 s58, s34, 0xb0000
	v_lshl_add_u64 v[248:249], s[34:35], 0, v[156:157]
	s_addc_u32 s59, s35, 0
	s_add_i32 s4, s5, s33
	global_load_lds_dwordx4 v[248:249], off
	v_lshl_add_u64 v[250:251], s[58:59], 0, v[154:155]
	s_mov_b32 m0, s4
	v_lshl_add_u64 v[252:253], s[62:63], 0, v[156:157]
	global_load_lds_dwordx4 v[250:251], off
	v_lshl_add_u64 v[250:251], s[58:59], 0, v[156:157]
	s_add_i32 m0, s4, 0x2000
	s_nop 0
	global_load_lds_dwordx4 v[250:251], off
	v_lshl_add_u64 v[250:251], s[62:63], 0, v[154:155]
	s_mov_b32 m0, s36
	s_nop 0
	global_load_lds_dwordx4 v[250:251], off
	s_mov_b32 m0, s64
	s_nop 0
	global_load_lds_dwordx4 v[252:253], off
	s_waitcnt vmcnt(8)
	s_waitcnt lgkmcnt(0)
	s_barrier
	s_waitcnt lgkmcnt(0)
	v_mfma_f32_16x16x32_bf16 v[60:63], v[128:131], v[216:219], v[60:63]
	v_mfma_f32_16x16x32_bf16 v[56:59], v[136:139], v[216:219], v[56:59]
	v_mfma_f32_16x16x32_bf16 v[44:47], v[128:131], v[224:227], v[44:47]
	v_mfma_f32_16x16x32_bf16 v[40:43], v[136:139], v[224:227], v[40:43]
	v_mfma_f32_16x16x32_bf16 v[28:31], v[128:131], v[232:235], v[28:31]
	v_mfma_f32_16x16x32_bf16 v[24:27], v[136:139], v[232:235], v[24:27]
	v_mfma_f32_16x16x32_bf16 v[12:15], v[128:131], v[240:243], v[12:15]
	v_mfma_f32_16x16x32_bf16 v[8:11], v[136:139], v[240:243], v[8:11]
	v_mfma_f32_16x16x32_bf16 v[60:63], v[132:135], v[220:223], v[60:63]
	v_mfma_f32_16x16x32_bf16 v[56:59], v[140:143], v[220:223], v[56:59]
	v_mfma_f32_16x16x32_bf16 v[44:47], v[132:135], v[228:231], v[44:47]
	v_mfma_f32_16x16x32_bf16 v[40:43], v[140:143], v[228:231], v[40:43]
	v_mfma_f32_16x16x32_bf16 v[28:31], v[132:135], v[236:239], v[28:31]
	v_mfma_f32_16x16x32_bf16 v[24:27], v[140:143], v[236:239], v[24:27]
	v_mfma_f32_16x16x32_bf16 v[12:15], v[132:135], v[244:247], v[12:15]
	v_mfma_f32_16x16x32_bf16 v[8:11], v[140:143], v[244:247], v[8:11]
	v_mfma_f32_16x16x32_bf16 v[52:55], v[178:181], v[216:219], v[52:55]
	v_mfma_f32_16x16x32_bf16 v[48:51], v[208:211], v[216:219], v[48:51]
	v_mfma_f32_16x16x32_bf16 v[36:39], v[178:181], v[224:227], v[36:39]
	v_mfma_f32_16x16x32_bf16 v[32:35], v[208:211], v[224:227], v[32:35]
	v_mfma_f32_16x16x32_bf16 v[20:23], v[178:181], v[232:235], v[20:23]
	v_mfma_f32_16x16x32_bf16 v[16:19], v[208:211], v[232:235], v[16:19]
	v_mfma_f32_16x16x32_bf16 v[4:7], v[178:181], v[240:243], v[4:7]
	v_mfma_f32_16x16x32_bf16 v[0:3], v[208:211], v[240:243], v[0:3]
	v_mfma_f32_16x16x32_bf16 v[52:55], v[204:207], v[220:223], v[52:55]
	v_mfma_f32_16x16x32_bf16 v[48:51], v[212:215], v[220:223], v[48:51]
	v_mfma_f32_16x16x32_bf16 v[36:39], v[204:207], v[228:231], v[36:39]
	v_mfma_f32_16x16x32_bf16 v[32:35], v[212:215], v[228:231], v[32:35]
	v_mfma_f32_16x16x32_bf16 v[20:23], v[204:207], v[236:239], v[20:23]
	v_mfma_f32_16x16x32_bf16 v[16:19], v[212:215], v[236:239], v[16:19]
	v_mfma_f32_16x16x32_bf16 v[4:7], v[204:207], v[244:247], v[4:7]
	v_mfma_f32_16x16x32_bf16 v[0:3], v[212:215], v[244:247], v[0:3]
	s_barrier
	s_add_i32 s4, 0, 0x18000
	s_add_i32 s5, 0, 0x1c000
	v_add_u32_e32 v140, s4, v166
	v_add_u32_e32 v144, s5, v166
	ds_read_b128 v[128:131], v140
	ds_read_b128 v[132:135], v140 offset:1024
	ds_read_b128 v[136:139], v140 offset:2048
	ds_read_b128 v[140:143], v140 offset:3072
	ds_read_b128 v[178:181], v144
	ds_read_b128 v[204:207], v144 offset:1024
	ds_read_b128 v[208:211], v144 offset:2048
	ds_read_b128 v[212:215], v144 offset:3072
	s_add_u32 s58, s62, 0xb0000
	s_addc_u32 s59, s63, 0
	s_mov_b32 m0, s65
	v_lshl_add_u64 v[202:203], s[58:59], 0, v[154:155]
	ds_read_b128 v[216:219], v176 offset:32768
	ds_read_b128 v[220:223], v176 offset:33792
	ds_read_b128 v[224:227], v176 offset:34816
	ds_read_b128 v[228:231], v176 offset:35840
	ds_read_b128 v[232:235], v176 offset:36864
	ds_read_b128 v[236:239], v176 offset:37888
	ds_read_b128 v[240:243], v176 offset:38912
	ds_read_b128 v[244:247], v176 offset:39936
	global_load_lds_dwordx4 v[202:203], off
	v_lshl_add_u64 v[202:203], s[58:59], 0, v[156:157]
	s_mov_b32 m0, s70
	s_nop 0
	global_load_lds_dwordx4 v[202:203], off
	s_waitcnt vmcnt(8)
	s_waitcnt lgkmcnt(0)
	s_barrier
	s_waitcnt lgkmcnt(0)
	v_mfma_f32_16x16x32_bf16 v[124:127], v[128:131], v[216:219], v[124:127]
	v_mfma_f32_16x16x32_bf16 v[120:123], v[136:139], v[216:219], v[120:123]
	v_mfma_f32_16x16x32_bf16 v[108:111], v[128:131], v[224:227], v[108:111]
	v_mfma_f32_16x16x32_bf16 v[104:107], v[136:139], v[224:227], v[104:107]
	v_mfma_f32_16x16x32_bf16 v[92:95], v[128:131], v[232:235], v[92:95]
	v_mfma_f32_16x16x32_bf16 v[88:91], v[136:139], v[232:235], v[88:91]
	v_mfma_f32_16x16x32_bf16 v[76:79], v[128:131], v[240:243], v[76:79]
	v_mfma_f32_16x16x32_bf16 v[72:75], v[136:139], v[240:243], v[72:75]
	v_mfma_f32_16x16x32_bf16 v[124:127], v[132:135], v[220:223], v[124:127]
	v_mfma_f32_16x16x32_bf16 v[120:123], v[140:143], v[220:223], v[120:123]
	v_mfma_f32_16x16x32_bf16 v[108:111], v[132:135], v[228:231], v[108:111]
	v_mfma_f32_16x16x32_bf16 v[104:107], v[140:143], v[228:231], v[104:107]
	v_mfma_f32_16x16x32_bf16 v[92:95], v[132:135], v[236:239], v[92:95]
	v_mfma_f32_16x16x32_bf16 v[88:91], v[140:143], v[236:239], v[88:91]
	v_mfma_f32_16x16x32_bf16 v[76:79], v[132:135], v[244:247], v[76:79]
	v_mfma_f32_16x16x32_bf16 v[72:75], v[140:143], v[244:247], v[72:75]
	v_mfma_f32_16x16x32_bf16 v[116:119], v[178:181], v[216:219], v[116:119]
	v_mfma_f32_16x16x32_bf16 v[112:115], v[208:211], v[216:219], v[112:115]
	v_mfma_f32_16x16x32_bf16 v[100:103], v[178:181], v[224:227], v[100:103]
	v_mfma_f32_16x16x32_bf16 v[96:99], v[208:211], v[224:227], v[96:99]
	v_mfma_f32_16x16x32_bf16 v[84:87], v[178:181], v[232:235], v[84:87]
	v_mfma_f32_16x16x32_bf16 v[80:83], v[208:211], v[232:235], v[80:83]
	v_mfma_f32_16x16x32_bf16 v[68:71], v[178:181], v[240:243], v[68:71]
	v_mfma_f32_16x16x32_bf16 v[64:67], v[208:211], v[240:243], v[64:67]
	v_mfma_f32_16x16x32_bf16 v[116:119], v[204:207], v[220:223], v[116:119]
	v_mfma_f32_16x16x32_bf16 v[112:115], v[212:215], v[220:223], v[112:115]
	v_mfma_f32_16x16x32_bf16 v[100:103], v[204:207], v[228:231], v[100:103]
	v_mfma_f32_16x16x32_bf16 v[96:99], v[212:215], v[228:231], v[96:99]
	v_mfma_f32_16x16x32_bf16 v[84:87], v[204:207], v[236:239], v[84:87]
	v_mfma_f32_16x16x32_bf16 v[80:83], v[212:215], v[236:239], v[80:83]
	v_mfma_f32_16x16x32_bf16 v[68:71], v[204:207], v[244:247], v[68:71]
	v_mfma_f32_16x16x32_bf16 v[64:67], v[212:215], v[244:247], v[64:67]
	s_barrier
	s_add_i32 s4, s4, s33
	v_lshl_add_u64 v[164:165], v[164:165], 0, s[26:27]
	s_mov_b32 m0, s4
	ds_read_b128 v[216:219], v176 offset:49152
	ds_read_b128 v[220:223], v176 offset:50176
	ds_read_b128 v[224:227], v176 offset:51200
	ds_read_b128 v[228:231], v176 offset:52224
	ds_read_b128 v[232:235], v176 offset:53248
	ds_read_b128 v[236:239], v176 offset:54272
	ds_read_b128 v[240:243], v176 offset:55296
	ds_read_b128 v[244:247], v176 offset:56320
	global_load_lds_dwordx4 v[164:165], off
	s_add_i32 m0, s4, 0x2000
	s_add_u32 s34, s34, 0xb0080
	v_lshl_add_u64 v[164:165], v[248:249], 0, s[26:27]
	s_addc_u32 s35, s35, 0
	s_add_i32 s4, s5, s33
	global_load_lds_dwordx4 v[164:165], off
	v_lshl_add_u64 v[164:165], s[34:35], 0, v[154:155]
	s_mov_b32 m0, s4
	s_nop 0
	global_load_lds_dwordx4 v[164:165], off
	v_lshl_add_u64 v[164:165], s[34:35], 0, v[156:157]
	s_add_i32 m0, s4, 0x2000
	s_nop 0
	global_load_lds_dwordx4 v[164:165], off
	v_lshl_add_u64 v[164:165], v[250:251], 0, s[26:27]
	s_mov_b32 m0, s71
	s_nop 0
	global_load_lds_dwordx4 v[164:165], off
	v_lshl_add_u64 v[164:165], v[252:253], 0, s[26:27]
	s_mov_b32 m0, s72
	s_nop 0
	global_load_lds_dwordx4 v[164:165], off
	s_waitcnt vmcnt(8)
	s_waitcnt lgkmcnt(0)
	s_barrier
	s_waitcnt lgkmcnt(0)
	v_mfma_f32_16x16x32_bf16 v[60:63], v[128:131], v[216:219], v[60:63]
	v_mfma_f32_16x16x32_bf16 v[56:59], v[136:139], v[216:219], v[56:59]
	v_mfma_f32_16x16x32_bf16 v[44:47], v[128:131], v[224:227], v[44:47]
	v_mfma_f32_16x16x32_bf16 v[40:43], v[136:139], v[224:227], v[40:43]
	v_mfma_f32_16x16x32_bf16 v[28:31], v[128:131], v[232:235], v[28:31]
	v_mfma_f32_16x16x32_bf16 v[24:27], v[136:139], v[232:235], v[24:27]
	v_mfma_f32_16x16x32_bf16 v[12:15], v[128:131], v[240:243], v[12:15]
	v_mfma_f32_16x16x32_bf16 v[8:11], v[136:139], v[240:243], v[8:11]
	v_mfma_f32_16x16x32_bf16 v[60:63], v[132:135], v[220:223], v[60:63]
	v_mfma_f32_16x16x32_bf16 v[56:59], v[140:143], v[220:223], v[56:59]
	v_mfma_f32_16x16x32_bf16 v[44:47], v[132:135], v[228:231], v[44:47]
	v_mfma_f32_16x16x32_bf16 v[40:43], v[140:143], v[228:231], v[40:43]
	v_mfma_f32_16x16x32_bf16 v[28:31], v[132:135], v[236:239], v[28:31]
	v_mfma_f32_16x16x32_bf16 v[24:27], v[140:143], v[236:239], v[24:27]
	v_mfma_f32_16x16x32_bf16 v[12:15], v[132:135], v[244:247], v[12:15]
	v_mfma_f32_16x16x32_bf16 v[8:11], v[140:143], v[244:247], v[8:11]
	v_mfma_f32_16x16x32_bf16 v[52:55], v[178:181], v[216:219], v[52:55]
	v_mfma_f32_16x16x32_bf16 v[48:51], v[208:211], v[216:219], v[48:51]
	v_mfma_f32_16x16x32_bf16 v[36:39], v[178:181], v[224:227], v[36:39]
	v_mfma_f32_16x16x32_bf16 v[32:35], v[208:211], v[224:227], v[32:35]
	v_mfma_f32_16x16x32_bf16 v[20:23], v[178:181], v[232:235], v[20:23]
	v_mfma_f32_16x16x32_bf16 v[16:19], v[208:211], v[232:235], v[16:19]
	v_mfma_f32_16x16x32_bf16 v[4:7], v[178:181], v[240:243], v[4:7]
	v_mfma_f32_16x16x32_bf16 v[0:3], v[208:211], v[240:243], v[0:3]
	v_mfma_f32_16x16x32_bf16 v[52:55], v[204:207], v[220:223], v[52:55]
	v_mfma_f32_16x16x32_bf16 v[48:51], v[212:215], v[220:223], v[48:51]
	v_mfma_f32_16x16x32_bf16 v[36:39], v[204:207], v[228:231], v[36:39]
	v_mfma_f32_16x16x32_bf16 v[32:35], v[212:215], v[228:231], v[32:35]
	v_mfma_f32_16x16x32_bf16 v[20:23], v[204:207], v[236:239], v[20:23]
	v_mfma_f32_16x16x32_bf16 v[16:19], v[212:215], v[236:239], v[16:19]
	v_mfma_f32_16x16x32_bf16 v[4:7], v[204:207], v[244:247], v[4:7]
	v_mfma_f32_16x16x32_bf16 v[0:3], v[212:215], v[244:247], v[0:3]
	s_barrier
	s_add_i32 s51, s51, 2
	s_add_u32 s28, s28, 0x100
	s_addc_u32 s29, s29, 0
	s_cmp_gt_u32 s51, 41
	s_mov_b64 s[58:59], s[60:61]
	s_cbranch_scc0 .LBB0_456
	s_and_b64 vcc, exec, s[54:55]
	s_cbranch_vccz .LBB0_459
	s_barrier

.LBB0_605:
	s_add_u32 s4, s0, 0xfffc0080
	s_addc_u32 s5, s1, -1
	s_add_i32 s89, 0, 0x10000
	s_cmp_eq_u32 s88, 12
	s_cselect_b32 s43, s3, s5
	s_cselect_b32 s42, s36, s4
	s_cselect_b32 s35, s39, s84
	s_cselect_b32 s34, s71, s79
	s_add_i32 s4, 0, 0x14000
	v_add_u32_e32 v140, s89, v203
	v_add_u32_e32 v144, s4, v203
	ds_read_b128 v[128:131], v140
	ds_read_b128 v[132:135], v140 offset:1024
	ds_read_b128 v[136:139], v140 offset:2048
	ds_read_b128 v[140:143], v140 offset:3072
	ds_read_b128 v[168:171], v144
	ds_read_b128 v[172:175], v144 offset:1024
	ds_read_b128 v[176:179], v144 offset:2048
	ds_read_b128 v[206:209], v144 offset:3072
	v_lshl_add_u64 v[180:181], s[0:1], 0, v[164:165]
	s_add_i32 m0, s69, 0xc000
	ds_read_b128 v[210:213], v205
	ds_read_b128 v[214:217], v205 offset:1024
	ds_read_b128 v[218:221], v205 offset:2048
	ds_read_b128 v[222:225], v205 offset:3072
	ds_read_b128 v[226:229], v205 offset:4096
	ds_read_b128 v[230:233], v205 offset:5120
	ds_read_b128 v[234:237], v205 offset:6144
	ds_read_b128 v[238:241], v205 offset:7168
	global_load_lds_dwordx4 v[180:181], off
	v_lshl_add_u64 v[180:181], s[0:1], 0, v[166:167]
	s_add_i32 m0, s69, 0xe000
	s_nop 0
	global_load_lds_dwordx4 v[180:181], off
	s_waitcnt vmcnt(8)
	s_waitcnt lgkmcnt(0)
	s_barrier
	s_waitcnt lgkmcnt(0)
	v_mfma_f32_16x16x32_bf16 v[124:127], v[128:131], v[210:213], v[124:127]
	v_mfma_f32_16x16x32_bf16 v[120:123], v[136:139], v[210:213], v[120:123]
	v_mfma_f32_16x16x32_bf16 v[112:115], v[128:131], v[218:221], v[112:115]
	v_mfma_f32_16x16x32_bf16 v[108:111], v[136:139], v[218:221], v[108:111]
	v_mfma_f32_16x16x32_bf16 v[100:103], v[128:131], v[226:229], v[100:103]
	v_mfma_f32_16x16x32_bf16 v[92:95], v[136:139], v[226:229], v[92:95]
	v_mfma_f32_16x16x32_bf16 v[84:87], v[128:131], v[234:237], v[84:87]
	v_mfma_f32_16x16x32_bf16 v[76:79], v[136:139], v[234:237], v[76:79]
	v_mfma_f32_16x16x32_bf16 v[124:127], v[132:135], v[214:217], v[124:127]
	v_mfma_f32_16x16x32_bf16 v[120:123], v[140:143], v[214:217], v[120:123]
	v_mfma_f32_16x16x32_bf16 v[112:115], v[132:135], v[222:225], v[112:115]
	v_mfma_f32_16x16x32_bf16 v[108:111], v[140:143], v[222:225], v[108:111]
	v_mfma_f32_16x16x32_bf16 v[100:103], v[132:135], v[230:233], v[100:103]
	v_mfma_f32_16x16x32_bf16 v[92:95], v[140:143], v[230:233], v[92:95]
	v_mfma_f32_16x16x32_bf16 v[84:87], v[132:135], v[238:241], v[84:87]
	v_mfma_f32_16x16x32_bf16 v[76:79], v[140:143], v[238:241], v[76:79]
	v_mfma_f32_16x16x32_bf16 v[116:119], v[168:171], v[210:213], v[116:119]
	v_mfma_f32_16x16x32_bf16 v[104:107], v[176:179], v[210:213], v[104:107]
	v_mfma_f32_16x16x32_bf16 v[96:99], v[168:171], v[218:221], v[96:99]
	v_mfma_f32_16x16x32_bf16 v[88:91], v[176:179], v[218:221], v[88:91]
	v_mfma_f32_16x16x32_bf16 v[80:83], v[168:171], v[226:229], v[80:83]
	v_mfma_f32_16x16x32_bf16 v[72:75], v[176:179], v[226:229], v[72:75]
	v_mfma_f32_16x16x32_bf16 v[68:71], v[168:171], v[234:237], v[68:71]
	v_mfma_f32_16x16x32_bf16 v[64:67], v[176:179], v[234:237], v[64:67]
	v_mfma_f32_16x16x32_bf16 v[116:119], v[172:175], v[214:217], v[116:119]
	v_mfma_f32_16x16x32_bf16 v[104:107], v[206:209], v[214:217], v[104:107]
	v_mfma_f32_16x16x32_bf16 v[96:99], v[172:175], v[222:225], v[96:99]
	v_mfma_f32_16x16x32_bf16 v[88:91], v[206:209], v[222:225], v[88:91]
	v_mfma_f32_16x16x32_bf16 v[80:83], v[172:175], v[230:233], v[80:83]
	v_mfma_f32_16x16x32_bf16 v[72:75], v[206:209], v[230:233], v[72:75]
	v_mfma_f32_16x16x32_bf16 v[68:71], v[172:175], v[238:241], v[68:71]
	v_mfma_f32_16x16x32_bf16 v[64:67], v[206:209], v[238:241], v[64:67]
	s_barrier
	s_add_i32 s5, s89, s28
	v_lshl_add_u64 v[180:181], s[34:35], 0, v[156:157]
	s_mov_b32 m0, s5
	ds_read_b128 v[210:213], v205 offset:16384
	ds_read_b128 v[214:217], v205 offset:17408
	ds_read_b128 v[218:221], v205 offset:18432
	ds_read_b128 v[222:225], v205 offset:19456
	ds_read_b128 v[226:229], v205 offset:20480
	ds_read_b128 v[230:233], v205 offset:21504
	ds_read_b128 v[234:237], v205 offset:22528
	ds_read_b128 v[238:241], v205 offset:23552
	global_load_lds_dwordx4 v[180:181], off
	s_add_i32 m0, s5, 0x2000
	s_add_u32 s90, s34, 0x40000
	v_lshl_add_u64 v[242:243], s[34:35], 0, v[160:161]
	s_addc_u32 s91, s35, 0
	s_add_i32 s4, s4, s28
	global_load_lds_dwordx4 v[242:243], off
	v_lshl_add_u64 v[244:245], s[90:91], 0, v[156:157]
	s_mov_b32 m0, s4
	v_lshl_add_u64 v[246:247], s[42:43], 0, v[158:159]
	global_load_lds_dwordx4 v[244:245], off
	v_lshl_add_u64 v[244:245], s[90:91], 0, v[160:161]
	s_add_i32 m0, s4, 0x2000
	s_nop 0
	global_load_lds_dwordx4 v[244:245], off
	v_lshl_add_u64 v[244:245], s[42:43], 0, v[154:155]
	s_mov_b32 m0, s69
	s_nop 0
	global_load_lds_dwordx4 v[244:245], off
	s_mov_b32 m0, s62
	s_nop 0
	global_load_lds_dwordx4 v[246:247], off
	s_waitcnt vmcnt(8)
	s_waitcnt lgkmcnt(0)
	s_barrier
	s_waitcnt lgkmcnt(0)
	v_mfma_f32_16x16x32_bf16 v[60:63], v[128:131], v[210:213], v[60:63]
	v_mfma_f32_16x16x32_bf16 v[56:59], v[136:139], v[210:213], v[56:59]
	v_mfma_f32_16x16x32_bf16 v[52:55], v[128:131], v[218:221], v[52:55]
	v_mfma_f32_16x16x32_bf16 v[44:47], v[136:139], v[218:221], v[44:47]
	v_mfma_f32_16x16x32_bf16 v[36:39], v[128:131], v[226:229], v[36:39]
	v_mfma_f32_16x16x32_bf16 v[28:31], v[136:139], v[226:229], v[28:31]
	v_mfma_f32_16x16x32_bf16 v[20:23], v[128:131], v[234:237], v[20:23]
	v_mfma_f32_16x16x32_bf16 v[12:15], v[136:139], v[234:237], v[12:15]
	v_mfma_f32_16x16x32_bf16 v[60:63], v[132:135], v[214:217], v[60:63]
	v_mfma_f32_16x16x32_bf16 v[56:59], v[140:143], v[214:217], v[56:59]
	v_mfma_f32_16x16x32_bf16 v[52:55], v[132:135], v[222:225], v[52:55]
	v_mfma_f32_16x16x32_bf16 v[44:47], v[140:143], v[222:225], v[44:47]
	v_mfma_f32_16x16x32_bf16 v[36:39], v[132:135], v[230:233], v[36:39]
	v_mfma_f32_16x16x32_bf16 v[28:31], v[140:143], v[230:233], v[28:31]
	v_mfma_f32_16x16x32_bf16 v[20:23], v[132:135], v[238:241], v[20:23]
	v_mfma_f32_16x16x32_bf16 v[12:15], v[140:143], v[238:241], v[12:15]
	v_mfma_f32_16x16x32_bf16 v[48:51], v[168:171], v[210:213], v[48:51]
	v_mfma_f32_16x16x32_bf16 v[40:43], v[176:179], v[210:213], v[40:43]
	v_mfma_f32_16x16x32_bf16 v[32:35], v[168:171], v[218:221], v[32:35]
	v_mfma_f32_16x16x32_bf16 v[24:27], v[176:179], v[218:221], v[24:27]
	v_mfma_f32_16x16x32_bf16 v[16:19], v[168:171], v[226:229], v[16:19]
	v_mfma_f32_16x16x32_bf16 v[8:11], v[176:179], v[226:229], v[8:11]
	v_mfma_f32_16x16x32_bf16 v[4:7], v[168:171], v[234:237], v[4:7]
	v_mfma_f32_16x16x32_bf16 v[0:3], v[176:179], v[234:237], v[0:3]
	v_mfma_f32_16x16x32_bf16 v[48:51], v[172:175], v[214:217], v[48:51]
	v_mfma_f32_16x16x32_bf16 v[40:43], v[206:209], v[214:217], v[40:43]
	v_mfma_f32_16x16x32_bf16 v[32:35], v[172:175], v[222:225], v[32:35]
	v_mfma_f32_16x16x32_bf16 v[24:27], v[206:209], v[222:225], v[24:27]
	v_mfma_f32_16x16x32_bf16 v[16:19], v[172:175], v[230:233], v[16:19]
	v_mfma_f32_16x16x32_bf16 v[8:11], v[206:209], v[230:233], v[8:11]
	v_mfma_f32_16x16x32_bf16 v[4:7], v[172:175], v[238:241], v[4:7]
	v_mfma_f32_16x16x32_bf16 v[0:3], v[206:209], v[238:241], v[0:3]
	s_barrier
	s_add_i32 s4, 0, 0x18000
	s_add_i32 s5, 0, 0x1c000
	v_add_u32_e32 v140, s4, v203
	v_add_u32_e32 v144, s5, v203
	ds_read_b128 v[128:131], v140
	ds_read_b128 v[132:135], v140 offset:1024
	ds_read_b128 v[136:139], v140 offset:2048
	ds_read_b128 v[140:143], v140 offset:3072
	ds_read_b128 v[168:171], v144
	ds_read_b128 v[172:175], v144 offset:1024
	ds_read_b128 v[176:179], v144 offset:2048
	ds_read_b128 v[206:209], v144 offset:3072
	s_add_u32 s42, s42, 0x40000
	s_addc_u32 s43, s43, 0
	s_mov_b32 m0, s63
	v_lshl_add_u64 v[248:249], s[42:43], 0, v[154:155]
	ds_read_b128 v[210:213], v205 offset:32768
	ds_read_b128 v[214:217], v205 offset:33792
	ds_read_b128 v[218:221], v205 offset:34816
	ds_read_b128 v[222:225], v205 offset:35840
	ds_read_b128 v[226:229], v205 offset:36864
	ds_read_b128 v[230:233], v205 offset:37888
	ds_read_b128 v[234:237], v205 offset:38912
	ds_read_b128 v[238:241], v205 offset:39936
	global_load_lds_dwordx4 v[248:249], off
	v_lshl_add_u64 v[248:249], s[42:43], 0, v[158:159]
	s_mov_b32 m0, s50
	s_nop 0
	global_load_lds_dwordx4 v[248:249], off
	s_waitcnt vmcnt(8)
	s_waitcnt lgkmcnt(0)
	s_barrier
	s_waitcnt lgkmcnt(0)
	v_mfma_f32_16x16x32_bf16 v[124:127], v[128:131], v[210:213], v[124:127]
	v_mfma_f32_16x16x32_bf16 v[120:123], v[136:139], v[210:213], v[120:123]
	v_mfma_f32_16x16x32_bf16 v[112:115], v[128:131], v[218:221], v[112:115]
	v_mfma_f32_16x16x32_bf16 v[108:111], v[136:139], v[218:221], v[108:111]
	v_mfma_f32_16x16x32_bf16 v[100:103], v[128:131], v[226:229], v[100:103]
	v_mfma_f32_16x16x32_bf16 v[92:95], v[136:139], v[226:229], v[92:95]
	v_mfma_f32_16x16x32_bf16 v[84:87], v[128:131], v[234:237], v[84:87]
	v_mfma_f32_16x16x32_bf16 v[76:79], v[136:139], v[234:237], v[76:79]
	v_mfma_f32_16x16x32_bf16 v[124:127], v[132:135], v[214:217], v[124:127]
	v_mfma_f32_16x16x32_bf16 v[120:123], v[140:143], v[214:217], v[120:123]
	v_mfma_f32_16x16x32_bf16 v[112:115], v[132:135], v[222:225], v[112:115]
	v_mfma_f32_16x16x32_bf16 v[108:111], v[140:143], v[222:225], v[108:111]
	v_mfma_f32_16x16x32_bf16 v[100:103], v[132:135], v[230:233], v[100:103]
	v_mfma_f32_16x16x32_bf16 v[92:95], v[140:143], v[230:233], v[92:95]
	v_mfma_f32_16x16x32_bf16 v[84:87], v[132:135], v[238:241], v[84:87]
	v_mfma_f32_16x16x32_bf16 v[76:79], v[140:143], v[238:241], v[76:79]
	v_mfma_f32_16x16x32_bf16 v[116:119], v[168:171], v[210:213], v[116:119]
	v_mfma_f32_16x16x32_bf16 v[104:107], v[176:179], v[210:213], v[104:107]
	v_mfma_f32_16x16x32_bf16 v[96:99], v[168:171], v[218:221], v[96:99]
	v_mfma_f32_16x16x32_bf16 v[88:91], v[176:179], v[218:221], v[88:91]
	v_mfma_f32_16x16x32_bf16 v[80:83], v[168:171], v[226:229], v[80:83]
	v_mfma_f32_16x16x32_bf16 v[72:75], v[176:179], v[226:229], v[72:75]
	v_mfma_f32_16x16x32_bf16 v[68:71], v[168:171], v[234:237], v[68:71]
	v_mfma_f32_16x16x32_bf16 v[64:67], v[176:179], v[234:237], v[64:67]
	v_mfma_f32_16x16x32_bf16 v[116:119], v[172:175], v[214:217], v[116:119]
	v_mfma_f32_16x16x32_bf16 v[104:107], v[206:209], v[214:217], v[104:107]
	v_mfma_f32_16x16x32_bf16 v[96:99], v[172:175], v[222:225], v[96:99]
	v_mfma_f32_16x16x32_bf16 v[88:91], v[206:209], v[222:225], v[88:91]
	v_mfma_f32_16x16x32_bf16 v[80:83], v[172:175], v[230:233], v[80:83]
	v_mfma_f32_16x16x32_bf16 v[72:75], v[206:209], v[230:233], v[72:75]
	v_mfma_f32_16x16x32_bf16 v[68:71], v[172:175], v[238:241], v[68:71]
	v_mfma_f32_16x16x32_bf16 v[64:67], v[206:209], v[238:241], v[64:67]
	s_barrier
	s_add_i32 s4, s4, s28
	v_lshl_add_u64 v[180:181], v[180:181], 0, s[26:27]
	s_mov_b32 m0, s4
	ds_read_b128 v[210:213], v205 offset:49152
	ds_read_b128 v[214:217], v205 offset:50176
	ds_read_b128 v[218:221], v205 offset:51200
	ds_read_b128 v[222:225], v205 offset:52224
	ds_read_b128 v[226:229], v205 offset:53248
	ds_read_b128 v[230:233], v205 offset:54272
	ds_read_b128 v[234:237], v205 offset:55296
	ds_read_b128 v[238:241], v205 offset:56320
	global_load_lds_dwordx4 v[180:181], off
	s_add_i32 m0, s4, 0x2000
	s_add_u32 s34, s34, 0x40080
	v_lshl_add_u64 v[180:181], v[242:243], 0, s[26:27]
	s_addc_u32 s35, s35, 0
	s_add_i32 s4, s5, s28
	global_load_lds_dwordx4 v[180:181], off
	v_lshl_add_u64 v[180:181], s[34:35], 0, v[156:157]
	s_mov_b32 m0, s4
	s_nop 0
	global_load_lds_dwordx4 v[180:181], off
	v_lshl_add_u64 v[180:181], s[34:35], 0, v[160:161]
	s_add_i32 m0, s4, 0x2000
	s_nop 0
	global_load_lds_dwordx4 v[180:181], off
	v_lshl_add_u64 v[180:181], v[244:245], 0, s[26:27]
	s_mov_b32 m0, s51
	s_nop 0
	global_load_lds_dwordx4 v[180:181], off
	v_lshl_add_u64 v[180:181], v[246:247], 0, s[26:27]
	s_mov_b32 m0, s64
	s_nop 0
	global_load_lds_dwordx4 v[180:181], off
	s_waitcnt vmcnt(8)
	s_waitcnt lgkmcnt(0)
	s_barrier
	s_waitcnt lgkmcnt(0)
	v_mfma_f32_16x16x32_bf16 v[60:63], v[128:131], v[210:213], v[60:63]
	v_mfma_f32_16x16x32_bf16 v[56:59], v[136:139], v[210:213], v[56:59]
	v_mfma_f32_16x16x32_bf16 v[52:55], v[128:131], v[218:221], v[52:55]
	v_mfma_f32_16x16x32_bf16 v[44:47], v[136:139], v[218:221], v[44:47]
	v_mfma_f32_16x16x32_bf16 v[36:39], v[128:131], v[226:229], v[36:39]
	v_mfma_f32_16x16x32_bf16 v[28:31], v[136:139], v[226:229], v[28:31]
	v_mfma_f32_16x16x32_bf16 v[20:23], v[128:131], v[234:237], v[20:23]
	v_mfma_f32_16x16x32_bf16 v[12:15], v[136:139], v[234:237], v[12:15]
	v_mfma_f32_16x16x32_bf16 v[60:63], v[132:135], v[214:217], v[60:63]
	v_mfma_f32_16x16x32_bf16 v[56:59], v[140:143], v[214:217], v[56:59]
	v_mfma_f32_16x16x32_bf16 v[52:55], v[132:135], v[222:225], v[52:55]
	v_mfma_f32_16x16x32_bf16 v[44:47], v[140:143], v[222:225], v[44:47]
	v_mfma_f32_16x16x32_bf16 v[36:39], v[132:135], v[230:233], v[36:39]
	v_mfma_f32_16x16x32_bf16 v[28:31], v[140:143], v[230:233], v[28:31]
	v_mfma_f32_16x16x32_bf16 v[20:23], v[132:135], v[238:241], v[20:23]
	v_mfma_f32_16x16x32_bf16 v[12:15], v[140:143], v[238:241], v[12:15]
	v_mfma_f32_16x16x32_bf16 v[48:51], v[168:171], v[210:213], v[48:51]
	v_mfma_f32_16x16x32_bf16 v[40:43], v[176:179], v[210:213], v[40:43]
	v_mfma_f32_16x16x32_bf16 v[32:35], v[168:171], v[218:221], v[32:35]
	v_mfma_f32_16x16x32_bf16 v[24:27], v[176:179], v[218:221], v[24:27]
	v_mfma_f32_16x16x32_bf16 v[16:19], v[168:171], v[226:229], v[16:19]
	v_mfma_f32_16x16x32_bf16 v[8:11], v[176:179], v[226:229], v[8:11]
	v_mfma_f32_16x16x32_bf16 v[4:7], v[168:171], v[234:237], v[4:7]
	v_mfma_f32_16x16x32_bf16 v[0:3], v[176:179], v[234:237], v[0:3]
	v_mfma_f32_16x16x32_bf16 v[48:51], v[172:175], v[214:217], v[48:51]
	v_mfma_f32_16x16x32_bf16 v[40:43], v[206:209], v[214:217], v[40:43]
	v_mfma_f32_16x16x32_bf16 v[32:35], v[172:175], v[222:225], v[32:35]
	v_mfma_f32_16x16x32_bf16 v[24:27], v[206:209], v[222:225], v[24:27]
	v_mfma_f32_16x16x32_bf16 v[16:19], v[172:175], v[230:233], v[16:19]
	v_mfma_f32_16x16x32_bf16 v[8:11], v[206:209], v[230:233], v[8:11]
	v_mfma_f32_16x16x32_bf16 v[4:7], v[172:175], v[238:241], v[4:7]
	v_mfma_f32_16x16x32_bf16 v[0:3], v[206:209], v[238:241], v[0:3]
	s_barrier
	s_add_i32 s88, s88, 2
	s_add_u32 s0, s0, 0x100
	s_addc_u32 s1, s1, 0
	s_add_u32 s79, s79, 0x100
	s_addc_u32 s84, s84, 0
	s_cmp_gt_u32 s88, 13
	s_cbranch_scc0 .LBB0_605
	s_and_b64 vcc, exec, s[66:67]
	s_cbranch_vccz .LBB0_608
	s_barrier

.LBB0_1005:
	s_add_u32 s4, s54, 0xfffe0080
	s_addc_u32 s5, s55, -1
	s_add_i32 s72, 0, 0x10000
	s_cmp_eq_u32 s71, 4
	s_cselect_b32 s59, s29, s5
	s_cselect_b32 s58, s47, s4
	v_add_u32_e32 v138, s72, v141
	s_cselect_b32 s35, s45, s70
	s_cselect_b32 s34, s68, s69
	s_add_i32 s73, 0, 0x14000
	ds_read_b128 v[154:157], v138
	ds_read_b128 v[158:161], v138 offset:1024
	ds_read_b128 v[162:165], v138 offset:2048
	ds_read_b128 v[166:169], v138 offset:3072
	v_add_u32_e32 v138, s73, v141
	ds_read_b128 v[170:173], v138
	ds_read_b128 v[174:177], v138 offset:1024
	ds_read_b128 v[178:181], v138 offset:2048
	ds_read_b128 v[204:207], v138 offset:3072
	v_lshl_add_u64 v[138:139], s[54:55], 0, v[134:135]
	s_add_i32 m0, s53, 0xc000
	ds_read_b128 v[208:211], v143
	ds_read_b128 v[212:215], v143 offset:1024
	ds_read_b128 v[216:219], v143 offset:2048
	ds_read_b128 v[220:223], v143 offset:3072
	ds_read_b128 v[224:227], v143 offset:4096
	ds_read_b128 v[228:231], v143 offset:5120
	ds_read_b128 v[232:235], v143 offset:6144
	ds_read_b128 v[236:239], v143 offset:7168
	global_load_lds_dwordx4 v[138:139], off
	v_lshl_add_u64 v[138:139], s[54:55], 0, v[136:137]
	s_add_i32 m0, s53, 0xe000
	s_nop 0
	global_load_lds_dwordx4 v[138:139], off
	s_waitcnt vmcnt(8)
	s_waitcnt lgkmcnt(0)
	s_barrier
	s_waitcnt lgkmcnt(0)
	v_mfma_f32_16x16x32_bf16 v[120:123], v[154:157], v[208:211], v[120:123]
	v_mfma_f32_16x16x32_bf16 v[124:127], v[162:165], v[208:211], v[124:127]
	v_mfma_f32_16x16x32_bf16 v[104:107], v[154:157], v[216:219], v[104:107]
	v_mfma_f32_16x16x32_bf16 v[108:111], v[162:165], v[216:219], v[108:111]
	v_mfma_f32_16x16x32_bf16 v[88:91], v[154:157], v[224:227], v[88:91]
	v_mfma_f32_16x16x32_bf16 v[92:95], v[162:165], v[224:227], v[92:95]
	v_mfma_f32_16x16x32_bf16 v[72:75], v[154:157], v[232:235], v[72:75]
	v_mfma_f32_16x16x32_bf16 v[76:79], v[162:165], v[232:235], v[76:79]
	v_mfma_f32_16x16x32_bf16 v[120:123], v[158:161], v[212:215], v[120:123]
	v_mfma_f32_16x16x32_bf16 v[124:127], v[166:169], v[212:215], v[124:127]
	v_mfma_f32_16x16x32_bf16 v[104:107], v[158:161], v[220:223], v[104:107]
	v_mfma_f32_16x16x32_bf16 v[108:111], v[166:169], v[220:223], v[108:111]
	v_mfma_f32_16x16x32_bf16 v[88:91], v[158:161], v[228:231], v[88:91]
	v_mfma_f32_16x16x32_bf16 v[92:95], v[166:169], v[228:231], v[92:95]
	v_mfma_f32_16x16x32_bf16 v[72:75], v[158:161], v[236:239], v[72:75]
	v_mfma_f32_16x16x32_bf16 v[76:79], v[166:169], v[236:239], v[76:79]
	v_mfma_f32_16x16x32_bf16 v[112:115], v[170:173], v[208:211], v[112:115]
	v_mfma_f32_16x16x32_bf16 v[116:119], v[178:181], v[208:211], v[116:119]
	v_mfma_f32_16x16x32_bf16 v[96:99], v[170:173], v[216:219], v[96:99]
	v_mfma_f32_16x16x32_bf16 v[100:103], v[178:181], v[216:219], v[100:103]
	v_mfma_f32_16x16x32_bf16 v[80:83], v[170:173], v[224:227], v[80:83]
	v_mfma_f32_16x16x32_bf16 v[84:87], v[178:181], v[224:227], v[84:87]
	v_mfma_f32_16x16x32_bf16 v[64:67], v[170:173], v[232:235], v[64:67]
	v_mfma_f32_16x16x32_bf16 v[68:71], v[178:181], v[232:235], v[68:71]
	v_mfma_f32_16x16x32_bf16 v[112:115], v[174:177], v[212:215], v[112:115]
	v_mfma_f32_16x16x32_bf16 v[116:119], v[204:207], v[212:215], v[116:119]
	v_mfma_f32_16x16x32_bf16 v[96:99], v[174:177], v[220:223], v[96:99]
	v_mfma_f32_16x16x32_bf16 v[100:103], v[204:207], v[220:223], v[100:103]
	v_mfma_f32_16x16x32_bf16 v[80:83], v[174:177], v[228:231], v[80:83]
	v_mfma_f32_16x16x32_bf16 v[84:87], v[204:207], v[228:231], v[84:87]
	v_mfma_f32_16x16x32_bf16 v[64:67], v[174:177], v[236:239], v[64:67]
	v_mfma_f32_16x16x32_bf16 v[68:71], v[204:207], v[236:239], v[68:71]
	s_barrier
	s_add_i32 s4, s72, s30
	v_lshl_add_u64 v[138:139], s[34:35], 0, v[144:145]
	s_mov_b32 m0, s4
	ds_read_b128 v[208:211], v143 offset:16384
	ds_read_b128 v[212:215], v143 offset:17408
	ds_read_b128 v[216:219], v143 offset:18432
	ds_read_b128 v[220:223], v143 offset:19456
	ds_read_b128 v[224:227], v143 offset:20480
	ds_read_b128 v[228:231], v143 offset:21504
	ds_read_b128 v[232:235], v143 offset:22528
	ds_read_b128 v[236:239], v143 offset:23552
	global_load_lds_dwordx4 v[138:139], off
	s_add_i32 m0, s4, 0x2000
	s_add_u32 s4, s34, 0x20000
	v_lshl_add_u64 v[202:203], s[34:35], 0, v[132:133]
	s_addc_u32 s5, s35, 0
	s_add_i32 s72, s73, s30
	global_load_lds_dwordx4 v[202:203], off
	v_lshl_add_u64 v[240:241], s[4:5], 0, v[144:145]
	s_mov_b32 m0, s72
	v_lshl_add_u64 v[242:243], s[58:59], 0, v[130:131]
	global_load_lds_dwordx4 v[240:241], off
	v_lshl_add_u64 v[240:241], s[4:5], 0, v[132:133]
	s_add_i32 m0, s72, 0x2000
	s_nop 0
	global_load_lds_dwordx4 v[240:241], off
	v_lshl_add_u64 v[240:241], s[58:59], 0, v[128:129]
	s_mov_b32 m0, s53
	s_nop 0
	global_load_lds_dwordx4 v[240:241], off
	s_mov_b32 m0, s62
	s_nop 0
	global_load_lds_dwordx4 v[242:243], off
	s_waitcnt vmcnt(8)
	s_waitcnt lgkmcnt(0)
	s_barrier
	s_waitcnt lgkmcnt(0)
	v_mfma_f32_16x16x32_bf16 v[56:59], v[154:157], v[208:211], v[56:59]
	v_mfma_f32_16x16x32_bf16 v[60:63], v[162:165], v[208:211], v[60:63]
	v_mfma_f32_16x16x32_bf16 v[40:43], v[154:157], v[216:219], v[40:43]
	v_mfma_f32_16x16x32_bf16 v[44:47], v[162:165], v[216:219], v[44:47]
	v_mfma_f32_16x16x32_bf16 v[24:27], v[154:157], v[224:227], v[24:27]
	v_mfma_f32_16x16x32_bf16 v[28:31], v[162:165], v[224:227], v[28:31]
	v_mfma_f32_16x16x32_bf16 v[8:11], v[154:157], v[232:235], v[8:11]
	v_mfma_f32_16x16x32_bf16 v[12:15], v[162:165], v[232:235], v[12:15]
	v_mfma_f32_16x16x32_bf16 v[56:59], v[158:161], v[212:215], v[56:59]
	v_mfma_f32_16x16x32_bf16 v[60:63], v[166:169], v[212:215], v[60:63]
	v_mfma_f32_16x16x32_bf16 v[40:43], v[158:161], v[220:223], v[40:43]
	v_mfma_f32_16x16x32_bf16 v[44:47], v[166:169], v[220:223], v[44:47]
	v_mfma_f32_16x16x32_bf16 v[24:27], v[158:161], v[228:231], v[24:27]
	v_mfma_f32_16x16x32_bf16 v[28:31], v[166:169], v[228:231], v[28:31]
	v_mfma_f32_16x16x32_bf16 v[8:11], v[158:161], v[236:239], v[8:11]
	v_mfma_f32_16x16x32_bf16 v[12:15], v[166:169], v[236:239], v[12:15]
	v_mfma_f32_16x16x32_bf16 v[48:51], v[170:173], v[208:211], v[48:51]
	v_mfma_f32_16x16x32_bf16 v[52:55], v[178:181], v[208:211], v[52:55]
	v_mfma_f32_16x16x32_bf16 v[32:35], v[170:173], v[216:219], v[32:35]
	v_mfma_f32_16x16x32_bf16 v[36:39], v[178:181], v[216:219], v[36:39]
	v_mfma_f32_16x16x32_bf16 v[16:19], v[170:173], v[224:227], v[16:19]
	v_mfma_f32_16x16x32_bf16 v[20:23], v[178:181], v[224:227], v[20:23]
	v_mfma_f32_16x16x32_bf16 v[0:3], v[170:173], v[232:235], v[0:3]
	v_mfma_f32_16x16x32_bf16 v[4:7], v[178:181], v[232:235], v[4:7]
	v_mfma_f32_16x16x32_bf16 v[48:51], v[174:177], v[212:215], v[48:51]
	v_mfma_f32_16x16x32_bf16 v[52:55], v[204:207], v[212:215], v[52:55]
	v_mfma_f32_16x16x32_bf16 v[32:35], v[174:177], v[220:223], v[32:35]
	v_mfma_f32_16x16x32_bf16 v[36:39], v[204:207], v[220:223], v[36:39]
	v_mfma_f32_16x16x32_bf16 v[16:19], v[174:177], v[228:231], v[16:19]
	v_mfma_f32_16x16x32_bf16 v[20:23], v[204:207], v[228:231], v[20:23]
	v_mfma_f32_16x16x32_bf16 v[0:3], v[174:177], v[236:239], v[0:3]
	v_mfma_f32_16x16x32_bf16 v[4:7], v[204:207], v[236:239], v[4:7]
	s_barrier
	s_add_i32 s72, 0, 0x18000
	s_add_i32 s73, 0, 0x1c000
	v_add_u32_e32 v166, s72, v141
	v_add_u32_e32 v204, s73, v141
	ds_read_b128 v[154:157], v166
	ds_read_b128 v[158:161], v166 offset:1024
	ds_read_b128 v[162:165], v166 offset:2048
	ds_read_b128 v[166:169], v166 offset:3072
	ds_read_b128 v[170:173], v204
	ds_read_b128 v[174:177], v204 offset:1024
	ds_read_b128 v[178:181], v204 offset:2048
	ds_read_b128 v[204:207], v204 offset:3072
	s_add_u32 s4, s58, 0x20000
	s_addc_u32 s5, s59, 0
	s_mov_b32 m0, s63
	v_lshl_add_u64 v[244:245], s[4:5], 0, v[128:129]
	ds_read_b128 v[208:211], v143 offset:32768
	ds_read_b128 v[212:215], v143 offset:33792
	ds_read_b128 v[216:219], v143 offset:34816
	ds_read_b128 v[220:223], v143 offset:35840
	ds_read_b128 v[224:227], v143 offset:36864
	ds_read_b128 v[228:231], v143 offset:37888
	ds_read_b128 v[232:235], v143 offset:38912
	ds_read_b128 v[236:239], v143 offset:39936
	global_load_lds_dwordx4 v[244:245], off
	v_lshl_add_u64 v[244:245], s[4:5], 0, v[130:131]
	s_mov_b32 m0, s64
	s_nop 0
	global_load_lds_dwordx4 v[244:245], off
	s_waitcnt vmcnt(8)
	s_waitcnt lgkmcnt(0)
	s_barrier
	s_waitcnt lgkmcnt(0)
	v_mfma_f32_16x16x32_bf16 v[120:123], v[154:157], v[208:211], v[120:123]
	v_mfma_f32_16x16x32_bf16 v[124:127], v[162:165], v[208:211], v[124:127]
	v_mfma_f32_16x16x32_bf16 v[104:107], v[154:157], v[216:219], v[104:107]
	v_mfma_f32_16x16x32_bf16 v[108:111], v[162:165], v[216:219], v[108:111]
	v_mfma_f32_16x16x32_bf16 v[88:91], v[154:157], v[224:227], v[88:91]
	v_mfma_f32_16x16x32_bf16 v[92:95], v[162:165], v[224:227], v[92:95]
	v_mfma_f32_16x16x32_bf16 v[72:75], v[154:157], v[232:235], v[72:75]
	v_mfma_f32_16x16x32_bf16 v[76:79], v[162:165], v[232:235], v[76:79]
	v_mfma_f32_16x16x32_bf16 v[120:123], v[158:161], v[212:215], v[120:123]
	v_mfma_f32_16x16x32_bf16 v[124:127], v[166:169], v[212:215], v[124:127]
	v_mfma_f32_16x16x32_bf16 v[104:107], v[158:161], v[220:223], v[104:107]
	v_mfma_f32_16x16x32_bf16 v[108:111], v[166:169], v[220:223], v[108:111]
	v_mfma_f32_16x16x32_bf16 v[88:91], v[158:161], v[228:231], v[88:91]
	v_mfma_f32_16x16x32_bf16 v[92:95], v[166:169], v[228:231], v[92:95]
	v_mfma_f32_16x16x32_bf16 v[72:75], v[158:161], v[236:239], v[72:75]
	v_mfma_f32_16x16x32_bf16 v[76:79], v[166:169], v[236:239], v[76:79]
	v_mfma_f32_16x16x32_bf16 v[112:115], v[170:173], v[208:211], v[112:115]
	v_mfma_f32_16x16x32_bf16 v[116:119], v[178:181], v[208:211], v[116:119]
	v_mfma_f32_16x16x32_bf16 v[96:99], v[170:173], v[216:219], v[96:99]
	v_mfma_f32_16x16x32_bf16 v[100:103], v[178:181], v[216:219], v[100:103]
	v_mfma_f32_16x16x32_bf16 v[80:83], v[170:173], v[224:227], v[80:83]
	v_mfma_f32_16x16x32_bf16 v[84:87], v[178:181], v[224:227], v[84:87]
	v_mfma_f32_16x16x32_bf16 v[64:67], v[170:173], v[232:235], v[64:67]
	v_mfma_f32_16x16x32_bf16 v[68:71], v[178:181], v[232:235], v[68:71]
	v_mfma_f32_16x16x32_bf16 v[112:115], v[174:177], v[212:215], v[112:115]
	v_mfma_f32_16x16x32_bf16 v[116:119], v[204:207], v[212:215], v[116:119]
	v_mfma_f32_16x16x32_bf16 v[96:99], v[174:177], v[220:223], v[96:99]
	v_mfma_f32_16x16x32_bf16 v[100:103], v[204:207], v[220:223], v[100:103]
	v_mfma_f32_16x16x32_bf16 v[80:83], v[174:177], v[228:231], v[80:83]
	v_mfma_f32_16x16x32_bf16 v[84:87], v[204:207], v[228:231], v[84:87]
	v_mfma_f32_16x16x32_bf16 v[64:67], v[174:177], v[236:239], v[64:67]
	v_mfma_f32_16x16x32_bf16 v[68:71], v[204:207], v[236:239], v[68:71]
	s_barrier
	s_add_i32 s4, s72, s30
	v_lshl_add_u64 v[138:139], v[138:139], 0, s[26:27]
	s_mov_b32 m0, s4
	ds_read_b128 v[208:211], v143 offset:49152
	ds_read_b128 v[212:215], v143 offset:50176
	ds_read_b128 v[216:219], v143 offset:51200
	ds_read_b128 v[220:223], v143 offset:52224
	ds_read_b128 v[224:227], v143 offset:53248
	ds_read_b128 v[228:231], v143 offset:54272
	ds_read_b128 v[232:235], v143 offset:55296
	ds_read_b128 v[236:239], v143 offset:56320
	global_load_lds_dwordx4 v[138:139], off
	s_add_i32 m0, s4, 0x2000
	s_add_u32 s4, s34, 0x20080
	v_lshl_add_u64 v[138:139], v[202:203], 0, s[26:27]
	s_addc_u32 s5, s35, 0
	s_add_i32 s34, s73, s30
	global_load_lds_dwordx4 v[138:139], off
	v_lshl_add_u64 v[138:139], s[4:5], 0, v[144:145]
	s_mov_b32 m0, s34
	s_nop 0
	global_load_lds_dwordx4 v[138:139], off
	v_lshl_add_u64 v[138:139], s[4:5], 0, v[132:133]
	s_add_i32 m0, s34, 0x2000
	s_nop 0
	global_load_lds_dwordx4 v[138:139], off
	v_lshl_add_u64 v[138:139], v[240:241], 0, s[26:27]
	s_mov_b32 m0, s65
	s_nop 0
	global_load_lds_dwordx4 v[138:139], off
	v_lshl_add_u64 v[138:139], v[242:243], 0, s[26:27]
	s_mov_b32 m0, s66
	s_nop 0
	global_load_lds_dwordx4 v[138:139], off
	s_waitcnt vmcnt(8)
	s_waitcnt lgkmcnt(0)
	s_barrier
	s_waitcnt lgkmcnt(0)
	v_mfma_f32_16x16x32_bf16 v[56:59], v[154:157], v[208:211], v[56:59]
	v_mfma_f32_16x16x32_bf16 v[60:63], v[162:165], v[208:211], v[60:63]
	v_mfma_f32_16x16x32_bf16 v[40:43], v[154:157], v[216:219], v[40:43]
	v_mfma_f32_16x16x32_bf16 v[44:47], v[162:165], v[216:219], v[44:47]
	v_mfma_f32_16x16x32_bf16 v[24:27], v[154:157], v[224:227], v[24:27]
	v_mfma_f32_16x16x32_bf16 v[28:31], v[162:165], v[224:227], v[28:31]
	v_mfma_f32_16x16x32_bf16 v[8:11], v[154:157], v[232:235], v[8:11]
	v_mfma_f32_16x16x32_bf16 v[12:15], v[162:165], v[232:235], v[12:15]
	v_mfma_f32_16x16x32_bf16 v[56:59], v[158:161], v[212:215], v[56:59]
	v_mfma_f32_16x16x32_bf16 v[60:63], v[166:169], v[212:215], v[60:63]
	v_mfma_f32_16x16x32_bf16 v[40:43], v[158:161], v[220:223], v[40:43]
	v_mfma_f32_16x16x32_bf16 v[44:47], v[166:169], v[220:223], v[44:47]
	v_mfma_f32_16x16x32_bf16 v[24:27], v[158:161], v[228:231], v[24:27]
	v_mfma_f32_16x16x32_bf16 v[28:31], v[166:169], v[228:231], v[28:31]
	v_mfma_f32_16x16x32_bf16 v[8:11], v[158:161], v[236:239], v[8:11]
	v_mfma_f32_16x16x32_bf16 v[12:15], v[166:169], v[236:239], v[12:15]
	v_mfma_f32_16x16x32_bf16 v[48:51], v[170:173], v[208:211], v[48:51]
	v_mfma_f32_16x16x32_bf16 v[52:55], v[178:181], v[208:211], v[52:55]
	v_mfma_f32_16x16x32_bf16 v[32:35], v[170:173], v[216:219], v[32:35]
	v_mfma_f32_16x16x32_bf16 v[36:39], v[178:181], v[216:219], v[36:39]
	v_mfma_f32_16x16x32_bf16 v[16:19], v[170:173], v[224:227], v[16:19]
	v_mfma_f32_16x16x32_bf16 v[20:23], v[178:181], v[224:227], v[20:23]
	v_mfma_f32_16x16x32_bf16 v[0:3], v[170:173], v[232:235], v[0:3]
	v_mfma_f32_16x16x32_bf16 v[4:7], v[178:181], v[232:235], v[4:7]
	v_mfma_f32_16x16x32_bf16 v[48:51], v[174:177], v[212:215], v[48:51]
	v_mfma_f32_16x16x32_bf16 v[52:55], v[204:207], v[212:215], v[52:55]
	v_mfma_f32_16x16x32_bf16 v[32:35], v[174:177], v[220:223], v[32:35]
	v_mfma_f32_16x16x32_bf16 v[36:39], v[204:207], v[220:223], v[36:39]
	v_mfma_f32_16x16x32_bf16 v[16:19], v[174:177], v[228:231], v[16:19]
	v_mfma_f32_16x16x32_bf16 v[20:23], v[204:207], v[228:231], v[20:23]
	v_mfma_f32_16x16x32_bf16 v[0:3], v[174:177], v[236:239], v[0:3]
	v_mfma_f32_16x16x32_bf16 v[4:7], v[204:207], v[236:239], v[4:7]
	s_barrier
	s_add_i32 s71, s71, 2
	s_add_u32 s54, s54, 0x100
	s_addc_u32 s55, s55, 0
	s_add_u32 s69, s69, 0x100
	s_addc_u32 s70, s70, 0
	s_cmp_gt_u32 s71, 5
	s_cbranch_scc0 .LBB0_1005
	v_readlane_b32 s68, v255, 7
	s_and_b64 vcc, exec, s[42:43]
	v_readlane_b32 s69, v255, 8
	s_cbranch_vccz .LBB0_1008
	s_barrier

.LBB0_1093:
	s_add_u32 s4, s58, 0xfffe0080
	s_addc_u32 s5, s59, -1
	s_add_i32 s74, 0, 0x10000
	s_cmp_eq_u32 s73, 4
	s_cselect_b32 s61, s33, s5
	s_cselect_b32 s60, s36, s4
	s_cselect_b32 s35, s49, s72
	s_cselect_b32 s34, s51, s71
	s_add_i32 s75, 0, 0x14000
	v_add_u32_e32 v164, s74, v143
	v_add_u32_e32 v180, s75, v143
	ds_read_b128 v[138:141], v164
	ds_read_b128 v[156:159], v164 offset:1024
	ds_read_b128 v[160:163], v164 offset:2048
	ds_read_b128 v[164:167], v164 offset:3072
	ds_read_b128 v[168:171], v180
	ds_read_b128 v[172:175], v180 offset:1024
	ds_read_b128 v[176:179], v180 offset:2048
	ds_read_b128 v[204:207], v180 offset:3072
	v_lshl_add_u64 v[180:181], s[58:59], 0, v[134:135]
	s_add_i32 m0, s64, 0xc000
	ds_read_b128 v[208:211], v155
	ds_read_b128 v[212:215], v155 offset:1024
	ds_read_b128 v[216:219], v155 offset:2048
	ds_read_b128 v[220:223], v155 offset:3072
	ds_read_b128 v[224:227], v155 offset:4096
	ds_read_b128 v[228:231], v155 offset:5120
	ds_read_b128 v[232:235], v155 offset:6144
	ds_read_b128 v[236:239], v155 offset:7168
	global_load_lds_dwordx4 v[180:181], off
	v_lshl_add_u64 v[180:181], s[58:59], 0, v[136:137]
	s_add_i32 m0, s64, 0xe000
	s_nop 0
	global_load_lds_dwordx4 v[180:181], off
	s_waitcnt vmcnt(8)
	s_waitcnt lgkmcnt(0)
	s_barrier
	s_waitcnt lgkmcnt(0)
	v_mfma_f32_16x16x32_bf16 v[124:127], v[138:141], v[208:211], v[124:127]
	v_mfma_f32_16x16x32_bf16 v[120:123], v[160:163], v[208:211], v[120:123]
	v_mfma_f32_16x16x32_bf16 v[108:111], v[138:141], v[216:219], v[108:111]
	v_mfma_f32_16x16x32_bf16 v[104:107], v[160:163], v[216:219], v[104:107]
	v_mfma_f32_16x16x32_bf16 v[92:95], v[138:141], v[224:227], v[92:95]
	v_mfma_f32_16x16x32_bf16 v[88:91], v[160:163], v[224:227], v[88:91]
	v_mfma_f32_16x16x32_bf16 v[76:79], v[138:141], v[232:235], v[76:79]
	v_mfma_f32_16x16x32_bf16 v[72:75], v[160:163], v[232:235], v[72:75]
	v_mfma_f32_16x16x32_bf16 v[124:127], v[156:159], v[212:215], v[124:127]
	v_mfma_f32_16x16x32_bf16 v[120:123], v[164:167], v[212:215], v[120:123]
	v_mfma_f32_16x16x32_bf16 v[108:111], v[156:159], v[220:223], v[108:111]
	v_mfma_f32_16x16x32_bf16 v[104:107], v[164:167], v[220:223], v[104:107]
	v_mfma_f32_16x16x32_bf16 v[92:95], v[156:159], v[228:231], v[92:95]
	v_mfma_f32_16x16x32_bf16 v[88:91], v[164:167], v[228:231], v[88:91]
	v_mfma_f32_16x16x32_bf16 v[76:79], v[156:159], v[236:239], v[76:79]
	v_mfma_f32_16x16x32_bf16 v[72:75], v[164:167], v[236:239], v[72:75]
	v_mfma_f32_16x16x32_bf16 v[116:119], v[168:171], v[208:211], v[116:119]
	v_mfma_f32_16x16x32_bf16 v[112:115], v[176:179], v[208:211], v[112:115]
	v_mfma_f32_16x16x32_bf16 v[100:103], v[168:171], v[216:219], v[100:103]
	v_mfma_f32_16x16x32_bf16 v[96:99], v[176:179], v[216:219], v[96:99]
	v_mfma_f32_16x16x32_bf16 v[84:87], v[168:171], v[224:227], v[84:87]
	v_mfma_f32_16x16x32_bf16 v[80:83], v[176:179], v[224:227], v[80:83]
	v_mfma_f32_16x16x32_bf16 v[68:71], v[168:171], v[232:235], v[68:71]
	v_mfma_f32_16x16x32_bf16 v[64:67], v[176:179], v[232:235], v[64:67]
	v_mfma_f32_16x16x32_bf16 v[116:119], v[172:175], v[212:215], v[116:119]
	v_mfma_f32_16x16x32_bf16 v[112:115], v[204:207], v[212:215], v[112:115]
	v_mfma_f32_16x16x32_bf16 v[100:103], v[172:175], v[220:223], v[100:103]
	v_mfma_f32_16x16x32_bf16 v[96:99], v[204:207], v[220:223], v[96:99]
	v_mfma_f32_16x16x32_bf16 v[84:87], v[172:175], v[228:231], v[84:87]
	v_mfma_f32_16x16x32_bf16 v[80:83], v[204:207], v[228:231], v[80:83]
	v_mfma_f32_16x16x32_bf16 v[68:71], v[172:175], v[236:239], v[68:71]
	v_mfma_f32_16x16x32_bf16 v[64:67], v[204:207], v[236:239], v[64:67]
	s_barrier
	s_add_i32 s4, s74, s28
	v_lshl_add_u64 v[180:181], s[34:35], 0, v[144:145]
	s_mov_b32 m0, s4
	ds_read_b128 v[208:211], v155 offset:16384
	ds_read_b128 v[212:215], v155 offset:17408
	ds_read_b128 v[216:219], v155 offset:18432
	ds_read_b128 v[220:223], v155 offset:19456
	ds_read_b128 v[224:227], v155 offset:20480
	ds_read_b128 v[228:231], v155 offset:21504
	ds_read_b128 v[232:235], v155 offset:22528
	ds_read_b128 v[236:239], v155 offset:23552
	global_load_lds_dwordx4 v[180:181], off
	s_add_i32 m0, s4, 0x2000
	s_add_u32 s4, s34, 0x20000
	v_lshl_add_u64 v[202:203], s[34:35], 0, v[132:133]
	s_addc_u32 s5, s35, 0
	s_add_i32 s74, s75, s28
	global_load_lds_dwordx4 v[202:203], off
	v_lshl_add_u64 v[240:241], s[4:5], 0, v[144:145]
	s_mov_b32 m0, s74
	v_lshl_add_u64 v[242:243], s[60:61], 0, v[130:131]
	global_load_lds_dwordx4 v[240:241], off
	v_lshl_add_u64 v[240:241], s[4:5], 0, v[132:133]
	s_add_i32 m0, s74, 0x2000
	s_nop 0
	global_load_lds_dwordx4 v[240:241], off
	v_lshl_add_u64 v[240:241], s[60:61], 0, v[128:129]
	s_mov_b32 m0, s64
	s_nop 0
	global_load_lds_dwordx4 v[240:241], off
	s_mov_b32 m0, s65
	s_nop 0
	global_load_lds_dwordx4 v[242:243], off
	s_waitcnt vmcnt(8)
	s_waitcnt lgkmcnt(0)
	s_barrier
	s_waitcnt lgkmcnt(0)
	v_mfma_f32_16x16x32_bf16 v[60:63], v[138:141], v[208:211], v[60:63]
	v_mfma_f32_16x16x32_bf16 v[56:59], v[160:163], v[208:211], v[56:59]
	v_mfma_f32_16x16x32_bf16 v[44:47], v[138:141], v[216:219], v[44:47]
	v_mfma_f32_16x16x32_bf16 v[40:43], v[160:163], v[216:219], v[40:43]
	v_mfma_f32_16x16x32_bf16 v[28:31], v[138:141], v[224:227], v[28:31]
	v_mfma_f32_16x16x32_bf16 v[24:27], v[160:163], v[224:227], v[24:27]
	v_mfma_f32_16x16x32_bf16 v[12:15], v[138:141], v[232:235], v[12:15]
	v_mfma_f32_16x16x32_bf16 v[8:11], v[160:163], v[232:235], v[8:11]
	v_mfma_f32_16x16x32_bf16 v[60:63], v[156:159], v[212:215], v[60:63]
	v_mfma_f32_16x16x32_bf16 v[56:59], v[164:167], v[212:215], v[56:59]
	v_mfma_f32_16x16x32_bf16 v[44:47], v[156:159], v[220:223], v[44:47]
	v_mfma_f32_16x16x32_bf16 v[40:43], v[164:167], v[220:223], v[40:43]
	v_mfma_f32_16x16x32_bf16 v[28:31], v[156:159], v[228:231], v[28:31]
	v_mfma_f32_16x16x32_bf16 v[24:27], v[164:167], v[228:231], v[24:27]
	v_mfma_f32_16x16x32_bf16 v[12:15], v[156:159], v[236:239], v[12:15]
	v_mfma_f32_16x16x32_bf16 v[8:11], v[164:167], v[236:239], v[8:11]
	v_mfma_f32_16x16x32_bf16 v[52:55], v[168:171], v[208:211], v[52:55]
	v_mfma_f32_16x16x32_bf16 v[48:51], v[176:179], v[208:211], v[48:51]
	v_mfma_f32_16x16x32_bf16 v[36:39], v[168:171], v[216:219], v[36:39]
	v_mfma_f32_16x16x32_bf16 v[32:35], v[176:179], v[216:219], v[32:35]
	v_mfma_f32_16x16x32_bf16 v[20:23], v[168:171], v[224:227], v[20:23]
	v_mfma_f32_16x16x32_bf16 v[16:19], v[176:179], v[224:227], v[16:19]
	v_mfma_f32_16x16x32_bf16 v[4:7], v[168:171], v[232:235], v[4:7]
	v_mfma_f32_16x16x32_bf16 v[0:3], v[176:179], v[232:235], v[0:3]
	v_mfma_f32_16x16x32_bf16 v[52:55], v[172:175], v[212:215], v[52:55]
	v_mfma_f32_16x16x32_bf16 v[48:51], v[204:207], v[212:215], v[48:51]
	v_mfma_f32_16x16x32_bf16 v[36:39], v[172:175], v[220:223], v[36:39]
	v_mfma_f32_16x16x32_bf16 v[32:35], v[204:207], v[220:223], v[32:35]
	v_mfma_f32_16x16x32_bf16 v[20:23], v[172:175], v[228:231], v[20:23]
	v_mfma_f32_16x16x32_bf16 v[16:19], v[204:207], v[228:231], v[16:19]
	v_mfma_f32_16x16x32_bf16 v[4:7], v[172:175], v[236:239], v[4:7]
	v_mfma_f32_16x16x32_bf16 v[0:3], v[204:207], v[236:239], v[0:3]
	s_barrier
	s_add_i32 s74, 0, 0x18000
	s_add_i32 s75, 0, 0x1c000
	v_add_u32_e32 v164, s74, v143
	v_add_u32_e32 v204, s75, v143
	ds_read_b128 v[138:141], v164
	ds_read_b128 v[156:159], v164 offset:1024
	ds_read_b128 v[160:163], v164 offset:2048
	ds_read_b128 v[164:167], v164 offset:3072
	ds_read_b128 v[168:171], v204
	ds_read_b128 v[172:175], v204 offset:1024
	ds_read_b128 v[176:179], v204 offset:2048
	ds_read_b128 v[204:207], v204 offset:3072
	s_add_u32 s4, s60, 0x20000
	s_addc_u32 s5, s61, 0
	s_mov_b32 m0, s66
	v_lshl_add_u64 v[244:245], s[4:5], 0, v[128:129]
	ds_read_b128 v[208:211], v155 offset:32768
	ds_read_b128 v[212:215], v155 offset:33792
	ds_read_b128 v[216:219], v155 offset:34816
	ds_read_b128 v[220:223], v155 offset:35840
	ds_read_b128 v[224:227], v155 offset:36864
	ds_read_b128 v[228:231], v155 offset:37888
	ds_read_b128 v[232:235], v155 offset:38912
	ds_read_b128 v[236:239], v155 offset:39936
	global_load_lds_dwordx4 v[244:245], off
	v_lshl_add_u64 v[244:245], s[4:5], 0, v[130:131]
	s_mov_b32 m0, s67
	s_nop 0
	global_load_lds_dwordx4 v[244:245], off
	s_waitcnt vmcnt(8)
	s_waitcnt lgkmcnt(0)
	s_barrier
	s_waitcnt lgkmcnt(0)
	v_mfma_f32_16x16x32_bf16 v[124:127], v[138:141], v[208:211], v[124:127]
	v_mfma_f32_16x16x32_bf16 v[120:123], v[160:163], v[208:211], v[120:123]
	v_mfma_f32_16x16x32_bf16 v[108:111], v[138:141], v[216:219], v[108:111]
	v_mfma_f32_16x16x32_bf16 v[104:107], v[160:163], v[216:219], v[104:107]
	v_mfma_f32_16x16x32_bf16 v[92:95], v[138:141], v[224:227], v[92:95]
	v_mfma_f32_16x16x32_bf16 v[88:91], v[160:163], v[224:227], v[88:91]
	v_mfma_f32_16x16x32_bf16 v[76:79], v[138:141], v[232:235], v[76:79]
	v_mfma_f32_16x16x32_bf16 v[72:75], v[160:163], v[232:235], v[72:75]
	v_mfma_f32_16x16x32_bf16 v[124:127], v[156:159], v[212:215], v[124:127]
	v_mfma_f32_16x16x32_bf16 v[120:123], v[164:167], v[212:215], v[120:123]
	v_mfma_f32_16x16x32_bf16 v[108:111], v[156:159], v[220:223], v[108:111]
	v_mfma_f32_16x16x32_bf16 v[104:107], v[164:167], v[220:223], v[104:107]
	v_mfma_f32_16x16x32_bf16 v[92:95], v[156:159], v[228:231], v[92:95]
	v_mfma_f32_16x16x32_bf16 v[88:91], v[164:167], v[228:231], v[88:91]
	v_mfma_f32_16x16x32_bf16 v[76:79], v[156:159], v[236:239], v[76:79]
	v_mfma_f32_16x16x32_bf16 v[72:75], v[164:167], v[236:239], v[72:75]
	v_mfma_f32_16x16x32_bf16 v[116:119], v[168:171], v[208:211], v[116:119]
	v_mfma_f32_16x16x32_bf16 v[112:115], v[176:179], v[208:211], v[112:115]
	v_mfma_f32_16x16x32_bf16 v[100:103], v[168:171], v[216:219], v[100:103]
	v_mfma_f32_16x16x32_bf16 v[96:99], v[176:179], v[216:219], v[96:99]
	v_mfma_f32_16x16x32_bf16 v[84:87], v[168:171], v[224:227], v[84:87]
	v_mfma_f32_16x16x32_bf16 v[80:83], v[176:179], v[224:227], v[80:83]
	v_mfma_f32_16x16x32_bf16 v[68:71], v[168:171], v[232:235], v[68:71]
	v_mfma_f32_16x16x32_bf16 v[64:67], v[176:179], v[232:235], v[64:67]
	v_mfma_f32_16x16x32_bf16 v[116:119], v[172:175], v[212:215], v[116:119]
	v_mfma_f32_16x16x32_bf16 v[112:115], v[204:207], v[212:215], v[112:115]
	v_mfma_f32_16x16x32_bf16 v[100:103], v[172:175], v[220:223], v[100:103]
	v_mfma_f32_16x16x32_bf16 v[96:99], v[204:207], v[220:223], v[96:99]
	v_mfma_f32_16x16x32_bf16 v[84:87], v[172:175], v[228:231], v[84:87]
	v_mfma_f32_16x16x32_bf16 v[80:83], v[204:207], v[228:231], v[80:83]
	v_mfma_f32_16x16x32_bf16 v[68:71], v[172:175], v[236:239], v[68:71]
	v_mfma_f32_16x16x32_bf16 v[64:67], v[204:207], v[236:239], v[64:67]
	s_barrier
	s_add_i32 s4, s74, s28
	v_lshl_add_u64 v[180:181], v[180:181], 0, s[26:27]
	s_mov_b32 m0, s4
	ds_read_b128 v[208:211], v155 offset:49152
	ds_read_b128 v[212:215], v155 offset:50176
	ds_read_b128 v[216:219], v155 offset:51200
	ds_read_b128 v[220:223], v155 offset:52224
	ds_read_b128 v[224:227], v155 offset:53248
	ds_read_b128 v[228:231], v155 offset:54272
	ds_read_b128 v[232:235], v155 offset:55296
	ds_read_b128 v[236:239], v155 offset:56320
	global_load_lds_dwordx4 v[180:181], off
	s_add_i32 m0, s4, 0x2000
	s_add_u32 s4, s34, 0x20080
	v_lshl_add_u64 v[180:181], v[202:203], 0, s[26:27]
	s_addc_u32 s5, s35, 0
	s_add_i32 s34, s75, s28
	global_load_lds_dwordx4 v[180:181], off
	v_lshl_add_u64 v[180:181], s[4:5], 0, v[144:145]
	s_mov_b32 m0, s34
	s_nop 0
	global_load_lds_dwordx4 v[180:181], off
	v_lshl_add_u64 v[180:181], s[4:5], 0, v[132:133]
	s_add_i32 m0, s34, 0x2000
	s_nop 0
	global_load_lds_dwordx4 v[180:181], off
	v_lshl_add_u64 v[180:181], v[240:241], 0, s[26:27]
	s_mov_b32 m0, s68
	s_nop 0
	global_load_lds_dwordx4 v[180:181], off
	v_lshl_add_u64 v[180:181], v[242:243], 0, s[26:27]
	s_mov_b32 m0, s69
	s_nop 0
	global_load_lds_dwordx4 v[180:181], off
	s_waitcnt vmcnt(8)
	s_waitcnt lgkmcnt(0)
	s_barrier
	s_waitcnt lgkmcnt(0)
	v_mfma_f32_16x16x32_bf16 v[60:63], v[138:141], v[208:211], v[60:63]
	v_mfma_f32_16x16x32_bf16 v[56:59], v[160:163], v[208:211], v[56:59]
	v_mfma_f32_16x16x32_bf16 v[44:47], v[138:141], v[216:219], v[44:47]
	v_mfma_f32_16x16x32_bf16 v[40:43], v[160:163], v[216:219], v[40:43]
	v_mfma_f32_16x16x32_bf16 v[28:31], v[138:141], v[224:227], v[28:31]
	v_mfma_f32_16x16x32_bf16 v[24:27], v[160:163], v[224:227], v[24:27]
	v_mfma_f32_16x16x32_bf16 v[12:15], v[138:141], v[232:235], v[12:15]
	v_mfma_f32_16x16x32_bf16 v[8:11], v[160:163], v[232:235], v[8:11]
	v_mfma_f32_16x16x32_bf16 v[60:63], v[156:159], v[212:215], v[60:63]
	v_mfma_f32_16x16x32_bf16 v[56:59], v[164:167], v[212:215], v[56:59]
	v_mfma_f32_16x16x32_bf16 v[44:47], v[156:159], v[220:223], v[44:47]
	v_mfma_f32_16x16x32_bf16 v[40:43], v[164:167], v[220:223], v[40:43]
	v_mfma_f32_16x16x32_bf16 v[28:31], v[156:159], v[228:231], v[28:31]
	v_mfma_f32_16x16x32_bf16 v[24:27], v[164:167], v[228:231], v[24:27]
	v_mfma_f32_16x16x32_bf16 v[12:15], v[156:159], v[236:239], v[12:15]
	v_mfma_f32_16x16x32_bf16 v[8:11], v[164:167], v[236:239], v[8:11]
	v_mfma_f32_16x16x32_bf16 v[52:55], v[168:171], v[208:211], v[52:55]
	v_mfma_f32_16x16x32_bf16 v[48:51], v[176:179], v[208:211], v[48:51]
	v_mfma_f32_16x16x32_bf16 v[36:39], v[168:171], v[216:219], v[36:39]
	v_mfma_f32_16x16x32_bf16 v[32:35], v[176:179], v[216:219], v[32:35]
	v_mfma_f32_16x16x32_bf16 v[20:23], v[168:171], v[224:227], v[20:23]
	v_mfma_f32_16x16x32_bf16 v[16:19], v[176:179], v[224:227], v[16:19]
	v_mfma_f32_16x16x32_bf16 v[4:7], v[168:171], v[232:235], v[4:7]
	v_mfma_f32_16x16x32_bf16 v[0:3], v[176:179], v[232:235], v[0:3]
	v_mfma_f32_16x16x32_bf16 v[52:55], v[172:175], v[212:215], v[52:55]
	v_mfma_f32_16x16x32_bf16 v[48:51], v[204:207], v[212:215], v[48:51]
	v_mfma_f32_16x16x32_bf16 v[36:39], v[172:175], v[220:223], v[36:39]
	v_mfma_f32_16x16x32_bf16 v[32:35], v[204:207], v[220:223], v[32:35]
	v_mfma_f32_16x16x32_bf16 v[20:23], v[172:175], v[228:231], v[20:23]
	v_mfma_f32_16x16x32_bf16 v[16:19], v[204:207], v[228:231], v[16:19]
	v_mfma_f32_16x16x32_bf16 v[4:7], v[172:175], v[236:239], v[4:7]
	v_mfma_f32_16x16x32_bf16 v[0:3], v[204:207], v[236:239], v[0:3]
	s_barrier
	s_add_i32 s73, s73, 2
	s_add_u32 s58, s58, 0x100
	s_addc_u32 s59, s59, 0
	s_add_u32 s71, s71, 0x100
	s_addc_u32 s72, s72, 0
	s_cmp_gt_u32 s73, 5
	s_cbranch_scc0 .LBB0_1093
	s_and_b64 vcc, exec, s[46:47]
	s_cbranch_vccz .LBB0_1096
	s_barrier

.LBB0_1117:
	s_add_u32 s4, s54, 0xfffe0080
	s_addc_u32 s5, s55, -1
	s_add_i32 s74, 0, 0x10000
	s_cmp_eq_u32 s73, 4
	s_cselect_b32 s59, s33, s5
	s_cselect_b32 s58, s36, s4
	s_cselect_b32 s35, s47, s72
	s_cselect_b32 s34, s49, s71
	s_add_i32 s75, 0, 0x14000
	v_add_u32_e32 v164, s74, v143
	v_add_u32_e32 v180, s75, v143
	ds_read_b128 v[138:141], v164
	ds_read_b128 v[156:159], v164 offset:1024
	ds_read_b128 v[160:163], v164 offset:2048
	ds_read_b128 v[164:167], v164 offset:3072
	ds_read_b128 v[168:171], v180
	ds_read_b128 v[172:175], v180 offset:1024
	ds_read_b128 v[176:179], v180 offset:2048
	ds_read_b128 v[204:207], v180 offset:3072
	v_lshl_add_u64 v[180:181], s[54:55], 0, v[134:135]
	s_add_i32 m0, s64, 0xc000
	ds_read_b128 v[208:211], v155
	ds_read_b128 v[212:215], v155 offset:1024
	ds_read_b128 v[216:219], v155 offset:2048
	ds_read_b128 v[220:223], v155 offset:3072
	ds_read_b128 v[224:227], v155 offset:4096
	ds_read_b128 v[228:231], v155 offset:5120
	ds_read_b128 v[232:235], v155 offset:6144
	ds_read_b128 v[236:239], v155 offset:7168
	global_load_lds_dwordx4 v[180:181], off
	v_lshl_add_u64 v[180:181], s[54:55], 0, v[136:137]
	s_add_i32 m0, s64, 0xe000
	s_nop 0
	global_load_lds_dwordx4 v[180:181], off
	s_waitcnt vmcnt(8)
	s_waitcnt lgkmcnt(0)
	s_barrier
	s_waitcnt lgkmcnt(0)
	v_mfma_f32_16x16x32_bf16 v[124:127], v[138:141], v[208:211], v[124:127]
	v_mfma_f32_16x16x32_bf16 v[120:123], v[160:163], v[208:211], v[120:123]
	v_mfma_f32_16x16x32_bf16 v[108:111], v[138:141], v[216:219], v[108:111]
	v_mfma_f32_16x16x32_bf16 v[104:107], v[160:163], v[216:219], v[104:107]
	v_mfma_f32_16x16x32_bf16 v[92:95], v[138:141], v[224:227], v[92:95]
	v_mfma_f32_16x16x32_bf16 v[88:91], v[160:163], v[224:227], v[88:91]
	v_mfma_f32_16x16x32_bf16 v[76:79], v[138:141], v[232:235], v[76:79]
	v_mfma_f32_16x16x32_bf16 v[72:75], v[160:163], v[232:235], v[72:75]
	v_mfma_f32_16x16x32_bf16 v[124:127], v[156:159], v[212:215], v[124:127]
	v_mfma_f32_16x16x32_bf16 v[120:123], v[164:167], v[212:215], v[120:123]
	v_mfma_f32_16x16x32_bf16 v[108:111], v[156:159], v[220:223], v[108:111]
	v_mfma_f32_16x16x32_bf16 v[104:107], v[164:167], v[220:223], v[104:107]
	v_mfma_f32_16x16x32_bf16 v[92:95], v[156:159], v[228:231], v[92:95]
	v_mfma_f32_16x16x32_bf16 v[88:91], v[164:167], v[228:231], v[88:91]
	v_mfma_f32_16x16x32_bf16 v[76:79], v[156:159], v[236:239], v[76:79]
	v_mfma_f32_16x16x32_bf16 v[72:75], v[164:167], v[236:239], v[72:75]
	v_mfma_f32_16x16x32_bf16 v[116:119], v[168:171], v[208:211], v[116:119]
	v_mfma_f32_16x16x32_bf16 v[112:115], v[176:179], v[208:211], v[112:115]
	v_mfma_f32_16x16x32_bf16 v[100:103], v[168:171], v[216:219], v[100:103]
	v_mfma_f32_16x16x32_bf16 v[96:99], v[176:179], v[216:219], v[96:99]
	v_mfma_f32_16x16x32_bf16 v[84:87], v[168:171], v[224:227], v[84:87]
	v_mfma_f32_16x16x32_bf16 v[80:83], v[176:179], v[224:227], v[80:83]
	v_mfma_f32_16x16x32_bf16 v[68:71], v[168:171], v[232:235], v[68:71]
	v_mfma_f32_16x16x32_bf16 v[64:67], v[176:179], v[232:235], v[64:67]
	v_mfma_f32_16x16x32_bf16 v[116:119], v[172:175], v[212:215], v[116:119]
	v_mfma_f32_16x16x32_bf16 v[112:115], v[204:207], v[212:215], v[112:115]
	v_mfma_f32_16x16x32_bf16 v[100:103], v[172:175], v[220:223], v[100:103]
	v_mfma_f32_16x16x32_bf16 v[96:99], v[204:207], v[220:223], v[96:99]
	v_mfma_f32_16x16x32_bf16 v[84:87], v[172:175], v[228:231], v[84:87]
	v_mfma_f32_16x16x32_bf16 v[80:83], v[204:207], v[228:231], v[80:83]
	v_mfma_f32_16x16x32_bf16 v[68:71], v[172:175], v[236:239], v[68:71]
	v_mfma_f32_16x16x32_bf16 v[64:67], v[204:207], v[236:239], v[64:67]
	s_barrier
	s_add_i32 s4, s74, s63
	v_lshl_add_u64 v[180:181], s[34:35], 0, v[144:145]
	s_mov_b32 m0, s4
	ds_read_b128 v[208:211], v155 offset:16384
	ds_read_b128 v[212:215], v155 offset:17408
	ds_read_b128 v[216:219], v155 offset:18432
	ds_read_b128 v[220:223], v155 offset:19456
	ds_read_b128 v[224:227], v155 offset:20480
	ds_read_b128 v[228:231], v155 offset:21504
	ds_read_b128 v[232:235], v155 offset:22528
	ds_read_b128 v[236:239], v155 offset:23552
	global_load_lds_dwordx4 v[180:181], off
	s_add_i32 m0, s4, 0x2000
	s_add_u32 s4, s34, 0x20000
	v_lshl_add_u64 v[202:203], s[34:35], 0, v[132:133]
	s_addc_u32 s5, s35, 0
	s_add_i32 s74, s75, s63
	global_load_lds_dwordx4 v[202:203], off
	v_lshl_add_u64 v[240:241], s[4:5], 0, v[144:145]
	s_mov_b32 m0, s74
	v_lshl_add_u64 v[242:243], s[58:59], 0, v[130:131]
	global_load_lds_dwordx4 v[240:241], off
	v_lshl_add_u64 v[240:241], s[4:5], 0, v[132:133]
	s_add_i32 m0, s74, 0x2000
	s_nop 0
	global_load_lds_dwordx4 v[240:241], off
	v_lshl_add_u64 v[240:241], s[58:59], 0, v[128:129]
	s_mov_b32 m0, s64
	s_nop 0
	global_load_lds_dwordx4 v[240:241], off
	s_mov_b32 m0, s65
	s_nop 0
	global_load_lds_dwordx4 v[242:243], off
	s_waitcnt vmcnt(8)
	s_waitcnt lgkmcnt(0)
	s_barrier
	s_waitcnt lgkmcnt(0)
	v_mfma_f32_16x16x32_bf16 v[60:63], v[138:141], v[208:211], v[60:63]
	v_mfma_f32_16x16x32_bf16 v[56:59], v[160:163], v[208:211], v[56:59]
	v_mfma_f32_16x16x32_bf16 v[44:47], v[138:141], v[216:219], v[44:47]
	v_mfma_f32_16x16x32_bf16 v[40:43], v[160:163], v[216:219], v[40:43]
	v_mfma_f32_16x16x32_bf16 v[28:31], v[138:141], v[224:227], v[28:31]
	v_mfma_f32_16x16x32_bf16 v[24:27], v[160:163], v[224:227], v[24:27]
	v_mfma_f32_16x16x32_bf16 v[12:15], v[138:141], v[232:235], v[12:15]
	v_mfma_f32_16x16x32_bf16 v[8:11], v[160:163], v[232:235], v[8:11]
	v_mfma_f32_16x16x32_bf16 v[60:63], v[156:159], v[212:215], v[60:63]
	v_mfma_f32_16x16x32_bf16 v[56:59], v[164:167], v[212:215], v[56:59]
	v_mfma_f32_16x16x32_bf16 v[44:47], v[156:159], v[220:223], v[44:47]
	v_mfma_f32_16x16x32_bf16 v[40:43], v[164:167], v[220:223], v[40:43]
	v_mfma_f32_16x16x32_bf16 v[28:31], v[156:159], v[228:231], v[28:31]
	v_mfma_f32_16x16x32_bf16 v[24:27], v[164:167], v[228:231], v[24:27]
	v_mfma_f32_16x16x32_bf16 v[12:15], v[156:159], v[236:239], v[12:15]
	v_mfma_f32_16x16x32_bf16 v[8:11], v[164:167], v[236:239], v[8:11]
	v_mfma_f32_16x16x32_bf16 v[52:55], v[168:171], v[208:211], v[52:55]
	v_mfma_f32_16x16x32_bf16 v[48:51], v[176:179], v[208:211], v[48:51]
	v_mfma_f32_16x16x32_bf16 v[36:39], v[168:171], v[216:219], v[36:39]
	v_mfma_f32_16x16x32_bf16 v[32:35], v[176:179], v[216:219], v[32:35]
	v_mfma_f32_16x16x32_bf16 v[20:23], v[168:171], v[224:227], v[20:23]
	v_mfma_f32_16x16x32_bf16 v[16:19], v[176:179], v[224:227], v[16:19]
	v_mfma_f32_16x16x32_bf16 v[4:7], v[168:171], v[232:235], v[4:7]
	v_mfma_f32_16x16x32_bf16 v[0:3], v[176:179], v[232:235], v[0:3]
	v_mfma_f32_16x16x32_bf16 v[52:55], v[172:175], v[212:215], v[52:55]
	v_mfma_f32_16x16x32_bf16 v[48:51], v[204:207], v[212:215], v[48:51]
	v_mfma_f32_16x16x32_bf16 v[36:39], v[172:175], v[220:223], v[36:39]
	v_mfma_f32_16x16x32_bf16 v[32:35], v[204:207], v[220:223], v[32:35]
	v_mfma_f32_16x16x32_bf16 v[20:23], v[172:175], v[228:231], v[20:23]
	v_mfma_f32_16x16x32_bf16 v[16:19], v[204:207], v[228:231], v[16:19]
	v_mfma_f32_16x16x32_bf16 v[4:7], v[172:175], v[236:239], v[4:7]
	v_mfma_f32_16x16x32_bf16 v[0:3], v[204:207], v[236:239], v[0:3]
	s_barrier
	s_add_i32 s74, 0, 0x18000
	s_add_i32 s75, 0, 0x1c000
	v_add_u32_e32 v164, s74, v143
	v_add_u32_e32 v204, s75, v143
	ds_read_b128 v[138:141], v164
	ds_read_b128 v[156:159], v164 offset:1024
	ds_read_b128 v[160:163], v164 offset:2048
	ds_read_b128 v[164:167], v164 offset:3072
	ds_read_b128 v[168:171], v204
	ds_read_b128 v[172:175], v204 offset:1024
	ds_read_b128 v[176:179], v204 offset:2048
	ds_read_b128 v[204:207], v204 offset:3072
	s_add_u32 s4, s58, 0x20000
	s_addc_u32 s5, s59, 0
	s_mov_b32 m0, s66
	v_lshl_add_u64 v[244:245], s[4:5], 0, v[128:129]
	ds_read_b128 v[208:211], v155 offset:32768
	ds_read_b128 v[212:215], v155 offset:33792
	ds_read_b128 v[216:219], v155 offset:34816
	ds_read_b128 v[220:223], v155 offset:35840
	ds_read_b128 v[224:227], v155 offset:36864
	ds_read_b128 v[228:231], v155 offset:37888
	ds_read_b128 v[232:235], v155 offset:38912
	ds_read_b128 v[236:239], v155 offset:39936
	global_load_lds_dwordx4 v[244:245], off
	v_lshl_add_u64 v[244:245], s[4:5], 0, v[130:131]
	s_mov_b32 m0, s67
	s_nop 0
	global_load_lds_dwordx4 v[244:245], off
	s_waitcnt vmcnt(8)
	s_waitcnt lgkmcnt(0)
	s_barrier
	s_waitcnt lgkmcnt(0)
	v_mfma_f32_16x16x32_bf16 v[124:127], v[138:141], v[208:211], v[124:127]
	v_mfma_f32_16x16x32_bf16 v[120:123], v[160:163], v[208:211], v[120:123]
	v_mfma_f32_16x16x32_bf16 v[108:111], v[138:141], v[216:219], v[108:111]
	v_mfma_f32_16x16x32_bf16 v[104:107], v[160:163], v[216:219], v[104:107]
	v_mfma_f32_16x16x32_bf16 v[92:95], v[138:141], v[224:227], v[92:95]
	v_mfma_f32_16x16x32_bf16 v[88:91], v[160:163], v[224:227], v[88:91]
	v_mfma_f32_16x16x32_bf16 v[76:79], v[138:141], v[232:235], v[76:79]
	v_mfma_f32_16x16x32_bf16 v[72:75], v[160:163], v[232:235], v[72:75]
	v_mfma_f32_16x16x32_bf16 v[124:127], v[156:159], v[212:215], v[124:127]
	v_mfma_f32_16x16x32_bf16 v[120:123], v[164:167], v[212:215], v[120:123]
	v_mfma_f32_16x16x32_bf16 v[108:111], v[156:159], v[220:223], v[108:111]
	v_mfma_f32_16x16x32_bf16 v[104:107], v[164:167], v[220:223], v[104:107]
	v_mfma_f32_16x16x32_bf16 v[92:95], v[156:159], v[228:231], v[92:95]
	v_mfma_f32_16x16x32_bf16 v[88:91], v[164:167], v[228:231], v[88:91]
	v_mfma_f32_16x16x32_bf16 v[76:79], v[156:159], v[236:239], v[76:79]
	v_mfma_f32_16x16x32_bf16 v[72:75], v[164:167], v[236:239], v[72:75]
	v_mfma_f32_16x16x32_bf16 v[116:119], v[168:171], v[208:211], v[116:119]
	v_mfma_f32_16x16x32_bf16 v[112:115], v[176:179], v[208:211], v[112:115]
	v_mfma_f32_16x16x32_bf16 v[100:103], v[168:171], v[216:219], v[100:103]
	v_mfma_f32_16x16x32_bf16 v[96:99], v[176:179], v[216:219], v[96:99]
	v_mfma_f32_16x16x32_bf16 v[84:87], v[168:171], v[224:227], v[84:87]
	v_mfma_f32_16x16x32_bf16 v[80:83], v[176:179], v[224:227], v[80:83]
	v_mfma_f32_16x16x32_bf16 v[68:71], v[168:171], v[232:235], v[68:71]
	v_mfma_f32_16x16x32_bf16 v[64:67], v[176:179], v[232:235], v[64:67]
	v_mfma_f32_16x16x32_bf16 v[116:119], v[172:175], v[212:215], v[116:119]
	v_mfma_f32_16x16x32_bf16 v[112:115], v[204:207], v[212:215], v[112:115]
	v_mfma_f32_16x16x32_bf16 v[100:103], v[172:175], v[220:223], v[100:103]
	v_mfma_f32_16x16x32_bf16 v[96:99], v[204:207], v[220:223], v[96:99]
	v_mfma_f32_16x16x32_bf16 v[84:87], v[172:175], v[228:231], v[84:87]
	v_mfma_f32_16x16x32_bf16 v[80:83], v[204:207], v[228:231], v[80:83]
	v_mfma_f32_16x16x32_bf16 v[68:71], v[172:175], v[236:239], v[68:71]
	v_mfma_f32_16x16x32_bf16 v[64:67], v[204:207], v[236:239], v[64:67]
	s_barrier
	s_add_i32 s4, s74, s63
	v_lshl_add_u64 v[180:181], v[180:181], 0, s[26:27]
	s_mov_b32 m0, s4
	ds_read_b128 v[208:211], v155 offset:49152
	ds_read_b128 v[212:215], v155 offset:50176
	ds_read_b128 v[216:219], v155 offset:51200
	ds_read_b128 v[220:223], v155 offset:52224
	ds_read_b128 v[224:227], v155 offset:53248
	ds_read_b128 v[228:231], v155 offset:54272
	ds_read_b128 v[232:235], v155 offset:55296
	ds_read_b128 v[236:239], v155 offset:56320
	global_load_lds_dwordx4 v[180:181], off
	s_add_i32 m0, s4, 0x2000
	s_add_u32 s4, s34, 0x20080
	v_lshl_add_u64 v[180:181], v[202:203], 0, s[26:27]
	s_addc_u32 s5, s35, 0
	s_add_i32 s34, s75, s63
	global_load_lds_dwordx4 v[180:181], off
	v_lshl_add_u64 v[180:181], s[4:5], 0, v[144:145]
	s_mov_b32 m0, s34
	s_nop 0
	global_load_lds_dwordx4 v[180:181], off
	v_lshl_add_u64 v[180:181], s[4:5], 0, v[132:133]
	s_add_i32 m0, s34, 0x2000
	s_nop 0
	global_load_lds_dwordx4 v[180:181], off
	v_lshl_add_u64 v[180:181], v[240:241], 0, s[26:27]
	s_mov_b32 m0, s68
	s_nop 0
	global_load_lds_dwordx4 v[180:181], off
	v_lshl_add_u64 v[180:181], v[242:243], 0, s[26:27]
	s_mov_b32 m0, s69
	s_nop 0
	global_load_lds_dwordx4 v[180:181], off
	s_waitcnt vmcnt(8)
	s_waitcnt lgkmcnt(0)
	s_barrier
	s_waitcnt lgkmcnt(0)
	v_mfma_f32_16x16x32_bf16 v[60:63], v[138:141], v[208:211], v[60:63]
	v_mfma_f32_16x16x32_bf16 v[56:59], v[160:163], v[208:211], v[56:59]
	v_mfma_f32_16x16x32_bf16 v[44:47], v[138:141], v[216:219], v[44:47]
	v_mfma_f32_16x16x32_bf16 v[40:43], v[160:163], v[216:219], v[40:43]
	v_mfma_f32_16x16x32_bf16 v[28:31], v[138:141], v[224:227], v[28:31]
	v_mfma_f32_16x16x32_bf16 v[24:27], v[160:163], v[224:227], v[24:27]
	v_mfma_f32_16x16x32_bf16 v[12:15], v[138:141], v[232:235], v[12:15]
	v_mfma_f32_16x16x32_bf16 v[8:11], v[160:163], v[232:235], v[8:11]
	v_mfma_f32_16x16x32_bf16 v[60:63], v[156:159], v[212:215], v[60:63]
	v_mfma_f32_16x16x32_bf16 v[56:59], v[164:167], v[212:215], v[56:59]
	v_mfma_f32_16x16x32_bf16 v[44:47], v[156:159], v[220:223], v[44:47]
	v_mfma_f32_16x16x32_bf16 v[40:43], v[164:167], v[220:223], v[40:43]
	v_mfma_f32_16x16x32_bf16 v[28:31], v[156:159], v[228:231], v[28:31]
	v_mfma_f32_16x16x32_bf16 v[24:27], v[164:167], v[228:231], v[24:27]
	v_mfma_f32_16x16x32_bf16 v[12:15], v[156:159], v[236:239], v[12:15]
	v_mfma_f32_16x16x32_bf16 v[8:11], v[164:167], v[236:239], v[8:11]
	v_mfma_f32_16x16x32_bf16 v[52:55], v[168:171], v[208:211], v[52:55]
	v_mfma_f32_16x16x32_bf16 v[48:51], v[176:179], v[208:211], v[48:51]
	v_mfma_f32_16x16x32_bf16 v[36:39], v[168:171], v[216:219], v[36:39]
	v_mfma_f32_16x16x32_bf16 v[32:35], v[176:179], v[216:219], v[32:35]
	v_mfma_f32_16x16x32_bf16 v[20:23], v[168:171], v[224:227], v[20:23]
	v_mfma_f32_16x16x32_bf16 v[16:19], v[176:179], v[224:227], v[16:19]
	v_mfma_f32_16x16x32_bf16 v[4:7], v[168:171], v[232:235], v[4:7]
	v_mfma_f32_16x16x32_bf16 v[0:3], v[176:179], v[232:235], v[0:3]
	v_mfma_f32_16x16x32_bf16 v[52:55], v[172:175], v[212:215], v[52:55]
	v_mfma_f32_16x16x32_bf16 v[48:51], v[204:207], v[212:215], v[48:51]
	v_mfma_f32_16x16x32_bf16 v[36:39], v[172:175], v[220:223], v[36:39]
	v_mfma_f32_16x16x32_bf16 v[32:35], v[204:207], v[220:223], v[32:35]
	v_mfma_f32_16x16x32_bf16 v[20:23], v[172:175], v[228:231], v[20:23]
	v_mfma_f32_16x16x32_bf16 v[16:19], v[204:207], v[228:231], v[16:19]
	v_mfma_f32_16x16x32_bf16 v[4:7], v[172:175], v[236:239], v[4:7]
	v_mfma_f32_16x16x32_bf16 v[0:3], v[204:207], v[236:239], v[0:3]
	s_barrier
	s_add_i32 s73, s73, 2
	s_add_u32 s54, s54, 0x100
	s_addc_u32 s55, s55, 0
	s_add_u32 s71, s71, 0x100
	s_addc_u32 s72, s72, 0
	s_cmp_gt_u32 s73, 5
	s_cbranch_scc0 .LBB0_1117
	s_and_b64 vcc, exec, s[44:45]
	s_cbranch_vccz .LBB0_1120
	s_barrier

.LBB0_1207:
	s_add_u32 s62, s60, 0x100
	s_addc_u32 s63, s61, 0
	s_add_i32 s4, 0, 0x10000
	s_cmp_eq_u32 s29, 12
	s_cselect_b32 s65, s55, s63
	s_cselect_b32 s64, s54, s62
	v_add_u32_e32 v142, s4, v160
	s_cselect_b32 s35, s59, s28
	s_cselect_b32 s34, s58, s3
	s_add_i32 s45, 0, 0x14000
	ds_read_b128 v[138:141], v142
	ds_read_b128 v[154:157], v142 offset:1024
	ds_read_b128 v[172:175], v142 offset:2048
	ds_read_b128 v[176:179], v142 offset:3072
	v_add_u32_e32 v142, s45, v160
	ds_read_b128 v[204:207], v142
	ds_read_b128 v[208:211], v142 offset:1024
	ds_read_b128 v[212:215], v142 offset:2048
	ds_read_b128 v[216:219], v142 offset:3072
	v_lshl_add_u64 v[142:143], s[60:61], 0, v[134:135]
	s_add_i32 m0, s69, 0xc000
	ds_read_b128 v[220:223], v170
	ds_read_b128 v[224:227], v170 offset:1024
	ds_read_b128 v[228:231], v170 offset:2048
	ds_read_b128 v[232:235], v170 offset:3072
	ds_read_b128 v[236:239], v170 offset:4096
	ds_read_b128 v[240:243], v170 offset:5120
	ds_read_b128 v[244:247], v170 offset:6144
	ds_read_b128 v[248:251], v170 offset:7168
	global_load_lds_dwordx4 v[142:143], off
	v_lshl_add_u64 v[142:143], s[60:61], 0, v[136:137]
	s_add_i32 m0, s69, 0xe000
	s_nop 0
	global_load_lds_dwordx4 v[142:143], off
	s_waitcnt vmcnt(8)
	s_waitcnt lgkmcnt(0)
	s_barrier
	s_waitcnt lgkmcnt(0)
	v_mfma_f32_16x16x32_bf16 v[124:127], v[138:141], v[220:223], v[124:127]
	v_mfma_f32_16x16x32_bf16 v[120:123], v[172:175], v[220:223], v[120:123]
	v_mfma_f32_16x16x32_bf16 v[108:111], v[138:141], v[228:231], v[108:111]
	v_mfma_f32_16x16x32_bf16 v[104:107], v[172:175], v[228:231], v[104:107]
	v_mfma_f32_16x16x32_bf16 v[92:95], v[138:141], v[236:239], v[92:95]
	v_mfma_f32_16x16x32_bf16 v[88:91], v[172:175], v[236:239], v[88:91]
	v_mfma_f32_16x16x32_bf16 v[76:79], v[138:141], v[244:247], v[76:79]
	v_mfma_f32_16x16x32_bf16 v[72:75], v[172:175], v[244:247], v[72:75]
	v_mfma_f32_16x16x32_bf16 v[124:127], v[154:157], v[224:227], v[124:127]
	v_mfma_f32_16x16x32_bf16 v[120:123], v[176:179], v[224:227], v[120:123]
	v_mfma_f32_16x16x32_bf16 v[108:111], v[154:157], v[232:235], v[108:111]
	v_mfma_f32_16x16x32_bf16 v[104:107], v[176:179], v[232:235], v[104:107]
	v_mfma_f32_16x16x32_bf16 v[92:95], v[154:157], v[240:243], v[92:95]
	v_mfma_f32_16x16x32_bf16 v[88:91], v[176:179], v[240:243], v[88:91]
	v_mfma_f32_16x16x32_bf16 v[76:79], v[154:157], v[248:251], v[76:79]
	v_mfma_f32_16x16x32_bf16 v[72:75], v[176:179], v[248:251], v[72:75]
	v_mfma_f32_16x16x32_bf16 v[116:119], v[204:207], v[220:223], v[116:119]
	v_mfma_f32_16x16x32_bf16 v[112:115], v[212:215], v[220:223], v[112:115]
	v_mfma_f32_16x16x32_bf16 v[100:103], v[204:207], v[228:231], v[100:103]
	v_mfma_f32_16x16x32_bf16 v[96:99], v[212:215], v[228:231], v[96:99]
	v_mfma_f32_16x16x32_bf16 v[84:87], v[204:207], v[236:239], v[84:87]
	v_mfma_f32_16x16x32_bf16 v[80:83], v[212:215], v[236:239], v[80:83]
	v_mfma_f32_16x16x32_bf16 v[68:71], v[204:207], v[244:247], v[68:71]
	v_mfma_f32_16x16x32_bf16 v[64:67], v[212:215], v[244:247], v[64:67]
	v_mfma_f32_16x16x32_bf16 v[116:119], v[208:211], v[224:227], v[116:119]
	v_mfma_f32_16x16x32_bf16 v[112:115], v[216:219], v[224:227], v[112:115]
	v_mfma_f32_16x16x32_bf16 v[100:103], v[208:211], v[232:235], v[100:103]
	v_mfma_f32_16x16x32_bf16 v[96:99], v[216:219], v[232:235], v[96:99]
	v_mfma_f32_16x16x32_bf16 v[84:87], v[208:211], v[240:243], v[84:87]
	v_mfma_f32_16x16x32_bf16 v[80:83], v[216:219], v[240:243], v[80:83]
	v_mfma_f32_16x16x32_bf16 v[68:71], v[208:211], v[248:251], v[68:71]
	v_mfma_f32_16x16x32_bf16 v[64:67], v[216:219], v[248:251], v[64:67]
	s_barrier
	s_add_i32 s4, s4, s33
	v_lshl_add_u64 v[142:143], s[34:35], 0, v[128:129]
	s_mov_b32 m0, s4
	ds_read_b128 v[220:223], v170 offset:16384
	ds_read_b128 v[224:227], v170 offset:17408
	ds_read_b128 v[228:231], v170 offset:18432
	ds_read_b128 v[232:235], v170 offset:19456
	ds_read_b128 v[236:239], v170 offset:20480
	ds_read_b128 v[240:243], v170 offset:21504
	ds_read_b128 v[244:247], v170 offset:22528
	ds_read_b128 v[248:251], v170 offset:23552
	global_load_lds_dwordx4 v[142:143], off
	s_add_i32 m0, s4, 0x2000
	s_add_u32 s4, s34, 0x40000
	v_lshl_add_u64 v[158:159], s[34:35], 0, v[130:131]
	s_addc_u32 s5, s35, 0
	s_add_i32 s45, s45, s33
	global_load_lds_dwordx4 v[158:159], off
	v_lshl_add_u64 v[180:181], s[4:5], 0, v[128:129]
	s_mov_b32 m0, s45
	v_lshl_add_u64 v[202:203], s[64:65], 0, v[130:131]
	global_load_lds_dwordx4 v[180:181], off
	v_lshl_add_u64 v[180:181], s[4:5], 0, v[130:131]
	s_add_i32 m0, s45, 0x2000
	s_nop 0
	global_load_lds_dwordx4 v[180:181], off
	v_lshl_add_u64 v[180:181], s[64:65], 0, v[128:129]
	s_mov_b32 m0, s69
	s_nop 0
	global_load_lds_dwordx4 v[180:181], off
	s_mov_b32 m0, s70
	s_nop 0
	global_load_lds_dwordx4 v[202:203], off
	s_waitcnt vmcnt(8)
	s_waitcnt lgkmcnt(0)
	s_barrier
	s_waitcnt lgkmcnt(0)
	v_mfma_f32_16x16x32_bf16 v[60:63], v[138:141], v[220:223], v[60:63]
	v_mfma_f32_16x16x32_bf16 v[56:59], v[172:175], v[220:223], v[56:59]
	v_mfma_f32_16x16x32_bf16 v[44:47], v[138:141], v[228:231], v[44:47]
	v_mfma_f32_16x16x32_bf16 v[40:43], v[172:175], v[228:231], v[40:43]
	v_mfma_f32_16x16x32_bf16 v[28:31], v[138:141], v[236:239], v[28:31]
	v_mfma_f32_16x16x32_bf16 v[24:27], v[172:175], v[236:239], v[24:27]
	v_mfma_f32_16x16x32_bf16 v[12:15], v[138:141], v[244:247], v[12:15]
	v_mfma_f32_16x16x32_bf16 v[8:11], v[172:175], v[244:247], v[8:11]
	v_mfma_f32_16x16x32_bf16 v[60:63], v[154:157], v[224:227], v[60:63]
	v_mfma_f32_16x16x32_bf16 v[56:59], v[176:179], v[224:227], v[56:59]
	v_mfma_f32_16x16x32_bf16 v[44:47], v[154:157], v[232:235], v[44:47]
	v_mfma_f32_16x16x32_bf16 v[40:43], v[176:179], v[232:235], v[40:43]
	v_mfma_f32_16x16x32_bf16 v[28:31], v[154:157], v[240:243], v[28:31]
	v_mfma_f32_16x16x32_bf16 v[24:27], v[176:179], v[240:243], v[24:27]
	v_mfma_f32_16x16x32_bf16 v[12:15], v[154:157], v[248:251], v[12:15]
	v_mfma_f32_16x16x32_bf16 v[8:11], v[176:179], v[248:251], v[8:11]
	v_mfma_f32_16x16x32_bf16 v[52:55], v[204:207], v[220:223], v[52:55]
	v_mfma_f32_16x16x32_bf16 v[48:51], v[212:215], v[220:223], v[48:51]
	v_mfma_f32_16x16x32_bf16 v[36:39], v[204:207], v[228:231], v[36:39]
	v_mfma_f32_16x16x32_bf16 v[32:35], v[212:215], v[228:231], v[32:35]
	v_mfma_f32_16x16x32_bf16 v[20:23], v[204:207], v[236:239], v[20:23]
	v_mfma_f32_16x16x32_bf16 v[16:19], v[212:215], v[236:239], v[16:19]
	v_mfma_f32_16x16x32_bf16 v[4:7], v[204:207], v[244:247], v[4:7]
	v_mfma_f32_16x16x32_bf16 v[0:3], v[212:215], v[244:247], v[0:3]
	v_mfma_f32_16x16x32_bf16 v[52:55], v[208:211], v[224:227], v[52:55]
	v_mfma_f32_16x16x32_bf16 v[48:51], v[216:219], v[224:227], v[48:51]
	v_mfma_f32_16x16x32_bf16 v[36:39], v[208:211], v[232:235], v[36:39]
	v_mfma_f32_16x16x32_bf16 v[32:35], v[216:219], v[232:235], v[32:35]
	v_mfma_f32_16x16x32_bf16 v[20:23], v[208:211], v[240:243], v[20:23]
	v_mfma_f32_16x16x32_bf16 v[16:19], v[216:219], v[240:243], v[16:19]
	v_mfma_f32_16x16x32_bf16 v[4:7], v[208:211], v[248:251], v[4:7]
	v_mfma_f32_16x16x32_bf16 v[0:3], v[216:219], v[248:251], v[0:3]
	s_barrier
	s_add_i32 s45, 0, 0x18000
	v_add_u32_e32 v144, s45, v160
	s_add_i32 s51, 0, 0x1c000
	ds_read_b128 v[138:141], v144
	ds_read_b128 v[154:157], v144 offset:1024
	ds_read_b128 v[172:175], v144 offset:2048
	ds_read_b128 v[176:179], v144 offset:3072
	v_add_u32_e32 v144, s51, v160
	ds_read_b128 v[204:207], v144
	ds_read_b128 v[208:211], v144 offset:1024
	ds_read_b128 v[212:215], v144 offset:2048
	ds_read_b128 v[216:219], v144 offset:3072
	s_add_u32 s4, s64, 0x40000
	s_addc_u32 s5, s65, 0
	s_mov_b32 m0, s71
	v_lshl_add_u64 v[252:253], s[4:5], 0, v[128:129]
	ds_read_b128 v[220:223], v170 offset:32768
	ds_read_b128 v[224:227], v170 offset:33792
	ds_read_b128 v[228:231], v170 offset:34816
	ds_read_b128 v[232:235], v170 offset:35840
	ds_read_b128 v[236:239], v170 offset:36864
	ds_read_b128 v[240:243], v170 offset:37888
	ds_read_b128 v[244:247], v170 offset:38912
	ds_read_b128 v[248:251], v170 offset:39936
	global_load_lds_dwordx4 v[252:253], off
	v_lshl_add_u64 v[252:253], s[4:5], 0, v[130:131]
	s_mov_b32 m0, s72
	s_nop 0
	global_load_lds_dwordx4 v[252:253], off
	s_waitcnt vmcnt(8)
	s_waitcnt lgkmcnt(0)
	s_barrier
	s_waitcnt lgkmcnt(0)
	v_mfma_f32_16x16x32_bf16 v[124:127], v[138:141], v[220:223], v[124:127]
	v_mfma_f32_16x16x32_bf16 v[120:123], v[172:175], v[220:223], v[120:123]
	v_mfma_f32_16x16x32_bf16 v[108:111], v[138:141], v[228:231], v[108:111]
	v_mfma_f32_16x16x32_bf16 v[104:107], v[172:175], v[228:231], v[104:107]
	v_mfma_f32_16x16x32_bf16 v[92:95], v[138:141], v[236:239], v[92:95]
	v_mfma_f32_16x16x32_bf16 v[88:91], v[172:175], v[236:239], v[88:91]
	v_mfma_f32_16x16x32_bf16 v[76:79], v[138:141], v[244:247], v[76:79]
	v_mfma_f32_16x16x32_bf16 v[72:75], v[172:175], v[244:247], v[72:75]
	v_mfma_f32_16x16x32_bf16 v[124:127], v[154:157], v[224:227], v[124:127]
	v_mfma_f32_16x16x32_bf16 v[120:123], v[176:179], v[224:227], v[120:123]
	v_mfma_f32_16x16x32_bf16 v[108:111], v[154:157], v[232:235], v[108:111]
	v_mfma_f32_16x16x32_bf16 v[104:107], v[176:179], v[232:235], v[104:107]
	v_mfma_f32_16x16x32_bf16 v[92:95], v[154:157], v[240:243], v[92:95]
	v_mfma_f32_16x16x32_bf16 v[88:91], v[176:179], v[240:243], v[88:91]
	v_mfma_f32_16x16x32_bf16 v[76:79], v[154:157], v[248:251], v[76:79]
	v_mfma_f32_16x16x32_bf16 v[72:75], v[176:179], v[248:251], v[72:75]
	v_mfma_f32_16x16x32_bf16 v[116:119], v[204:207], v[220:223], v[116:119]
	v_mfma_f32_16x16x32_bf16 v[112:115], v[212:215], v[220:223], v[112:115]
	v_mfma_f32_16x16x32_bf16 v[100:103], v[204:207], v[228:231], v[100:103]
	v_mfma_f32_16x16x32_bf16 v[96:99], v[212:215], v[228:231], v[96:99]
	v_mfma_f32_16x16x32_bf16 v[84:87], v[204:207], v[236:239], v[84:87]
	v_mfma_f32_16x16x32_bf16 v[80:83], v[212:215], v[236:239], v[80:83]
	v_mfma_f32_16x16x32_bf16 v[68:71], v[204:207], v[244:247], v[68:71]
	v_mfma_f32_16x16x32_bf16 v[64:67], v[212:215], v[244:247], v[64:67]
	v_mfma_f32_16x16x32_bf16 v[116:119], v[208:211], v[224:227], v[116:119]
	v_mfma_f32_16x16x32_bf16 v[112:115], v[216:219], v[224:227], v[112:115]
	v_mfma_f32_16x16x32_bf16 v[100:103], v[208:211], v[232:235], v[100:103]
	v_mfma_f32_16x16x32_bf16 v[96:99], v[216:219], v[232:235], v[96:99]
	v_mfma_f32_16x16x32_bf16 v[84:87], v[208:211], v[240:243], v[84:87]
	v_mfma_f32_16x16x32_bf16 v[80:83], v[216:219], v[240:243], v[80:83]
	v_mfma_f32_16x16x32_bf16 v[68:71], v[208:211], v[248:251], v[68:71]
	v_mfma_f32_16x16x32_bf16 v[64:67], v[216:219], v[248:251], v[64:67]
	s_barrier
	s_add_i32 s4, s45, s33
	v_lshl_add_u64 v[142:143], v[142:143], 0, s[26:27]
	s_mov_b32 m0, s4
	ds_read_b128 v[220:223], v170 offset:49152
	ds_read_b128 v[224:227], v170 offset:50176
	ds_read_b128 v[228:231], v170 offset:51200
	ds_read_b128 v[232:235], v170 offset:52224
	ds_read_b128 v[236:239], v170 offset:53248
	ds_read_b128 v[240:243], v170 offset:54272
	ds_read_b128 v[244:247], v170 offset:55296
	ds_read_b128 v[248:251], v170 offset:56320
	global_load_lds_dwordx4 v[142:143], off
	s_add_i32 m0, s4, 0x2000
	s_add_u32 s4, s34, 0x40080
	v_lshl_add_u64 v[142:143], v[158:159], 0, s[26:27]
	s_addc_u32 s5, s35, 0
	s_add_i32 s34, s51, s33
	global_load_lds_dwordx4 v[142:143], off
	v_lshl_add_u64 v[142:143], s[4:5], 0, v[128:129]
	s_mov_b32 m0, s34
	s_nop 0
	global_load_lds_dwordx4 v[142:143], off
	v_lshl_add_u64 v[142:143], s[4:5], 0, v[130:131]
	s_add_i32 m0, s34, 0x2000
	s_nop 0
	global_load_lds_dwordx4 v[142:143], off
	v_lshl_add_u64 v[142:143], v[180:181], 0, s[26:27]
	s_mov_b32 m0, s73
	s_nop 0
	global_load_lds_dwordx4 v[142:143], off
	v_lshl_add_u64 v[142:143], v[202:203], 0, s[26:27]
	s_mov_b32 m0, s74
	s_nop 0
	global_load_lds_dwordx4 v[142:143], off
	s_waitcnt vmcnt(8)
	s_waitcnt lgkmcnt(0)
	s_barrier
	s_waitcnt lgkmcnt(0)
	v_mfma_f32_16x16x32_bf16 v[60:63], v[138:141], v[220:223], v[60:63]
	v_mfma_f32_16x16x32_bf16 v[56:59], v[172:175], v[220:223], v[56:59]
	v_mfma_f32_16x16x32_bf16 v[44:47], v[138:141], v[228:231], v[44:47]
	v_mfma_f32_16x16x32_bf16 v[40:43], v[172:175], v[228:231], v[40:43]
	v_mfma_f32_16x16x32_bf16 v[28:31], v[138:141], v[236:239], v[28:31]
	v_mfma_f32_16x16x32_bf16 v[24:27], v[172:175], v[236:239], v[24:27]
	v_mfma_f32_16x16x32_bf16 v[12:15], v[138:141], v[244:247], v[12:15]
	v_mfma_f32_16x16x32_bf16 v[8:11], v[172:175], v[244:247], v[8:11]
	v_mfma_f32_16x16x32_bf16 v[60:63], v[154:157], v[224:227], v[60:63]
	v_mfma_f32_16x16x32_bf16 v[56:59], v[176:179], v[224:227], v[56:59]
	v_mfma_f32_16x16x32_bf16 v[44:47], v[154:157], v[232:235], v[44:47]
	v_mfma_f32_16x16x32_bf16 v[40:43], v[176:179], v[232:235], v[40:43]
	v_mfma_f32_16x16x32_bf16 v[28:31], v[154:157], v[240:243], v[28:31]
	v_mfma_f32_16x16x32_bf16 v[24:27], v[176:179], v[240:243], v[24:27]
	v_mfma_f32_16x16x32_bf16 v[12:15], v[154:157], v[248:251], v[12:15]
	v_mfma_f32_16x16x32_bf16 v[8:11], v[176:179], v[248:251], v[8:11]
	v_mfma_f32_16x16x32_bf16 v[52:55], v[204:207], v[220:223], v[52:55]
	v_mfma_f32_16x16x32_bf16 v[48:51], v[212:215], v[220:223], v[48:51]
	v_mfma_f32_16x16x32_bf16 v[36:39], v[204:207], v[228:231], v[36:39]
	v_mfma_f32_16x16x32_bf16 v[32:35], v[212:215], v[228:231], v[32:35]
	v_mfma_f32_16x16x32_bf16 v[20:23], v[204:207], v[236:239], v[20:23]
	v_mfma_f32_16x16x32_bf16 v[16:19], v[212:215], v[236:239], v[16:19]
	v_mfma_f32_16x16x32_bf16 v[4:7], v[204:207], v[244:247], v[4:7]
	v_mfma_f32_16x16x32_bf16 v[0:3], v[212:215], v[244:247], v[0:3]
	v_mfma_f32_16x16x32_bf16 v[52:55], v[208:211], v[224:227], v[52:55]
	v_mfma_f32_16x16x32_bf16 v[48:51], v[216:219], v[224:227], v[48:51]
	v_mfma_f32_16x16x32_bf16 v[36:39], v[208:211], v[232:235], v[36:39]
	v_mfma_f32_16x16x32_bf16 v[32:35], v[216:219], v[232:235], v[32:35]
	v_mfma_f32_16x16x32_bf16 v[20:23], v[208:211], v[240:243], v[20:23]
	v_mfma_f32_16x16x32_bf16 v[16:19], v[216:219], v[240:243], v[16:19]
	v_mfma_f32_16x16x32_bf16 v[4:7], v[208:211], v[248:251], v[4:7]
	v_mfma_f32_16x16x32_bf16 v[0:3], v[216:219], v[248:251], v[0:3]
	s_barrier
	s_add_i32 s29, s29, 2
	s_add_u32 s3, s3, 0x100
	s_addc_u32 s28, s28, 0
	s_cmp_gt_u32 s29, 13
	s_mov_b64 s[60:61], s[62:63]
	s_cbranch_scc0 .LBB0_1207
	s_and_b64 vcc, exec, s[48:49]
	s_cbranch_vccz .LBB0_1210
	s_barrier

.LBB0_1305:
	s_add_u32 s4, s2, 0xfffc0080
	s_addc_u32 s5, s3, -1
	s_add_i32 s74, 0, 0x10000
	s_cmp_eq_u32 s73, 12
	s_cselect_b32 s61, s36, s5
	s_cselect_b32 s60, s51, s4
	s_cselect_b32 s35, s49, s72
	s_cselect_b32 s34, s70, s71
	s_add_i32 s75, 0, 0x14000
	v_add_u32_e32 v164, s74, v143
	v_add_u32_e32 v180, s75, v143
	ds_read_b128 v[138:141], v164
	ds_read_b128 v[156:159], v164 offset:1024
	ds_read_b128 v[160:163], v164 offset:2048
	ds_read_b128 v[164:167], v164 offset:3072
	ds_read_b128 v[168:171], v180
	ds_read_b128 v[172:175], v180 offset:1024
	ds_read_b128 v[176:179], v180 offset:2048
	ds_read_b128 v[204:207], v180 offset:3072
	v_lshl_add_u64 v[180:181], s[2:3], 0, v[134:135]
	s_add_i32 m0, s59, 0xc000
	ds_read_b128 v[208:211], v155
	ds_read_b128 v[212:215], v155 offset:1024
	ds_read_b128 v[216:219], v155 offset:2048
	ds_read_b128 v[220:223], v155 offset:3072
	ds_read_b128 v[224:227], v155 offset:4096
	ds_read_b128 v[228:231], v155 offset:5120
	ds_read_b128 v[232:235], v155 offset:6144
	ds_read_b128 v[236:239], v155 offset:7168
	global_load_lds_dwordx4 v[180:181], off
	v_lshl_add_u64 v[180:181], s[2:3], 0, v[136:137]
	s_add_i32 m0, s59, 0xe000
	s_nop 0
	global_load_lds_dwordx4 v[180:181], off
	s_waitcnt vmcnt(8)
	s_waitcnt lgkmcnt(0)
	s_barrier
	s_waitcnt lgkmcnt(0)
	v_mfma_f32_16x16x32_bf16 v[124:127], v[138:141], v[208:211], v[124:127]
	v_mfma_f32_16x16x32_bf16 v[120:123], v[160:163], v[208:211], v[120:123]
	v_mfma_f32_16x16x32_bf16 v[108:111], v[138:141], v[216:219], v[108:111]
	v_mfma_f32_16x16x32_bf16 v[104:107], v[160:163], v[216:219], v[104:107]
	v_mfma_f32_16x16x32_bf16 v[92:95], v[138:141], v[224:227], v[92:95]
	v_mfma_f32_16x16x32_bf16 v[88:91], v[160:163], v[224:227], v[88:91]
	v_mfma_f32_16x16x32_bf16 v[76:79], v[138:141], v[232:235], v[76:79]
	v_mfma_f32_16x16x32_bf16 v[72:75], v[160:163], v[232:235], v[72:75]
	v_mfma_f32_16x16x32_bf16 v[124:127], v[156:159], v[212:215], v[124:127]
	v_mfma_f32_16x16x32_bf16 v[120:123], v[164:167], v[212:215], v[120:123]
	v_mfma_f32_16x16x32_bf16 v[108:111], v[156:159], v[220:223], v[108:111]
	v_mfma_f32_16x16x32_bf16 v[104:107], v[164:167], v[220:223], v[104:107]
	v_mfma_f32_16x16x32_bf16 v[92:95], v[156:159], v[228:231], v[92:95]
	v_mfma_f32_16x16x32_bf16 v[88:91], v[164:167], v[228:231], v[88:91]
	v_mfma_f32_16x16x32_bf16 v[76:79], v[156:159], v[236:239], v[76:79]
	v_mfma_f32_16x16x32_bf16 v[72:75], v[164:167], v[236:239], v[72:75]
	v_mfma_f32_16x16x32_bf16 v[116:119], v[168:171], v[208:211], v[116:119]
	v_mfma_f32_16x16x32_bf16 v[112:115], v[176:179], v[208:211], v[112:115]
	v_mfma_f32_16x16x32_bf16 v[100:103], v[168:171], v[216:219], v[100:103]
	v_mfma_f32_16x16x32_bf16 v[96:99], v[176:179], v[216:219], v[96:99]
	v_mfma_f32_16x16x32_bf16 v[84:87], v[168:171], v[224:227], v[84:87]
	v_mfma_f32_16x16x32_bf16 v[80:83], v[176:179], v[224:227], v[80:83]
	v_mfma_f32_16x16x32_bf16 v[68:71], v[168:171], v[232:235], v[68:71]
	v_mfma_f32_16x16x32_bf16 v[64:67], v[176:179], v[232:235], v[64:67]
	v_mfma_f32_16x16x32_bf16 v[116:119], v[172:175], v[212:215], v[116:119]
	v_mfma_f32_16x16x32_bf16 v[112:115], v[204:207], v[212:215], v[112:115]
	v_mfma_f32_16x16x32_bf16 v[100:103], v[172:175], v[220:223], v[100:103]
	v_mfma_f32_16x16x32_bf16 v[96:99], v[204:207], v[220:223], v[96:99]
	v_mfma_f32_16x16x32_bf16 v[84:87], v[172:175], v[228:231], v[84:87]
	v_mfma_f32_16x16x32_bf16 v[80:83], v[204:207], v[228:231], v[80:83]
	v_mfma_f32_16x16x32_bf16 v[68:71], v[172:175], v[236:239], v[68:71]
	v_mfma_f32_16x16x32_bf16 v[64:67], v[204:207], v[236:239], v[64:67]
	s_barrier
	s_add_i32 s4, s74, s1
	v_lshl_add_u64 v[180:181], s[34:35], 0, v[144:145]
	s_mov_b32 m0, s4
	ds_read_b128 v[208:211], v155 offset:16384
	ds_read_b128 v[212:215], v155 offset:17408
	ds_read_b128 v[216:219], v155 offset:18432
	ds_read_b128 v[220:223], v155 offset:19456
	ds_read_b128 v[224:227], v155 offset:20480
	ds_read_b128 v[228:231], v155 offset:21504
	ds_read_b128 v[232:235], v155 offset:22528
	ds_read_b128 v[236:239], v155 offset:23552
	global_load_lds_dwordx4 v[180:181], off
	s_add_i32 m0, s4, 0x2000
	s_add_u32 s4, s34, 0x40000
	v_lshl_add_u64 v[202:203], s[34:35], 0, v[128:129]
	s_addc_u32 s5, s35, 0
	s_add_i32 s74, s75, s1
	global_load_lds_dwordx4 v[202:203], off
	v_lshl_add_u64 v[240:241], s[4:5], 0, v[144:145]
	s_mov_b32 m0, s74
	v_lshl_add_u64 v[242:243], s[60:61], 0, v[130:131]
	global_load_lds_dwordx4 v[240:241], off
	v_lshl_add_u64 v[240:241], s[4:5], 0, v[128:129]
	s_add_i32 m0, s74, 0x2000
	s_nop 0
	global_load_lds_dwordx4 v[240:241], off
	v_lshl_add_u64 v[240:241], s[60:61], 0, v[132:133]
	s_mov_b32 m0, s59
	s_nop 0
	global_load_lds_dwordx4 v[240:241], off
	s_mov_b32 m0, s64
	s_nop 0
	global_load_lds_dwordx4 v[242:243], off
	s_waitcnt vmcnt(8)
	s_waitcnt lgkmcnt(0)
	s_barrier
	s_waitcnt lgkmcnt(0)
	v_mfma_f32_16x16x32_bf16 v[60:63], v[138:141], v[208:211], v[60:63]
	v_mfma_f32_16x16x32_bf16 v[56:59], v[160:163], v[208:211], v[56:59]
	v_mfma_f32_16x16x32_bf16 v[44:47], v[138:141], v[216:219], v[44:47]
	v_mfma_f32_16x16x32_bf16 v[40:43], v[160:163], v[216:219], v[40:43]
	v_mfma_f32_16x16x32_bf16 v[28:31], v[138:141], v[224:227], v[28:31]
	v_mfma_f32_16x16x32_bf16 v[24:27], v[160:163], v[224:227], v[24:27]
	v_mfma_f32_16x16x32_bf16 v[12:15], v[138:141], v[232:235], v[12:15]
	v_mfma_f32_16x16x32_bf16 v[8:11], v[160:163], v[232:235], v[8:11]
	v_mfma_f32_16x16x32_bf16 v[60:63], v[156:159], v[212:215], v[60:63]
	v_mfma_f32_16x16x32_bf16 v[56:59], v[164:167], v[212:215], v[56:59]
	v_mfma_f32_16x16x32_bf16 v[44:47], v[156:159], v[220:223], v[44:47]
	v_mfma_f32_16x16x32_bf16 v[40:43], v[164:167], v[220:223], v[40:43]
	v_mfma_f32_16x16x32_bf16 v[28:31], v[156:159], v[228:231], v[28:31]
	v_mfma_f32_16x16x32_bf16 v[24:27], v[164:167], v[228:231], v[24:27]
	v_mfma_f32_16x16x32_bf16 v[12:15], v[156:159], v[236:239], v[12:15]
	v_mfma_f32_16x16x32_bf16 v[8:11], v[164:167], v[236:239], v[8:11]
	v_mfma_f32_16x16x32_bf16 v[52:55], v[168:171], v[208:211], v[52:55]
	v_mfma_f32_16x16x32_bf16 v[48:51], v[176:179], v[208:211], v[48:51]
	v_mfma_f32_16x16x32_bf16 v[36:39], v[168:171], v[216:219], v[36:39]
	v_mfma_f32_16x16x32_bf16 v[32:35], v[176:179], v[216:219], v[32:35]
	v_mfma_f32_16x16x32_bf16 v[20:23], v[168:171], v[224:227], v[20:23]
	v_mfma_f32_16x16x32_bf16 v[16:19], v[176:179], v[224:227], v[16:19]
	v_mfma_f32_16x16x32_bf16 v[4:7], v[168:171], v[232:235], v[4:7]
	v_mfma_f32_16x16x32_bf16 v[0:3], v[176:179], v[232:235], v[0:3]
	v_mfma_f32_16x16x32_bf16 v[52:55], v[172:175], v[212:215], v[52:55]
	v_mfma_f32_16x16x32_bf16 v[48:51], v[204:207], v[212:215], v[48:51]
	v_mfma_f32_16x16x32_bf16 v[36:39], v[172:175], v[220:223], v[36:39]
	v_mfma_f32_16x16x32_bf16 v[32:35], v[204:207], v[220:223], v[32:35]
	v_mfma_f32_16x16x32_bf16 v[20:23], v[172:175], v[228:231], v[20:23]
	v_mfma_f32_16x16x32_bf16 v[16:19], v[204:207], v[228:231], v[16:19]
	v_mfma_f32_16x16x32_bf16 v[4:7], v[172:175], v[236:239], v[4:7]
	v_mfma_f32_16x16x32_bf16 v[0:3], v[204:207], v[236:239], v[0:3]
	s_barrier
	s_add_i32 s74, 0, 0x18000
	s_add_i32 s75, 0, 0x1c000
	v_add_u32_e32 v164, s74, v143
	v_add_u32_e32 v204, s75, v143
	ds_read_b128 v[138:141], v164
	ds_read_b128 v[156:159], v164 offset:1024
	ds_read_b128 v[160:163], v164 offset:2048
	ds_read_b128 v[164:167], v164 offset:3072
	ds_read_b128 v[168:171], v204
	ds_read_b128 v[172:175], v204 offset:1024
	ds_read_b128 v[176:179], v204 offset:2048
	ds_read_b128 v[204:207], v204 offset:3072
	s_add_u32 s4, s60, 0x40000
	s_addc_u32 s5, s61, 0
	s_mov_b32 m0, s65
	v_lshl_add_u64 v[244:245], s[4:5], 0, v[132:133]
	ds_read_b128 v[208:211], v155 offset:32768
	ds_read_b128 v[212:215], v155 offset:33792
	ds_read_b128 v[216:219], v155 offset:34816
	ds_read_b128 v[220:223], v155 offset:35840
	ds_read_b128 v[224:227], v155 offset:36864
	ds_read_b128 v[228:231], v155 offset:37888
	ds_read_b128 v[232:235], v155 offset:38912
	ds_read_b128 v[236:239], v155 offset:39936
	global_load_lds_dwordx4 v[244:245], off
	v_lshl_add_u64 v[244:245], s[4:5], 0, v[130:131]
	s_mov_b32 m0, s66
	s_nop 0
	global_load_lds_dwordx4 v[244:245], off
	s_waitcnt vmcnt(8)
	s_waitcnt lgkmcnt(0)
	s_barrier
	s_waitcnt lgkmcnt(0)
	v_mfma_f32_16x16x32_bf16 v[124:127], v[138:141], v[208:211], v[124:127]
	v_mfma_f32_16x16x32_bf16 v[120:123], v[160:163], v[208:211], v[120:123]
	v_mfma_f32_16x16x32_bf16 v[108:111], v[138:141], v[216:219], v[108:111]
	v_mfma_f32_16x16x32_bf16 v[104:107], v[160:163], v[216:219], v[104:107]
	v_mfma_f32_16x16x32_bf16 v[92:95], v[138:141], v[224:227], v[92:95]
	v_mfma_f32_16x16x32_bf16 v[88:91], v[160:163], v[224:227], v[88:91]
	v_mfma_f32_16x16x32_bf16 v[76:79], v[138:141], v[232:235], v[76:79]
	v_mfma_f32_16x16x32_bf16 v[72:75], v[160:163], v[232:235], v[72:75]
	v_mfma_f32_16x16x32_bf16 v[124:127], v[156:159], v[212:215], v[124:127]
	v_mfma_f32_16x16x32_bf16 v[120:123], v[164:167], v[212:215], v[120:123]
	v_mfma_f32_16x16x32_bf16 v[108:111], v[156:159], v[220:223], v[108:111]
	v_mfma_f32_16x16x32_bf16 v[104:107], v[164:167], v[220:223], v[104:107]
	v_mfma_f32_16x16x32_bf16 v[92:95], v[156:159], v[228:231], v[92:95]
	v_mfma_f32_16x16x32_bf16 v[88:91], v[164:167], v[228:231], v[88:91]
	v_mfma_f32_16x16x32_bf16 v[76:79], v[156:159], v[236:239], v[76:79]
	v_mfma_f32_16x16x32_bf16 v[72:75], v[164:167], v[236:239], v[72:75]
	v_mfma_f32_16x16x32_bf16 v[116:119], v[168:171], v[208:211], v[116:119]
	v_mfma_f32_16x16x32_bf16 v[112:115], v[176:179], v[208:211], v[112:115]
	v_mfma_f32_16x16x32_bf16 v[100:103], v[168:171], v[216:219], v[100:103]
	v_mfma_f32_16x16x32_bf16 v[96:99], v[176:179], v[216:219], v[96:99]
	v_mfma_f32_16x16x32_bf16 v[84:87], v[168:171], v[224:227], v[84:87]
	v_mfma_f32_16x16x32_bf16 v[80:83], v[176:179], v[224:227], v[80:83]
	v_mfma_f32_16x16x32_bf16 v[68:71], v[168:171], v[232:235], v[68:71]
	v_mfma_f32_16x16x32_bf16 v[64:67], v[176:179], v[232:235], v[64:67]
	v_mfma_f32_16x16x32_bf16 v[116:119], v[172:175], v[212:215], v[116:119]
	v_mfma_f32_16x16x32_bf16 v[112:115], v[204:207], v[212:215], v[112:115]
	v_mfma_f32_16x16x32_bf16 v[100:103], v[172:175], v[220:223], v[100:103]
	v_mfma_f32_16x16x32_bf16 v[96:99], v[204:207], v[220:223], v[96:99]
	v_mfma_f32_16x16x32_bf16 v[84:87], v[172:175], v[228:231], v[84:87]
	v_mfma_f32_16x16x32_bf16 v[80:83], v[204:207], v[228:231], v[80:83]
	v_mfma_f32_16x16x32_bf16 v[68:71], v[172:175], v[236:239], v[68:71]
	v_mfma_f32_16x16x32_bf16 v[64:67], v[204:207], v[236:239], v[64:67]
	s_barrier
	s_add_i32 s4, s74, s1
	v_lshl_add_u64 v[180:181], v[180:181], 0, s[26:27]
	s_mov_b32 m0, s4
	ds_read_b128 v[208:211], v155 offset:49152
	ds_read_b128 v[212:215], v155 offset:50176
	ds_read_b128 v[216:219], v155 offset:51200
	ds_read_b128 v[220:223], v155 offset:52224
	ds_read_b128 v[224:227], v155 offset:53248
	ds_read_b128 v[228:231], v155 offset:54272
	ds_read_b128 v[232:235], v155 offset:55296
	ds_read_b128 v[236:239], v155 offset:56320
	global_load_lds_dwordx4 v[180:181], off
	s_add_i32 m0, s4, 0x2000
	s_add_u32 s4, s34, 0x40080
	v_lshl_add_u64 v[180:181], v[202:203], 0, s[26:27]
	s_addc_u32 s5, s35, 0
	s_add_i32 s34, s75, s1
	global_load_lds_dwordx4 v[180:181], off
	v_lshl_add_u64 v[180:181], s[4:5], 0, v[144:145]
	s_mov_b32 m0, s34
	s_nop 0
	global_load_lds_dwordx4 v[180:181], off
	v_lshl_add_u64 v[180:181], s[4:5], 0, v[128:129]
	s_add_i32 m0, s34, 0x2000
	s_nop 0
	global_load_lds_dwordx4 v[180:181], off
	v_lshl_add_u64 v[180:181], v[240:241], 0, s[26:27]
	s_mov_b32 m0, s67
	s_nop 0
	global_load_lds_dwordx4 v[180:181], off
	v_lshl_add_u64 v[180:181], v[242:243], 0, s[26:27]
	s_mov_b32 m0, s68
	s_nop 0
	global_load_lds_dwordx4 v[180:181], off
	s_waitcnt vmcnt(8)
	s_waitcnt lgkmcnt(0)
	s_barrier
	s_waitcnt lgkmcnt(0)
	v_mfma_f32_16x16x32_bf16 v[60:63], v[138:141], v[208:211], v[60:63]
	v_mfma_f32_16x16x32_bf16 v[56:59], v[160:163], v[208:211], v[56:59]
	v_mfma_f32_16x16x32_bf16 v[44:47], v[138:141], v[216:219], v[44:47]
	v_mfma_f32_16x16x32_bf16 v[40:43], v[160:163], v[216:219], v[40:43]
	v_mfma_f32_16x16x32_bf16 v[28:31], v[138:141], v[224:227], v[28:31]
	v_mfma_f32_16x16x32_bf16 v[24:27], v[160:163], v[224:227], v[24:27]
	v_mfma_f32_16x16x32_bf16 v[12:15], v[138:141], v[232:235], v[12:15]
	v_mfma_f32_16x16x32_bf16 v[8:11], v[160:163], v[232:235], v[8:11]
	v_mfma_f32_16x16x32_bf16 v[60:63], v[156:159], v[212:215], v[60:63]
	v_mfma_f32_16x16x32_bf16 v[56:59], v[164:167], v[212:215], v[56:59]
	v_mfma_f32_16x16x32_bf16 v[44:47], v[156:159], v[220:223], v[44:47]
	v_mfma_f32_16x16x32_bf16 v[40:43], v[164:167], v[220:223], v[40:43]
	v_mfma_f32_16x16x32_bf16 v[28:31], v[156:159], v[228:231], v[28:31]
	v_mfma_f32_16x16x32_bf16 v[24:27], v[164:167], v[228:231], v[24:27]
	v_mfma_f32_16x16x32_bf16 v[12:15], v[156:159], v[236:239], v[12:15]
	v_mfma_f32_16x16x32_bf16 v[8:11], v[164:167], v[236:239], v[8:11]
	v_mfma_f32_16x16x32_bf16 v[52:55], v[168:171], v[208:211], v[52:55]
	v_mfma_f32_16x16x32_bf16 v[48:51], v[176:179], v[208:211], v[48:51]
	v_mfma_f32_16x16x32_bf16 v[36:39], v[168:171], v[216:219], v[36:39]
	v_mfma_f32_16x16x32_bf16 v[32:35], v[176:179], v[216:219], v[32:35]
	v_mfma_f32_16x16x32_bf16 v[20:23], v[168:171], v[224:227], v[20:23]
	v_mfma_f32_16x16x32_bf16 v[16:19], v[176:179], v[224:227], v[16:19]
	v_mfma_f32_16x16x32_bf16 v[4:7], v[168:171], v[232:235], v[4:7]
	v_mfma_f32_16x16x32_bf16 v[0:3], v[176:179], v[232:235], v[0:3]
	v_mfma_f32_16x16x32_bf16 v[52:55], v[172:175], v[212:215], v[52:55]
	v_mfma_f32_16x16x32_bf16 v[48:51], v[204:207], v[212:215], v[48:51]
	v_mfma_f32_16x16x32_bf16 v[36:39], v[172:175], v[220:223], v[36:39]
	v_mfma_f32_16x16x32_bf16 v[32:35], v[204:207], v[220:223], v[32:35]
	v_mfma_f32_16x16x32_bf16 v[20:23], v[172:175], v[228:231], v[20:23]
	v_mfma_f32_16x16x32_bf16 v[16:19], v[204:207], v[228:231], v[16:19]
	v_mfma_f32_16x16x32_bf16 v[4:7], v[172:175], v[236:239], v[4:7]
	v_mfma_f32_16x16x32_bf16 v[0:3], v[204:207], v[236:239], v[0:3]
	s_barrier
	s_add_i32 s73, s73, 2
	s_add_u32 s2, s2, 0x100
	s_addc_u32 s3, s3, 0
	s_add_u32 s71, s71, 0x100
	s_addc_u32 s72, s72, 0
	s_cmp_gt_u32 s73, 13
	s_cbranch_scc0 .LBB0_1305
	v_lshl_add_u32 v140, s58, 8, v142
	v_ashrrev_i32_e32 v141, 31, v140
	v_lshl_add_u64 v[156:157], v[140:141], 4, s[44:45]
	global_load_dwordx4 v[208:211], v[156:157], off
	global_load_dwordx4 v[212:215], v[156:157], off offset:256
	global_load_dwordx4 v[216:219], v[156:157], off offset:512
	global_load_dwordx4 v[220:223], v[156:157], off offset:768
	global_load_dwordx4 v[224:227], v[156:157], off offset:2048
	global_load_dwordx4 v[228:231], v[156:157], off offset:2304
	global_load_dwordx4 v[232:235], v[156:157], off offset:2560
	global_load_dwordx4 v[236:239], v[156:157], off offset:2816
	s_and_b64 vcc, exec, s[46:47]
	s_cbranch_vccz .LBB0_1308
	s_barrier

.LBB0_1399:
	s_add_u32 s58, s54, 0x100
	s_addc_u32 s59, s55, 0
	s_add_i32 s4, 0, 0x10000
	s_cmp_eq_u32 s29, 40
	s_cselect_b32 s61, s45, s59
	s_cselect_b32 s60, s44, s58
	v_add_u32_e32 v142, s4, v160
	s_cselect_b32 s35, s53, s28
	s_cselect_b32 s34, s52, s3
	s_add_i32 s47, 0, 0x14000
	ds_read_b128 v[138:141], v142
	ds_read_b128 v[154:157], v142 offset:1024
	ds_read_b128 v[172:175], v142 offset:2048
	ds_read_b128 v[176:179], v142 offset:3072
	v_add_u32_e32 v142, s47, v160
	ds_read_b128 v[204:207], v142
	ds_read_b128 v[208:211], v142 offset:1024
	ds_read_b128 v[212:215], v142 offset:2048
	ds_read_b128 v[216:219], v142 offset:3072
	v_lshl_add_u64 v[142:143], s[54:55], 0, v[134:135]
	s_add_i32 m0, s65, 0xc000
	ds_read_b128 v[220:223], v170
	ds_read_b128 v[224:227], v170 offset:1024
	ds_read_b128 v[228:231], v170 offset:2048
	ds_read_b128 v[232:235], v170 offset:3072
	ds_read_b128 v[236:239], v170 offset:4096
	ds_read_b128 v[240:243], v170 offset:5120
	ds_read_b128 v[244:247], v170 offset:6144
	ds_read_b128 v[248:251], v170 offset:7168
	global_load_lds_dwordx4 v[142:143], off
	v_lshl_add_u64 v[142:143], s[54:55], 0, v[136:137]
	s_add_i32 m0, s65, 0xe000
	s_nop 0
	global_load_lds_dwordx4 v[142:143], off
	s_waitcnt vmcnt(8)
	s_waitcnt lgkmcnt(0)
	s_barrier
	s_waitcnt lgkmcnt(0)
	v_mfma_f32_16x16x32_bf16 v[124:127], v[138:141], v[220:223], v[124:127]
	v_mfma_f32_16x16x32_bf16 v[120:123], v[172:175], v[220:223], v[120:123]
	v_mfma_f32_16x16x32_bf16 v[108:111], v[138:141], v[228:231], v[108:111]
	v_mfma_f32_16x16x32_bf16 v[104:107], v[172:175], v[228:231], v[104:107]
	v_mfma_f32_16x16x32_bf16 v[92:95], v[138:141], v[236:239], v[92:95]
	v_mfma_f32_16x16x32_bf16 v[88:91], v[172:175], v[236:239], v[88:91]
	v_mfma_f32_16x16x32_bf16 v[76:79], v[138:141], v[244:247], v[76:79]
	v_mfma_f32_16x16x32_bf16 v[72:75], v[172:175], v[244:247], v[72:75]
	v_mfma_f32_16x16x32_bf16 v[124:127], v[154:157], v[224:227], v[124:127]
	v_mfma_f32_16x16x32_bf16 v[120:123], v[176:179], v[224:227], v[120:123]
	v_mfma_f32_16x16x32_bf16 v[108:111], v[154:157], v[232:235], v[108:111]
	v_mfma_f32_16x16x32_bf16 v[104:107], v[176:179], v[232:235], v[104:107]
	v_mfma_f32_16x16x32_bf16 v[92:95], v[154:157], v[240:243], v[92:95]
	v_mfma_f32_16x16x32_bf16 v[88:91], v[176:179], v[240:243], v[88:91]
	v_mfma_f32_16x16x32_bf16 v[76:79], v[154:157], v[248:251], v[76:79]
	v_mfma_f32_16x16x32_bf16 v[72:75], v[176:179], v[248:251], v[72:75]
	v_mfma_f32_16x16x32_bf16 v[116:119], v[204:207], v[220:223], v[116:119]
	v_mfma_f32_16x16x32_bf16 v[112:115], v[212:215], v[220:223], v[112:115]
	v_mfma_f32_16x16x32_bf16 v[100:103], v[204:207], v[228:231], v[100:103]
	v_mfma_f32_16x16x32_bf16 v[96:99], v[212:215], v[228:231], v[96:99]
	v_mfma_f32_16x16x32_bf16 v[84:87], v[204:207], v[236:239], v[84:87]
	v_mfma_f32_16x16x32_bf16 v[80:83], v[212:215], v[236:239], v[80:83]
	v_mfma_f32_16x16x32_bf16 v[68:71], v[204:207], v[244:247], v[68:71]
	v_mfma_f32_16x16x32_bf16 v[64:67], v[212:215], v[244:247], v[64:67]
	v_mfma_f32_16x16x32_bf16 v[116:119], v[208:211], v[224:227], v[116:119]
	v_mfma_f32_16x16x32_bf16 v[112:115], v[216:219], v[224:227], v[112:115]
	v_mfma_f32_16x16x32_bf16 v[100:103], v[208:211], v[232:235], v[100:103]
	v_mfma_f32_16x16x32_bf16 v[96:99], v[216:219], v[232:235], v[96:99]
	v_mfma_f32_16x16x32_bf16 v[84:87], v[208:211], v[240:243], v[84:87]
	v_mfma_f32_16x16x32_bf16 v[80:83], v[216:219], v[240:243], v[80:83]
	v_mfma_f32_16x16x32_bf16 v[68:71], v[208:211], v[248:251], v[68:71]
	v_mfma_f32_16x16x32_bf16 v[64:67], v[216:219], v[248:251], v[64:67]
	s_barrier
	s_add_i32 s4, s4, s33
	v_lshl_add_u64 v[142:143], s[34:35], 0, v[128:129]
	s_mov_b32 m0, s4
	ds_read_b128 v[220:223], v170 offset:16384
	ds_read_b128 v[224:227], v170 offset:17408
	ds_read_b128 v[228:231], v170 offset:18432
	ds_read_b128 v[232:235], v170 offset:19456
	ds_read_b128 v[236:239], v170 offset:20480
	ds_read_b128 v[240:243], v170 offset:21504
	ds_read_b128 v[244:247], v170 offset:22528
	ds_read_b128 v[248:251], v170 offset:23552
	global_load_lds_dwordx4 v[142:143], off
	s_add_i32 m0, s4, 0x2000
	s_add_u32 s4, s34, 0xb0000
	v_lshl_add_u64 v[158:159], s[34:35], 0, v[130:131]
	s_addc_u32 s5, s35, 0
	s_add_i32 s47, s47, s33
	global_load_lds_dwordx4 v[158:159], off
	v_lshl_add_u64 v[180:181], s[4:5], 0, v[128:129]
	s_mov_b32 m0, s47
	v_lshl_add_u64 v[202:203], s[60:61], 0, v[130:131]
	global_load_lds_dwordx4 v[180:181], off
	v_lshl_add_u64 v[180:181], s[4:5], 0, v[130:131]
	s_add_i32 m0, s47, 0x2000
	s_nop 0
	global_load_lds_dwordx4 v[180:181], off
	v_lshl_add_u64 v[180:181], s[60:61], 0, v[128:129]
	s_mov_b32 m0, s65
	s_nop 0
	global_load_lds_dwordx4 v[180:181], off
	s_mov_b32 m0, s66
	s_nop 0
	global_load_lds_dwordx4 v[202:203], off
	s_waitcnt vmcnt(8)
	s_waitcnt lgkmcnt(0)
	s_barrier
	s_waitcnt lgkmcnt(0)
	v_mfma_f32_16x16x32_bf16 v[60:63], v[138:141], v[220:223], v[60:63]
	v_mfma_f32_16x16x32_bf16 v[56:59], v[172:175], v[220:223], v[56:59]
	v_mfma_f32_16x16x32_bf16 v[44:47], v[138:141], v[228:231], v[44:47]
	v_mfma_f32_16x16x32_bf16 v[40:43], v[172:175], v[228:231], v[40:43]
	v_mfma_f32_16x16x32_bf16 v[28:31], v[138:141], v[236:239], v[28:31]
	v_mfma_f32_16x16x32_bf16 v[24:27], v[172:175], v[236:239], v[24:27]
	v_mfma_f32_16x16x32_bf16 v[12:15], v[138:141], v[244:247], v[12:15]
	v_mfma_f32_16x16x32_bf16 v[8:11], v[172:175], v[244:247], v[8:11]
	v_mfma_f32_16x16x32_bf16 v[60:63], v[154:157], v[224:227], v[60:63]
	v_mfma_f32_16x16x32_bf16 v[56:59], v[176:179], v[224:227], v[56:59]
	v_mfma_f32_16x16x32_bf16 v[44:47], v[154:157], v[232:235], v[44:47]
	v_mfma_f32_16x16x32_bf16 v[40:43], v[176:179], v[232:235], v[40:43]
	v_mfma_f32_16x16x32_bf16 v[28:31], v[154:157], v[240:243], v[28:31]
	v_mfma_f32_16x16x32_bf16 v[24:27], v[176:179], v[240:243], v[24:27]
	v_mfma_f32_16x16x32_bf16 v[12:15], v[154:157], v[248:251], v[12:15]
	v_mfma_f32_16x16x32_bf16 v[8:11], v[176:179], v[248:251], v[8:11]
	v_mfma_f32_16x16x32_bf16 v[52:55], v[204:207], v[220:223], v[52:55]
	v_mfma_f32_16x16x32_bf16 v[48:51], v[212:215], v[220:223], v[48:51]
	v_mfma_f32_16x16x32_bf16 v[36:39], v[204:207], v[228:231], v[36:39]
	v_mfma_f32_16x16x32_bf16 v[32:35], v[212:215], v[228:231], v[32:35]
	v_mfma_f32_16x16x32_bf16 v[20:23], v[204:207], v[236:239], v[20:23]
	v_mfma_f32_16x16x32_bf16 v[16:19], v[212:215], v[236:239], v[16:19]
	v_mfma_f32_16x16x32_bf16 v[4:7], v[204:207], v[244:247], v[4:7]
	v_mfma_f32_16x16x32_bf16 v[0:3], v[212:215], v[244:247], v[0:3]
	v_mfma_f32_16x16x32_bf16 v[52:55], v[208:211], v[224:227], v[52:55]
	v_mfma_f32_16x16x32_bf16 v[48:51], v[216:219], v[224:227], v[48:51]
	v_mfma_f32_16x16x32_bf16 v[36:39], v[208:211], v[232:235], v[36:39]
	v_mfma_f32_16x16x32_bf16 v[32:35], v[216:219], v[232:235], v[32:35]
	v_mfma_f32_16x16x32_bf16 v[20:23], v[208:211], v[240:243], v[20:23]
	v_mfma_f32_16x16x32_bf16 v[16:19], v[216:219], v[240:243], v[16:19]
	v_mfma_f32_16x16x32_bf16 v[4:7], v[208:211], v[248:251], v[4:7]
	v_mfma_f32_16x16x32_bf16 v[0:3], v[216:219], v[248:251], v[0:3]
	s_barrier
	s_add_i32 s47, 0, 0x18000
	v_add_u32_e32 v144, s47, v160
	s_add_i32 s54, 0, 0x1c000
	ds_read_b128 v[138:141], v144
	ds_read_b128 v[154:157], v144 offset:1024
	ds_read_b128 v[172:175], v144 offset:2048
	ds_read_b128 v[176:179], v144 offset:3072
	v_add_u32_e32 v144, s54, v160
	ds_read_b128 v[204:207], v144
	ds_read_b128 v[208:211], v144 offset:1024
	ds_read_b128 v[212:215], v144 offset:2048
	ds_read_b128 v[216:219], v144 offset:3072
	s_add_u32 s4, s60, 0xb0000
	s_addc_u32 s5, s61, 0
	s_mov_b32 m0, s67
	v_lshl_add_u64 v[252:253], s[4:5], 0, v[128:129]
	ds_read_b128 v[220:223], v170 offset:32768
	ds_read_b128 v[224:227], v170 offset:33792
	ds_read_b128 v[228:231], v170 offset:34816
	ds_read_b128 v[232:235], v170 offset:35840
	ds_read_b128 v[236:239], v170 offset:36864
	ds_read_b128 v[240:243], v170 offset:37888
	ds_read_b128 v[244:247], v170 offset:38912
	ds_read_b128 v[248:251], v170 offset:39936
	global_load_lds_dwordx4 v[252:253], off
	v_lshl_add_u64 v[252:253], s[4:5], 0, v[130:131]
	s_mov_b32 m0, s68
	s_nop 0
	global_load_lds_dwordx4 v[252:253], off
	s_waitcnt vmcnt(8)
	s_waitcnt lgkmcnt(0)
	s_barrier
	s_waitcnt lgkmcnt(0)
	v_mfma_f32_16x16x32_bf16 v[124:127], v[138:141], v[220:223], v[124:127]
	v_mfma_f32_16x16x32_bf16 v[120:123], v[172:175], v[220:223], v[120:123]
	v_mfma_f32_16x16x32_bf16 v[108:111], v[138:141], v[228:231], v[108:111]
	v_mfma_f32_16x16x32_bf16 v[104:107], v[172:175], v[228:231], v[104:107]
	v_mfma_f32_16x16x32_bf16 v[92:95], v[138:141], v[236:239], v[92:95]
	v_mfma_f32_16x16x32_bf16 v[88:91], v[172:175], v[236:239], v[88:91]
	v_mfma_f32_16x16x32_bf16 v[76:79], v[138:141], v[244:247], v[76:79]
	v_mfma_f32_16x16x32_bf16 v[72:75], v[172:175], v[244:247], v[72:75]
	v_mfma_f32_16x16x32_bf16 v[124:127], v[154:157], v[224:227], v[124:127]
	v_mfma_f32_16x16x32_bf16 v[120:123], v[176:179], v[224:227], v[120:123]
	v_mfma_f32_16x16x32_bf16 v[108:111], v[154:157], v[232:235], v[108:111]
	v_mfma_f32_16x16x32_bf16 v[104:107], v[176:179], v[232:235], v[104:107]
	v_mfma_f32_16x16x32_bf16 v[92:95], v[154:157], v[240:243], v[92:95]
	v_mfma_f32_16x16x32_bf16 v[88:91], v[176:179], v[240:243], v[88:91]
	v_mfma_f32_16x16x32_bf16 v[76:79], v[154:157], v[248:251], v[76:79]
	v_mfma_f32_16x16x32_bf16 v[72:75], v[176:179], v[248:251], v[72:75]
	v_mfma_f32_16x16x32_bf16 v[116:119], v[204:207], v[220:223], v[116:119]
	v_mfma_f32_16x16x32_bf16 v[112:115], v[212:215], v[220:223], v[112:115]
	v_mfma_f32_16x16x32_bf16 v[100:103], v[204:207], v[228:231], v[100:103]
	v_mfma_f32_16x16x32_bf16 v[96:99], v[212:215], v[228:231], v[96:99]
	v_mfma_f32_16x16x32_bf16 v[84:87], v[204:207], v[236:239], v[84:87]
	v_mfma_f32_16x16x32_bf16 v[80:83], v[212:215], v[236:239], v[80:83]
	v_mfma_f32_16x16x32_bf16 v[68:71], v[204:207], v[244:247], v[68:71]
	v_mfma_f32_16x16x32_bf16 v[64:67], v[212:215], v[244:247], v[64:67]
	v_mfma_f32_16x16x32_bf16 v[116:119], v[208:211], v[224:227], v[116:119]
	v_mfma_f32_16x16x32_bf16 v[112:115], v[216:219], v[224:227], v[112:115]
	v_mfma_f32_16x16x32_bf16 v[100:103], v[208:211], v[232:235], v[100:103]
	v_mfma_f32_16x16x32_bf16 v[96:99], v[216:219], v[232:235], v[96:99]
	v_mfma_f32_16x16x32_bf16 v[84:87], v[208:211], v[240:243], v[84:87]
	v_mfma_f32_16x16x32_bf16 v[80:83], v[216:219], v[240:243], v[80:83]
	v_mfma_f32_16x16x32_bf16 v[68:71], v[208:211], v[248:251], v[68:71]
	v_mfma_f32_16x16x32_bf16 v[64:67], v[216:219], v[248:251], v[64:67]
	s_barrier
	s_add_i32 s4, s47, s33
	v_lshl_add_u64 v[142:143], v[142:143], 0, s[26:27]
	s_mov_b32 m0, s4
	ds_read_b128 v[220:223], v170 offset:49152
	ds_read_b128 v[224:227], v170 offset:50176
	ds_read_b128 v[228:231], v170 offset:51200
	ds_read_b128 v[232:235], v170 offset:52224
	ds_read_b128 v[236:239], v170 offset:53248
	ds_read_b128 v[240:243], v170 offset:54272
	ds_read_b128 v[244:247], v170 offset:55296
	ds_read_b128 v[248:251], v170 offset:56320
	global_load_lds_dwordx4 v[142:143], off
	s_add_i32 m0, s4, 0x2000
	s_add_u32 s4, s34, 0xb0080
	v_lshl_add_u64 v[142:143], v[158:159], 0, s[26:27]
	s_addc_u32 s5, s35, 0
	s_add_i32 s34, s54, s33
	global_load_lds_dwordx4 v[142:143], off
	v_lshl_add_u64 v[142:143], s[4:5], 0, v[128:129]
	s_mov_b32 m0, s34
	s_nop 0
	global_load_lds_dwordx4 v[142:143], off
	v_lshl_add_u64 v[142:143], s[4:5], 0, v[130:131]
	s_add_i32 m0, s34, 0x2000
	s_nop 0
	global_load_lds_dwordx4 v[142:143], off
	v_lshl_add_u64 v[142:143], v[180:181], 0, s[26:27]
	s_mov_b32 m0, s69
	s_nop 0
	global_load_lds_dwordx4 v[142:143], off
	v_lshl_add_u64 v[142:143], v[202:203], 0, s[26:27]
	s_mov_b32 m0, s70
	s_nop 0
	global_load_lds_dwordx4 v[142:143], off
	s_waitcnt vmcnt(8)
	s_waitcnt lgkmcnt(0)
	s_barrier
	s_waitcnt lgkmcnt(0)
	v_mfma_f32_16x16x32_bf16 v[60:63], v[138:141], v[220:223], v[60:63]
	v_mfma_f32_16x16x32_bf16 v[56:59], v[172:175], v[220:223], v[56:59]
	v_mfma_f32_16x16x32_bf16 v[44:47], v[138:141], v[228:231], v[44:47]
	v_mfma_f32_16x16x32_bf16 v[40:43], v[172:175], v[228:231], v[40:43]
	v_mfma_f32_16x16x32_bf16 v[28:31], v[138:141], v[236:239], v[28:31]
	v_mfma_f32_16x16x32_bf16 v[24:27], v[172:175], v[236:239], v[24:27]
	v_mfma_f32_16x16x32_bf16 v[12:15], v[138:141], v[244:247], v[12:15]
	v_mfma_f32_16x16x32_bf16 v[8:11], v[172:175], v[244:247], v[8:11]
	v_mfma_f32_16x16x32_bf16 v[60:63], v[154:157], v[224:227], v[60:63]
	v_mfma_f32_16x16x32_bf16 v[56:59], v[176:179], v[224:227], v[56:59]
	v_mfma_f32_16x16x32_bf16 v[44:47], v[154:157], v[232:235], v[44:47]
	v_mfma_f32_16x16x32_bf16 v[40:43], v[176:179], v[232:235], v[40:43]
	v_mfma_f32_16x16x32_bf16 v[28:31], v[154:157], v[240:243], v[28:31]
	v_mfma_f32_16x16x32_bf16 v[24:27], v[176:179], v[240:243], v[24:27]
	v_mfma_f32_16x16x32_bf16 v[12:15], v[154:157], v[248:251], v[12:15]
	v_mfma_f32_16x16x32_bf16 v[8:11], v[176:179], v[248:251], v[8:11]
	v_mfma_f32_16x16x32_bf16 v[52:55], v[204:207], v[220:223], v[52:55]
	v_mfma_f32_16x16x32_bf16 v[48:51], v[212:215], v[220:223], v[48:51]
	v_mfma_f32_16x16x32_bf16 v[36:39], v[204:207], v[228:231], v[36:39]
	v_mfma_f32_16x16x32_bf16 v[32:35], v[212:215], v[228:231], v[32:35]
	v_mfma_f32_16x16x32_bf16 v[20:23], v[204:207], v[236:239], v[20:23]
	v_mfma_f32_16x16x32_bf16 v[16:19], v[212:215], v[236:239], v[16:19]
	v_mfma_f32_16x16x32_bf16 v[4:7], v[204:207], v[244:247], v[4:7]
	v_mfma_f32_16x16x32_bf16 v[0:3], v[212:215], v[244:247], v[0:3]
	v_mfma_f32_16x16x32_bf16 v[52:55], v[208:211], v[224:227], v[52:55]
	v_mfma_f32_16x16x32_bf16 v[48:51], v[216:219], v[224:227], v[48:51]
	v_mfma_f32_16x16x32_bf16 v[36:39], v[208:211], v[232:235], v[36:39]
	v_mfma_f32_16x16x32_bf16 v[32:35], v[216:219], v[232:235], v[32:35]
	v_mfma_f32_16x16x32_bf16 v[20:23], v[208:211], v[240:243], v[20:23]
	v_mfma_f32_16x16x32_bf16 v[16:19], v[216:219], v[240:243], v[16:19]
	v_mfma_f32_16x16x32_bf16 v[4:7], v[208:211], v[248:251], v[4:7]
	v_mfma_f32_16x16x32_bf16 v[0:3], v[216:219], v[248:251], v[0:3]
	s_barrier
	s_add_i32 s29, s29, 2
	s_add_u32 s3, s3, 0x100
	s_addc_u32 s28, s28, 0
	s_cmp_gt_u32 s29, 41
	s_mov_b64 s[54:55], s[58:59]
	s_cbranch_scc0 .LBB0_1399
	s_and_b64 vcc, exec, s[50:51]
	s_cbranch_vccz .LBB0_1402
	s_barrier
